# K-loops: s_setprio moved off the barrier critical path (setprio 1 before the pre-burst barrier, setprio 0 after the trailing barrier), duplicate lgkmcnt wait removed
# baseline (speedup 1.0000x reference)
.LBB0_124:
	s_ashr_i32 s79, s78, 31
	s_lshl_b64 s[10:11], s[78:79], 19
	s_add_u32 s80, s54, s10
	v_cmp_lt_i64_e32 vcc, s[72:73], v[178:179]
	s_addc_u32 s81, s55, s11
	s_and_b64 s[10:11], vcc, exec
	s_cselect_b32 s1, s81, s87
	s_cselect_b32 s10, s80, s86
	s_ashr_i32 s77, s76, 31
	s_lshl_b64 s[36:37], s[76:77], 19
	s_add_u32 s72, s66, s36
	s_addc_u32 s73, s59, s37
	s_and_b64 s[36:37], vcc, exec
	s_cselect_b32 s11, s73, s83
	s_cselect_b32 s25, s72, s82
	s_add_u32 s86, s86, 0x40080
	s_addc_u32 s87, s87, 0
	s_add_u32 s33, s82, 0x100
	s_addc_u32 s36, s83, 0
	s_mov_b32 s37, -2
	s_add_u32 s27, s86, 0xfffc0080
	s_addc_u32 s56, s87, -1
	s_add_i32 s57, 0, 0x10000
	v_add_u32_e32 v76, s57, v217
	ds_read_b128 v[64:67], v76
	ds_read_b128 v[68:71], v76 offset:1024
	ds_read_b128 v[72:75], v76 offset:2048
	ds_read_b128 v[76:79], v76 offset:3072
	s_cmp_eq_u32 s37, 12
	s_cselect_b32 vcc_hi, s1, s56
	s_cselect_b32 vcc_lo, s10, s27
	s_cselect_b32 s83, s11, s36
	s_cselect_b32 s82, s25, s33
	v_lshl_add_u64 v[168:169], s[86:87], 0, v[164:165]
	s_add_i32 m0, s75, 0xc000
	ds_read_b128 v[80:83], v220
	ds_read_b128 v[84:87], v220 offset:1024
	ds_read_b128 v[88:91], v220 offset:2048
	ds_read_b128 v[92:95], v220 offset:3072
	ds_read_b128 v[188:191], v220 offset:4096
	ds_read_b128 v[192:195], v220 offset:5120
	ds_read_b128 v[196:199], v220 offset:6144
	ds_read_b128 v[200:203], v220 offset:7168
	global_load_lds_dwordx4 v[168:169], off
	v_lshl_add_u64 v[168:169], s[86:87], 0, v[166:167]
	s_add_i32 m0, s75, 0xe000
	s_nop 0
	global_load_lds_dwordx4 v[168:169], off
	s_waitcnt lgkmcnt(8)
	s_setprio 1
	s_barrier
	s_waitcnt lgkmcnt(0)
	v_mfma_f32_16x16x32_bf16 v[146:149], v[64:67], v[80:83], 0
	v_mfma_f32_16x16x32_bf16 v[116:119], v[72:75], v[80:83], 0
	v_mfma_f32_16x16x32_bf16 v[158:161], v[64:67], v[88:91], 0
	v_mfma_f32_16x16x32_bf16 v[124:127], v[72:75], v[88:91], 0
	v_mfma_f32_16x16x32_bf16 v[154:157], v[64:67], v[188:191], 0
	v_mfma_f32_16x16x32_bf16 v[112:115], v[72:75], v[188:191], 0
	v_mfma_f32_16x16x32_bf16 v[150:153], v[64:67], v[196:199], 0
	v_mfma_f32_16x16x32_bf16 v[120:123], v[72:75], v[196:199], 0
	v_mfma_f32_16x16x32_bf16 v[146:149], v[68:71], v[84:87], v[146:149]
	v_mfma_f32_16x16x32_bf16 v[116:119], v[76:79], v[84:87], v[116:119]
	v_mfma_f32_16x16x32_bf16 v[158:161], v[68:71], v[92:95], v[158:161]
	v_mfma_f32_16x16x32_bf16 v[124:127], v[76:79], v[92:95], v[124:127]
	v_mfma_f32_16x16x32_bf16 v[154:157], v[68:71], v[192:195], v[154:157]
	v_mfma_f32_16x16x32_bf16 v[112:115], v[76:79], v[192:195], v[112:115]
	v_mfma_f32_16x16x32_bf16 v[150:153], v[68:71], v[200:203], v[150:153]
	v_mfma_f32_16x16x32_bf16 v[120:123], v[76:79], v[200:203], v[120:123]
	s_barrier
	s_setprio 0
	s_add_i32 s27, 0, 0x14000
	v_add_u32_e32 v168, s27, v217
	s_add_i32 s56, s57, s74
	ds_read_b128 v[204:207], v168
	ds_read_b128 v[222:225], v168 offset:1024
	ds_read_b128 v[228:231], v168 offset:2048
	ds_read_b128 v[232:235], v168 offset:3072
	v_lshl_add_u64 v[168:169], s[82:83], 0, v[144:145]
	s_mov_b32 m0, s56
	v_lshl_add_u64 v[176:177], s[82:83], 0, v[162:163]
	global_load_lds_dwordx4 v[168:169], off
	s_add_i32 m0, s56, 0x2000
	s_nop 0
	global_load_lds_dwordx4 v[176:177], off
	s_setprio 1
	s_barrier
	s_waitcnt lgkmcnt(0)
	v_mfma_f32_16x16x32_bf16 v[140:143], v[204:207], v[80:83], 0
	v_mfma_f32_16x16x32_bf16 v[80:83], v[228:231], v[80:83], 0
	v_mfma_f32_16x16x32_bf16 v[140:143], v[222:225], v[84:87], v[140:143]
	v_mfma_f32_16x16x32_bf16 v[80:83], v[232:235], v[84:87], v[80:83]
	v_mfma_f32_16x16x32_bf16 v[84:87], v[204:207], v[88:91], 0
	v_mfma_f32_16x16x32_bf16 v[88:91], v[228:231], v[88:91], 0
	v_mfma_f32_16x16x32_bf16 v[100:103], v[228:231], v[188:191], 0
	v_mfma_f32_16x16x32_bf16 v[104:107], v[204:207], v[196:199], 0
	v_mfma_f32_16x16x32_bf16 v[96:99], v[228:231], v[196:199], 0
	v_mfma_f32_16x16x32_bf16 v[84:87], v[222:225], v[92:95], v[84:87]
	v_mfma_f32_16x16x32_bf16 v[88:91], v[232:235], v[92:95], v[88:91]
	v_mfma_f32_16x16x32_bf16 v[92:95], v[204:207], v[188:191], 0
	v_mfma_f32_16x16x32_bf16 v[100:103], v[232:235], v[192:195], v[100:103]
	v_mfma_f32_16x16x32_bf16 v[128:131], v[222:225], v[200:203], v[104:107]
	v_mfma_f32_16x16x32_bf16 v[96:99], v[232:235], v[200:203], v[96:99]
	v_mfma_f32_16x16x32_bf16 v[92:95], v[222:225], v[192:195], v[92:95]
	s_setprio 0
	s_mov_b32 m0, s75
	v_lshl_add_u64 v[240:241], vcc, 0, v[144:145]
	s_barrier
	ds_read_b128 v[104:107], v220 offset:16384
	ds_read_b128 v[108:111], v220 offset:17408
	ds_read_b128 v[132:135], v220 offset:18432
	ds_read_b128 v[136:139], v220 offset:19456
	ds_read_b128 v[188:191], v220 offset:20480
	ds_read_b128 v[192:195], v220 offset:21504
	ds_read_b128 v[196:199], v220 offset:22528
	ds_read_b128 v[200:203], v220 offset:23552
	global_load_lds_dwordx4 v[240:241], off
	v_lshl_add_u64 v[242:243], vcc, 0, v[162:163]
	s_mov_b32 m0, s85
	s_nop 0
	global_load_lds_dwordx4 v[242:243], off
	s_setprio 1
	s_barrier
	s_waitcnt lgkmcnt(0)
	v_mfma_f32_16x16x32_bf16 v[48:51], v[64:67], v[104:107], 0
	v_mfma_f32_16x16x32_bf16 v[20:23], v[72:75], v[104:107], 0
	v_mfma_f32_16x16x32_bf16 v[60:63], v[64:67], v[132:135], 0
	v_mfma_f32_16x16x32_bf16 v[28:31], v[72:75], v[132:135], 0
	v_mfma_f32_16x16x32_bf16 v[56:59], v[64:67], v[188:191], 0
	v_mfma_f32_16x16x32_bf16 v[16:19], v[72:75], v[188:191], 0
	v_mfma_f32_16x16x32_bf16 v[52:55], v[64:67], v[196:199], 0
	v_mfma_f32_16x16x32_bf16 v[24:27], v[72:75], v[196:199], 0
	v_mfma_f32_16x16x32_bf16 v[48:51], v[68:71], v[108:111], v[48:51]
	v_mfma_f32_16x16x32_bf16 v[20:23], v[76:79], v[108:111], v[20:23]
	v_mfma_f32_16x16x32_bf16 v[60:63], v[68:71], v[136:139], v[60:63]
	v_mfma_f32_16x16x32_bf16 v[28:31], v[76:79], v[136:139], v[28:31]
	v_mfma_f32_16x16x32_bf16 v[56:59], v[68:71], v[192:195], v[56:59]
	v_mfma_f32_16x16x32_bf16 v[16:19], v[76:79], v[192:195], v[16:19]
	v_mfma_f32_16x16x32_bf16 v[52:55], v[68:71], v[200:203], v[52:55]
	v_mfma_f32_16x16x32_bf16 v[24:27], v[76:79], v[200:203], v[24:27]
	s_barrier
	s_setprio 0
	s_add_u32 s56, s82, 0x40000
	s_addc_u32 s57, s83, 0
	s_add_i32 s27, s27, s74
	v_lshl_add_u64 v[64:65], s[56:57], 0, v[144:145]
	s_mov_b32 m0, s27
	s_nop 0
	global_load_lds_dwordx4 v[64:65], off
	v_lshl_add_u64 v[64:65], s[56:57], 0, v[162:163]
	s_add_i32 m0, s27, 0x2000
	s_nop 0
	global_load_lds_dwordx4 v[64:65], off
	s_waitcnt vmcnt(6)
	s_setprio 1
	s_barrier
	v_mfma_f32_16x16x32_bf16 v[44:47], v[204:207], v[104:107], 0
	v_mfma_f32_16x16x32_bf16 v[12:15], v[228:231], v[104:107], 0
	v_mfma_f32_16x16x32_bf16 v[40:43], v[204:207], v[132:135], 0
	v_mfma_f32_16x16x32_bf16 v[8:11], v[228:231], v[132:135], 0
	v_mfma_f32_16x16x32_bf16 v[36:39], v[204:207], v[188:191], 0
	v_mfma_f32_16x16x32_bf16 v[4:7], v[228:231], v[188:191], 0
	v_mfma_f32_16x16x32_bf16 v[32:35], v[204:207], v[196:199], 0
	v_mfma_f32_16x16x32_bf16 v[0:3], v[228:231], v[196:199], 0
	v_mfma_f32_16x16x32_bf16 v[44:47], v[222:225], v[108:111], v[44:47]
	v_mfma_f32_16x16x32_bf16 v[12:15], v[232:235], v[108:111], v[12:15]
	v_mfma_f32_16x16x32_bf16 v[40:43], v[222:225], v[136:139], v[40:43]
	v_mfma_f32_16x16x32_bf16 v[8:11], v[232:235], v[136:139], v[8:11]
	v_mfma_f32_16x16x32_bf16 v[36:39], v[222:225], v[192:195], v[36:39]
	v_mfma_f32_16x16x32_bf16 v[4:7], v[232:235], v[192:195], v[4:7]
	v_mfma_f32_16x16x32_bf16 v[32:35], v[222:225], v[200:203], v[32:35]
	v_mfma_f32_16x16x32_bf16 v[0:3], v[232:235], v[200:203], v[0:3]
	s_setprio 0
	s_add_i32 s27, 0, 0x18000
	v_add_u32_e32 v76, s27, v217
	s_barrier
	ds_read_b128 v[64:67], v76
	ds_read_b128 v[68:71], v76 offset:1024
	ds_read_b128 v[72:75], v76 offset:2048
	ds_read_b128 v[76:79], v76 offset:3072
	s_add_u32 s56, vcc_lo, 0x40000
	s_addc_u32 s57, vcc_hi, 0
	s_mov_b32 m0, s98
	v_lshl_add_u64 v[136:137], s[56:57], 0, v[144:145]
	ds_read_b128 v[104:107], v220 offset:32768
	ds_read_b128 v[108:111], v220 offset:33792
	ds_read_b128 v[132:135], v220 offset:34816
	ds_read_b128 v[188:191], v220 offset:35840
	ds_read_b128 v[192:195], v220 offset:36864
	ds_read_b128 v[196:199], v220 offset:37888
	ds_read_b128 v[200:203], v220 offset:38912
	ds_read_b128 v[204:207], v220 offset:39936
	global_load_lds_dwordx4 v[136:137], off
	v_lshl_add_u64 v[136:137], s[56:57], 0, v[162:163]
	s_mov_b32 m0, s29
	s_nop 0
	global_load_lds_dwordx4 v[136:137], off
	s_waitcnt lgkmcnt(8)
	s_setprio 1
	s_barrier
	s_waitcnt lgkmcnt(0)
	v_mfma_f32_16x16x32_bf16 v[136:139], v[64:67], v[104:107], v[146:149]
	v_mfma_f32_16x16x32_bf16 v[146:149], v[68:71], v[108:111], v[136:139]
	v_mfma_f32_16x16x32_bf16 v[136:139], v[64:67], v[132:135], v[158:161]
	v_mfma_f32_16x16x32_bf16 v[158:161], v[68:71], v[188:191], v[136:139]
	v_mfma_f32_16x16x32_bf16 v[136:139], v[64:67], v[192:195], v[154:157]
	v_mfma_f32_16x16x32_bf16 v[116:119], v[72:75], v[104:107], v[116:119]
	v_mfma_f32_16x16x32_bf16 v[124:127], v[72:75], v[132:135], v[124:127]
	v_mfma_f32_16x16x32_bf16 v[154:157], v[68:71], v[196:199], v[136:139]
	v_mfma_f32_16x16x32_bf16 v[112:115], v[72:75], v[192:195], v[112:115]
	v_mfma_f32_16x16x32_bf16 v[136:139], v[64:67], v[200:203], v[150:153]
	v_mfma_f32_16x16x32_bf16 v[120:123], v[72:75], v[200:203], v[120:123]
	v_mfma_f32_16x16x32_bf16 v[116:119], v[76:79], v[108:111], v[116:119]
	v_mfma_f32_16x16x32_bf16 v[124:127], v[76:79], v[188:191], v[124:127]
	v_mfma_f32_16x16x32_bf16 v[112:115], v[76:79], v[196:199], v[112:115]
	v_mfma_f32_16x16x32_bf16 v[150:153], v[68:71], v[204:207], v[136:139]
	v_mfma_f32_16x16x32_bf16 v[120:123], v[76:79], v[204:207], v[120:123]
	s_barrier
	s_setprio 0
	s_add_i32 s58, 0, 0x1c000
	v_add_u32_e32 v136, s58, v217
	s_add_i32 s27, s27, s74
	ds_read_b128 v[222:225], v136
	ds_read_b128 v[228:231], v136 offset:1024
	ds_read_b128 v[232:235], v136 offset:2048
	ds_read_b128 v[236:239], v136 offset:3072
	v_lshl_add_u64 v[136:137], v[168:169], 0, s[18:19]
	s_mov_b32 m0, s27
	s_nop 0
	global_load_lds_dwordx4 v[136:137], off
	v_lshl_add_u64 v[136:137], v[176:177], 0, s[18:19]
	s_add_i32 m0, s27, 0x2000
	s_nop 0
	global_load_lds_dwordx4 v[136:137], off
	s_setprio 1
	s_barrier
	s_waitcnt lgkmcnt(0)
	v_mfma_f32_16x16x32_bf16 v[136:139], v[222:225], v[104:107], v[140:143]
	v_mfma_f32_16x16x32_bf16 v[80:83], v[232:235], v[104:107], v[80:83]
	v_mfma_f32_16x16x32_bf16 v[140:143], v[228:231], v[108:111], v[136:139]
	v_mfma_f32_16x16x32_bf16 v[108:111], v[236:239], v[108:111], v[80:83]
	v_mfma_f32_16x16x32_bf16 v[80:83], v[222:225], v[132:135], v[84:87]
	v_mfma_f32_16x16x32_bf16 v[136:139], v[228:231], v[188:191], v[80:83]
	v_mfma_f32_16x16x32_bf16 v[80:83], v[232:235], v[132:135], v[88:91]
	v_mfma_f32_16x16x32_bf16 v[104:107], v[236:239], v[188:191], v[80:83]
	v_mfma_f32_16x16x32_bf16 v[80:83], v[222:225], v[192:195], v[92:95]
	v_mfma_f32_16x16x32_bf16 v[132:135], v[228:231], v[196:199], v[80:83]
	v_mfma_f32_16x16x32_bf16 v[80:83], v[232:235], v[192:195], v[100:103]
	v_mfma_f32_16x16x32_bf16 v[100:103], v[236:239], v[196:199], v[80:83]
	v_mfma_f32_16x16x32_bf16 v[80:83], v[222:225], v[200:203], v[128:131]
	v_mfma_f32_16x16x32_bf16 v[128:131], v[228:231], v[204:207], v[80:83]
	v_mfma_f32_16x16x32_bf16 v[80:83], v[232:235], v[200:203], v[96:99]
	v_mfma_f32_16x16x32_bf16 v[96:99], v[236:239], v[204:207], v[80:83]
	s_setprio 0
	s_mov_b32 m0, s31
	v_lshl_add_u64 v[168:169], v[240:241], 0, s[18:19]
	s_barrier
	s_nop 2
	ds_read_b128 v[80:83], v220 offset:49152
	ds_read_b128 v[84:87], v220 offset:50176
	ds_read_b128 v[88:91], v220 offset:51200
	ds_read_b128 v[92:95], v220 offset:52224
	ds_read_b128 v[188:191], v220 offset:53248
	ds_read_b128 v[192:195], v220 offset:54272
	ds_read_b128 v[196:199], v220 offset:55296
	ds_read_b128 v[200:203], v220 offset:56320
	global_load_lds_dwordx4 v[168:169], off
	v_lshl_add_u64 v[168:169], v[242:243], 0, s[18:19]
	s_mov_b32 m0, s34
	s_nop 0
	global_load_lds_dwordx4 v[168:169], off
	s_setprio 1
	s_barrier
	s_waitcnt lgkmcnt(0)
	v_mfma_f32_16x16x32_bf16 v[48:51], v[64:67], v[80:83], v[48:51]
	v_mfma_f32_16x16x32_bf16 v[20:23], v[72:75], v[80:83], v[20:23]
	v_mfma_f32_16x16x32_bf16 v[60:63], v[64:67], v[88:91], v[60:63]
	v_mfma_f32_16x16x32_bf16 v[28:31], v[72:75], v[88:91], v[28:31]
	v_mfma_f32_16x16x32_bf16 v[56:59], v[64:67], v[188:191], v[56:59]
	v_mfma_f32_16x16x32_bf16 v[16:19], v[72:75], v[188:191], v[16:19]
	v_mfma_f32_16x16x32_bf16 v[52:55], v[64:67], v[196:199], v[52:55]
	v_mfma_f32_16x16x32_bf16 v[24:27], v[72:75], v[196:199], v[24:27]
	v_mfma_f32_16x16x32_bf16 v[48:51], v[68:71], v[84:87], v[48:51]
	v_mfma_f32_16x16x32_bf16 v[20:23], v[76:79], v[84:87], v[20:23]
	v_mfma_f32_16x16x32_bf16 v[60:63], v[68:71], v[92:95], v[60:63]
	v_mfma_f32_16x16x32_bf16 v[28:31], v[76:79], v[92:95], v[28:31]
	v_mfma_f32_16x16x32_bf16 v[56:59], v[68:71], v[192:195], v[56:59]
	v_mfma_f32_16x16x32_bf16 v[16:19], v[76:79], v[192:195], v[16:19]
	v_mfma_f32_16x16x32_bf16 v[52:55], v[68:71], v[200:203], v[52:55]
	v_mfma_f32_16x16x32_bf16 v[24:27], v[76:79], v[200:203], v[24:27]
	s_barrier
	s_setprio 0
	s_add_u32 s56, s82, 0x40080
	s_addc_u32 s57, s83, 0
	s_add_i32 s27, s58, s74
	v_lshl_add_u64 v[64:65], s[56:57], 0, v[144:145]
	s_mov_b32 m0, s27
	s_nop 0
	global_load_lds_dwordx4 v[64:65], off
	v_lshl_add_u64 v[64:65], s[56:57], 0, v[162:163]
	s_add_i32 m0, s27, 0x2000
	s_nop 0
	global_load_lds_dwordx4 v[64:65], off
	s_waitcnt vmcnt(6)
	s_setprio 1
	s_barrier
	v_mfma_f32_16x16x32_bf16 v[44:47], v[222:225], v[80:83], v[44:47]
	v_mfma_f32_16x16x32_bf16 v[12:15], v[232:235], v[80:83], v[12:15]
	v_mfma_f32_16x16x32_bf16 v[40:43], v[222:225], v[88:91], v[40:43]
	v_mfma_f32_16x16x32_bf16 v[8:11], v[232:235], v[88:91], v[8:11]
	v_mfma_f32_16x16x32_bf16 v[36:39], v[222:225], v[188:191], v[36:39]
	v_mfma_f32_16x16x32_bf16 v[4:7], v[232:235], v[188:191], v[4:7]
	v_mfma_f32_16x16x32_bf16 v[32:35], v[222:225], v[196:199], v[32:35]
	v_mfma_f32_16x16x32_bf16 v[0:3], v[232:235], v[196:199], v[0:3]
	v_mfma_f32_16x16x32_bf16 v[44:47], v[228:231], v[84:87], v[44:47]
	v_mfma_f32_16x16x32_bf16 v[12:15], v[236:239], v[84:87], v[12:15]
	v_mfma_f32_16x16x32_bf16 v[40:43], v[228:231], v[92:95], v[40:43]
	v_mfma_f32_16x16x32_bf16 v[8:11], v[236:239], v[92:95], v[8:11]
	v_mfma_f32_16x16x32_bf16 v[36:39], v[228:231], v[192:195], v[36:39]
	v_mfma_f32_16x16x32_bf16 v[4:7], v[236:239], v[192:195], v[4:7]
	v_mfma_f32_16x16x32_bf16 v[32:35], v[228:231], v[200:203], v[32:35]
	v_mfma_f32_16x16x32_bf16 v[0:3], v[236:239], v[200:203], v[0:3]
	s_setprio 0
	s_add_i32 s37, s37, 2
	s_add_u32 s86, s86, 0x100
	s_addc_u32 s87, s87, 0
	s_add_u32 s33, s33, 0x100
	s_addc_u32 s36, s36, 0
	s_cmp_gt_u32 s37, 13
	s_barrier
.LBB0_125:
	s_add_u32 s27, s86, 0xfffc0080
	s_addc_u32 s56, s87, -1
	s_add_i32 s57, 0, 0x10000
	v_add_u32_e32 v76, s57, v217
	ds_read_b128 v[64:67], v76
	ds_read_b128 v[68:71], v76 offset:1024
	ds_read_b128 v[72:75], v76 offset:2048
	ds_read_b128 v[76:79], v76 offset:3072
	s_cmp_eq_u32 s37, 12
	s_cselect_b32 vcc_hi, s1, s56
	s_cselect_b32 vcc_lo, s10, s27
	s_cselect_b32 s83, s11, s36
	s_cselect_b32 s82, s25, s33
	v_lshl_add_u64 v[168:169], s[86:87], 0, v[164:165]
	s_add_i32 m0, s75, 0xc000
	ds_read_b128 v[80:83], v220
	ds_read_b128 v[84:87], v220 offset:1024
	ds_read_b128 v[88:91], v220 offset:2048
	ds_read_b128 v[92:95], v220 offset:3072
	ds_read_b128 v[188:191], v220 offset:4096
	ds_read_b128 v[192:195], v220 offset:5120
	ds_read_b128 v[196:199], v220 offset:6144
	ds_read_b128 v[200:203], v220 offset:7168
	global_load_lds_dwordx4 v[168:169], off
	v_lshl_add_u64 v[168:169], s[86:87], 0, v[166:167]
	s_add_i32 m0, s75, 0xe000
	s_nop 0
	global_load_lds_dwordx4 v[168:169], off
	s_waitcnt lgkmcnt(8)
	s_barrier
	s_waitcnt lgkmcnt(0)
	s_setprio 1
	s_waitcnt lgkmcnt(0)
	v_mfma_f32_16x16x32_bf16 v[146:149], v[64:67], v[80:83], v[146:149]
	v_mfma_f32_16x16x32_bf16 v[116:119], v[72:75], v[80:83], v[116:119]
	v_mfma_f32_16x16x32_bf16 v[158:161], v[64:67], v[88:91], v[158:161]
	v_mfma_f32_16x16x32_bf16 v[124:127], v[72:75], v[88:91], v[124:127]
	v_mfma_f32_16x16x32_bf16 v[154:157], v[64:67], v[188:191], v[154:157]
	v_mfma_f32_16x16x32_bf16 v[112:115], v[72:75], v[188:191], v[112:115]
	v_mfma_f32_16x16x32_bf16 v[150:153], v[64:67], v[196:199], v[150:153]
	v_mfma_f32_16x16x32_bf16 v[120:123], v[72:75], v[196:199], v[120:123]
	v_mfma_f32_16x16x32_bf16 v[146:149], v[68:71], v[84:87], v[146:149]
	v_mfma_f32_16x16x32_bf16 v[116:119], v[76:79], v[84:87], v[116:119]
	v_mfma_f32_16x16x32_bf16 v[158:161], v[68:71], v[92:95], v[158:161]
	v_mfma_f32_16x16x32_bf16 v[124:127], v[76:79], v[92:95], v[124:127]
	v_mfma_f32_16x16x32_bf16 v[154:157], v[68:71], v[192:195], v[154:157]
	v_mfma_f32_16x16x32_bf16 v[112:115], v[76:79], v[192:195], v[112:115]
	v_mfma_f32_16x16x32_bf16 v[150:153], v[68:71], v[200:203], v[150:153]
	v_mfma_f32_16x16x32_bf16 v[120:123], v[76:79], v[200:203], v[120:123]
	s_barrier
	s_setprio 0
	s_add_i32 s27, 0, 0x14000
	v_add_u32_e32 v168, s27, v217
	s_add_i32 s56, s57, s74
	ds_read_b128 v[204:207], v168
	ds_read_b128 v[222:225], v168 offset:1024
	ds_read_b128 v[228:231], v168 offset:2048
	ds_read_b128 v[232:235], v168 offset:3072
	v_lshl_add_u64 v[168:169], s[82:83], 0, v[144:145]
	s_mov_b32 m0, s56
	v_lshl_add_u64 v[176:177], s[82:83], 0, v[162:163]
	global_load_lds_dwordx4 v[168:169], off
	s_add_i32 m0, s56, 0x2000
	s_nop 0
	global_load_lds_dwordx4 v[176:177], off
	s_barrier
	s_waitcnt lgkmcnt(0)
	s_setprio 1
	s_waitcnt lgkmcnt(0)
	v_mfma_f32_16x16x32_bf16 v[140:143], v[204:207], v[80:83], v[140:143]
	v_mfma_f32_16x16x32_bf16 v[80:83], v[228:231], v[80:83], v[108:111]
	v_mfma_f32_16x16x32_bf16 v[140:143], v[222:225], v[84:87], v[140:143]
	v_mfma_f32_16x16x32_bf16 v[80:83], v[232:235], v[84:87], v[80:83]
	v_mfma_f32_16x16x32_bf16 v[84:87], v[204:207], v[88:91], v[136:139]
	v_mfma_f32_16x16x32_bf16 v[88:91], v[228:231], v[88:91], v[104:107]
	v_mfma_f32_16x16x32_bf16 v[100:103], v[228:231], v[188:191], v[100:103]
	v_mfma_f32_16x16x32_bf16 v[104:107], v[204:207], v[196:199], v[128:131]
	v_mfma_f32_16x16x32_bf16 v[96:99], v[228:231], v[196:199], v[96:99]
	v_mfma_f32_16x16x32_bf16 v[84:87], v[222:225], v[92:95], v[84:87]
	v_mfma_f32_16x16x32_bf16 v[88:91], v[232:235], v[92:95], v[88:91]
	v_mfma_f32_16x16x32_bf16 v[92:95], v[204:207], v[188:191], v[132:135]
	v_mfma_f32_16x16x32_bf16 v[100:103], v[232:235], v[192:195], v[100:103]
	v_mfma_f32_16x16x32_bf16 v[128:131], v[222:225], v[200:203], v[104:107]
	v_mfma_f32_16x16x32_bf16 v[96:99], v[232:235], v[200:203], v[96:99]
	v_mfma_f32_16x16x32_bf16 v[92:95], v[222:225], v[192:195], v[92:95]
	s_setprio 0
	s_mov_b32 m0, s75
	v_lshl_add_u64 v[240:241], vcc, 0, v[144:145]
	s_barrier
	ds_read_b128 v[104:107], v220 offset:16384
	ds_read_b128 v[108:111], v220 offset:17408
	ds_read_b128 v[132:135], v220 offset:18432
	ds_read_b128 v[136:139], v220 offset:19456
	ds_read_b128 v[188:191], v220 offset:20480
	ds_read_b128 v[192:195], v220 offset:21504
	ds_read_b128 v[196:199], v220 offset:22528
	ds_read_b128 v[200:203], v220 offset:23552
	global_load_lds_dwordx4 v[240:241], off
	v_lshl_add_u64 v[242:243], vcc, 0, v[162:163]
	s_mov_b32 m0, s85
	s_nop 0
	global_load_lds_dwordx4 v[242:243], off
	s_barrier
	s_waitcnt lgkmcnt(0)
	s_setprio 1
	s_waitcnt lgkmcnt(0)
	v_mfma_f32_16x16x32_bf16 v[48:51], v[64:67], v[104:107], v[48:51]
	v_mfma_f32_16x16x32_bf16 v[20:23], v[72:75], v[104:107], v[20:23]
	v_mfma_f32_16x16x32_bf16 v[60:63], v[64:67], v[132:135], v[60:63]
	v_mfma_f32_16x16x32_bf16 v[28:31], v[72:75], v[132:135], v[28:31]
	v_mfma_f32_16x16x32_bf16 v[56:59], v[64:67], v[188:191], v[56:59]
	v_mfma_f32_16x16x32_bf16 v[16:19], v[72:75], v[188:191], v[16:19]
	v_mfma_f32_16x16x32_bf16 v[52:55], v[64:67], v[196:199], v[52:55]
	v_mfma_f32_16x16x32_bf16 v[24:27], v[72:75], v[196:199], v[24:27]
	v_mfma_f32_16x16x32_bf16 v[48:51], v[68:71], v[108:111], v[48:51]
	v_mfma_f32_16x16x32_bf16 v[20:23], v[76:79], v[108:111], v[20:23]
	v_mfma_f32_16x16x32_bf16 v[60:63], v[68:71], v[136:139], v[60:63]
	v_mfma_f32_16x16x32_bf16 v[28:31], v[76:79], v[136:139], v[28:31]
	v_mfma_f32_16x16x32_bf16 v[56:59], v[68:71], v[192:195], v[56:59]
	v_mfma_f32_16x16x32_bf16 v[16:19], v[76:79], v[192:195], v[16:19]
	v_mfma_f32_16x16x32_bf16 v[52:55], v[68:71], v[200:203], v[52:55]
	v_mfma_f32_16x16x32_bf16 v[24:27], v[76:79], v[200:203], v[24:27]
	s_barrier
	s_setprio 0
	s_add_u32 s56, s82, 0x40000
	s_addc_u32 s57, s83, 0
	s_add_i32 s27, s27, s74
	v_lshl_add_u64 v[64:65], s[56:57], 0, v[144:145]
	s_mov_b32 m0, s27
	s_nop 0
	global_load_lds_dwordx4 v[64:65], off
	v_lshl_add_u64 v[64:65], s[56:57], 0, v[162:163]
	s_add_i32 m0, s27, 0x2000
	s_nop 0
	global_load_lds_dwordx4 v[64:65], off
	s_waitcnt vmcnt(6)
	s_setprio 1
	s_barrier
	v_mfma_f32_16x16x32_bf16 v[44:47], v[204:207], v[104:107], v[44:47]
	v_mfma_f32_16x16x32_bf16 v[12:15], v[228:231], v[104:107], v[12:15]
	v_mfma_f32_16x16x32_bf16 v[40:43], v[204:207], v[132:135], v[40:43]
	v_mfma_f32_16x16x32_bf16 v[8:11], v[228:231], v[132:135], v[8:11]
	v_mfma_f32_16x16x32_bf16 v[36:39], v[204:207], v[188:191], v[36:39]
	v_mfma_f32_16x16x32_bf16 v[4:7], v[228:231], v[188:191], v[4:7]
	v_mfma_f32_16x16x32_bf16 v[32:35], v[204:207], v[196:199], v[32:35]
	v_mfma_f32_16x16x32_bf16 v[0:3], v[228:231], v[196:199], v[0:3]
	v_mfma_f32_16x16x32_bf16 v[44:47], v[222:225], v[108:111], v[44:47]
	v_mfma_f32_16x16x32_bf16 v[12:15], v[232:235], v[108:111], v[12:15]
	v_mfma_f32_16x16x32_bf16 v[40:43], v[222:225], v[136:139], v[40:43]
	v_mfma_f32_16x16x32_bf16 v[8:11], v[232:235], v[136:139], v[8:11]
	v_mfma_f32_16x16x32_bf16 v[36:39], v[222:225], v[192:195], v[36:39]
	v_mfma_f32_16x16x32_bf16 v[4:7], v[232:235], v[192:195], v[4:7]
	v_mfma_f32_16x16x32_bf16 v[32:35], v[222:225], v[200:203], v[32:35]
	v_mfma_f32_16x16x32_bf16 v[0:3], v[232:235], v[200:203], v[0:3]
	s_setprio 0
	s_add_i32 s27, 0, 0x18000
	v_add_u32_e32 v76, s27, v217
	s_barrier
	ds_read_b128 v[64:67], v76
	ds_read_b128 v[68:71], v76 offset:1024
	ds_read_b128 v[72:75], v76 offset:2048
	ds_read_b128 v[76:79], v76 offset:3072
	s_add_u32 s56, vcc_lo, 0x40000
	s_addc_u32 s57, vcc_hi, 0
	s_mov_b32 m0, s98
	v_lshl_add_u64 v[136:137], s[56:57], 0, v[144:145]
	ds_read_b128 v[104:107], v220 offset:32768
	ds_read_b128 v[108:111], v220 offset:33792
	ds_read_b128 v[132:135], v220 offset:34816
	ds_read_b128 v[188:191], v220 offset:35840
	ds_read_b128 v[192:195], v220 offset:36864
	ds_read_b128 v[196:199], v220 offset:37888
	ds_read_b128 v[200:203], v220 offset:38912
	ds_read_b128 v[204:207], v220 offset:39936
	global_load_lds_dwordx4 v[136:137], off
	v_lshl_add_u64 v[136:137], s[56:57], 0, v[162:163]
	s_mov_b32 m0, s29
	s_nop 0
	global_load_lds_dwordx4 v[136:137], off
	s_waitcnt lgkmcnt(8)
	s_barrier
	s_waitcnt lgkmcnt(0)
	s_setprio 1
	s_waitcnt lgkmcnt(0)
	v_mfma_f32_16x16x32_bf16 v[136:139], v[64:67], v[104:107], v[146:149]
	v_mfma_f32_16x16x32_bf16 v[146:149], v[68:71], v[108:111], v[136:139]
	v_mfma_f32_16x16x32_bf16 v[136:139], v[64:67], v[132:135], v[158:161]
	v_mfma_f32_16x16x32_bf16 v[158:161], v[68:71], v[188:191], v[136:139]
	v_mfma_f32_16x16x32_bf16 v[136:139], v[64:67], v[192:195], v[154:157]
	v_mfma_f32_16x16x32_bf16 v[116:119], v[72:75], v[104:107], v[116:119]
	v_mfma_f32_16x16x32_bf16 v[124:127], v[72:75], v[132:135], v[124:127]
	v_mfma_f32_16x16x32_bf16 v[154:157], v[68:71], v[196:199], v[136:139]
	v_mfma_f32_16x16x32_bf16 v[112:115], v[72:75], v[192:195], v[112:115]
	v_mfma_f32_16x16x32_bf16 v[136:139], v[64:67], v[200:203], v[150:153]
	v_mfma_f32_16x16x32_bf16 v[120:123], v[72:75], v[200:203], v[120:123]
	v_mfma_f32_16x16x32_bf16 v[116:119], v[76:79], v[108:111], v[116:119]
	v_mfma_f32_16x16x32_bf16 v[124:127], v[76:79], v[188:191], v[124:127]
	v_mfma_f32_16x16x32_bf16 v[112:115], v[76:79], v[196:199], v[112:115]
	v_mfma_f32_16x16x32_bf16 v[150:153], v[68:71], v[204:207], v[136:139]
	v_mfma_f32_16x16x32_bf16 v[120:123], v[76:79], v[204:207], v[120:123]
	s_barrier
	s_setprio 0
	s_add_i32 s58, 0, 0x1c000
	v_add_u32_e32 v136, s58, v217
	s_add_i32 s27, s27, s74
	ds_read_b128 v[222:225], v136
	ds_read_b128 v[228:231], v136 offset:1024
	ds_read_b128 v[232:235], v136 offset:2048
	ds_read_b128 v[236:239], v136 offset:3072
	v_lshl_add_u64 v[136:137], v[168:169], 0, s[18:19]
	s_mov_b32 m0, s27
	s_nop 0
	global_load_lds_dwordx4 v[136:137], off
	v_lshl_add_u64 v[136:137], v[176:177], 0, s[18:19]
	s_add_i32 m0, s27, 0x2000
	s_nop 0
	global_load_lds_dwordx4 v[136:137], off
	s_barrier
	s_waitcnt lgkmcnt(0)
	s_setprio 1
	s_waitcnt lgkmcnt(0)
	v_mfma_f32_16x16x32_bf16 v[136:139], v[222:225], v[104:107], v[140:143]
	v_mfma_f32_16x16x32_bf16 v[80:83], v[232:235], v[104:107], v[80:83]
	v_mfma_f32_16x16x32_bf16 v[140:143], v[228:231], v[108:111], v[136:139]
	v_mfma_f32_16x16x32_bf16 v[108:111], v[236:239], v[108:111], v[80:83]
	v_mfma_f32_16x16x32_bf16 v[80:83], v[222:225], v[132:135], v[84:87]
	v_mfma_f32_16x16x32_bf16 v[136:139], v[228:231], v[188:191], v[80:83]
	v_mfma_f32_16x16x32_bf16 v[80:83], v[232:235], v[132:135], v[88:91]
	v_mfma_f32_16x16x32_bf16 v[104:107], v[236:239], v[188:191], v[80:83]
	v_mfma_f32_16x16x32_bf16 v[80:83], v[222:225], v[192:195], v[92:95]
	v_mfma_f32_16x16x32_bf16 v[132:135], v[228:231], v[196:199], v[80:83]
	v_mfma_f32_16x16x32_bf16 v[80:83], v[232:235], v[192:195], v[100:103]
	v_mfma_f32_16x16x32_bf16 v[100:103], v[236:239], v[196:199], v[80:83]
	v_mfma_f32_16x16x32_bf16 v[80:83], v[222:225], v[200:203], v[128:131]
	v_mfma_f32_16x16x32_bf16 v[128:131], v[228:231], v[204:207], v[80:83]
	v_mfma_f32_16x16x32_bf16 v[80:83], v[232:235], v[200:203], v[96:99]
	v_mfma_f32_16x16x32_bf16 v[96:99], v[236:239], v[204:207], v[80:83]
	s_setprio 0
	s_mov_b32 m0, s31
	v_lshl_add_u64 v[168:169], v[240:241], 0, s[18:19]
	s_barrier
	s_nop 2
	ds_read_b128 v[80:83], v220 offset:49152
	ds_read_b128 v[84:87], v220 offset:50176
	ds_read_b128 v[88:91], v220 offset:51200
	ds_read_b128 v[92:95], v220 offset:52224
	ds_read_b128 v[188:191], v220 offset:53248
	ds_read_b128 v[192:195], v220 offset:54272
	ds_read_b128 v[196:199], v220 offset:55296
	ds_read_b128 v[200:203], v220 offset:56320
	global_load_lds_dwordx4 v[168:169], off
	v_lshl_add_u64 v[168:169], v[242:243], 0, s[18:19]
	s_mov_b32 m0, s34
	s_nop 0
	global_load_lds_dwordx4 v[168:169], off
	s_barrier
	s_waitcnt lgkmcnt(0)
	s_setprio 1
	s_waitcnt lgkmcnt(0)
	v_mfma_f32_16x16x32_bf16 v[48:51], v[64:67], v[80:83], v[48:51]
	v_mfma_f32_16x16x32_bf16 v[20:23], v[72:75], v[80:83], v[20:23]
	v_mfma_f32_16x16x32_bf16 v[60:63], v[64:67], v[88:91], v[60:63]
	v_mfma_f32_16x16x32_bf16 v[28:31], v[72:75], v[88:91], v[28:31]
	v_mfma_f32_16x16x32_bf16 v[56:59], v[64:67], v[188:191], v[56:59]
	v_mfma_f32_16x16x32_bf16 v[16:19], v[72:75], v[188:191], v[16:19]
	v_mfma_f32_16x16x32_bf16 v[52:55], v[64:67], v[196:199], v[52:55]
	v_mfma_f32_16x16x32_bf16 v[24:27], v[72:75], v[196:199], v[24:27]
	v_mfma_f32_16x16x32_bf16 v[48:51], v[68:71], v[84:87], v[48:51]
	v_mfma_f32_16x16x32_bf16 v[20:23], v[76:79], v[84:87], v[20:23]
	v_mfma_f32_16x16x32_bf16 v[60:63], v[68:71], v[92:95], v[60:63]
	v_mfma_f32_16x16x32_bf16 v[28:31], v[76:79], v[92:95], v[28:31]
	v_mfma_f32_16x16x32_bf16 v[56:59], v[68:71], v[192:195], v[56:59]
	v_mfma_f32_16x16x32_bf16 v[16:19], v[76:79], v[192:195], v[16:19]
	v_mfma_f32_16x16x32_bf16 v[52:55], v[68:71], v[200:203], v[52:55]
	v_mfma_f32_16x16x32_bf16 v[24:27], v[76:79], v[200:203], v[24:27]
	s_barrier
	s_setprio 0
	s_add_u32 s56, s82, 0x40080
	s_addc_u32 s57, s83, 0
	s_add_i32 s27, s58, s74
	v_lshl_add_u64 v[64:65], s[56:57], 0, v[144:145]
	s_mov_b32 m0, s27
	s_nop 0
	global_load_lds_dwordx4 v[64:65], off
	v_lshl_add_u64 v[64:65], s[56:57], 0, v[162:163]
	s_add_i32 m0, s27, 0x2000
	s_nop 0
	global_load_lds_dwordx4 v[64:65], off
	s_waitcnt vmcnt(6)
	s_setprio 1
	s_barrier
	v_mfma_f32_16x16x32_bf16 v[44:47], v[222:225], v[80:83], v[44:47]
	v_mfma_f32_16x16x32_bf16 v[12:15], v[232:235], v[80:83], v[12:15]
	v_mfma_f32_16x16x32_bf16 v[40:43], v[222:225], v[88:91], v[40:43]
	v_mfma_f32_16x16x32_bf16 v[8:11], v[232:235], v[88:91], v[8:11]
	v_mfma_f32_16x16x32_bf16 v[36:39], v[222:225], v[188:191], v[36:39]
	v_mfma_f32_16x16x32_bf16 v[4:7], v[232:235], v[188:191], v[4:7]
	v_mfma_f32_16x16x32_bf16 v[32:35], v[222:225], v[196:199], v[32:35]
	v_mfma_f32_16x16x32_bf16 v[0:3], v[232:235], v[196:199], v[0:3]
	v_mfma_f32_16x16x32_bf16 v[44:47], v[228:231], v[84:87], v[44:47]
	v_mfma_f32_16x16x32_bf16 v[12:15], v[236:239], v[84:87], v[12:15]
	v_mfma_f32_16x16x32_bf16 v[40:43], v[228:231], v[92:95], v[40:43]
	v_mfma_f32_16x16x32_bf16 v[8:11], v[236:239], v[92:95], v[8:11]
	v_mfma_f32_16x16x32_bf16 v[36:39], v[228:231], v[192:195], v[36:39]
	v_mfma_f32_16x16x32_bf16 v[4:7], v[236:239], v[192:195], v[4:7]
	v_mfma_f32_16x16x32_bf16 v[32:35], v[228:231], v[200:203], v[32:35]
	v_mfma_f32_16x16x32_bf16 v[0:3], v[236:239], v[200:203], v[0:3]
	s_setprio 0
	s_add_i32 s37, s37, 2
	s_add_u32 s86, s86, 0x100
	s_addc_u32 s87, s87, 0
	s_add_u32 s33, s33, 0x100
	s_addc_u32 s36, s36, 0
	s_cmp_gt_u32 s37, 13
	s_barrier
	s_cbranch_scc0 .LBB0_125
	s_lshl_b32 s1, s84, 8
	v_readlane_b32 s10, v254, 61
	s_add_i32 s1, s1, s10
	v_or_b32_e32 v198, s1, v216
	s_add_i32 s10, s1, 0x80
	v_or_b32_e32 v168, s10, v216
	v_lshl_or_b32 v188, s0, 7, v219
	v_lshlrev_b32_e32 v190, 2, v188
	v_lshlrev_b32_e32 v189, 1, v188
	s_ashr_i32 s11, s1, 5
	s_movk_i32 s10, 0xb00
	s_movk_i32 s20, 0x1600
	s_mov_b32 s101, 0xbfb8aa3b
	s_cmp_eq_u32 s84, s100
	s_cbranch_scc1 .Ldepi_w
	v_ashrrev_i32_e32 v199, 31, v198
	v_ashrrev_i32_e32 v169, 31, v168
	v_lshl_add_u64 v[170:171], v[198:199], 3, s[48:49]
	v_lshl_add_u64 v[172:173], v[168:169], 3, s[48:49]
	global_load_dwordx2 v[176:177], v[170:171], off
	global_load_dwordx2 v[202:203], v[170:171], off offset:128
	global_load_dwordx2 v[206:207], v[170:171], off offset:256
	global_load_dwordx2 v[222:223], v[170:171], off offset:384
	global_load_dwordx2 v[200:201], v[172:173], off
	global_load_dwordx2 v[196:197], v[172:173], off offset:128
	global_load_dwordx2 v[194:195], v[172:173], off offset:256
	global_load_dwordx2 v[192:193], v[172:173], off offset:384

.LBB0_195:
	s_add_u32 s42, s78, 0x80
	s_addc_u32 s43, s79, 0
	s_add_u32 s33, s44, 0x100
	s_addc_u32 s37, s45, 0
	s_mov_b32 s27, 0
	s_waitcnt lgkmcnt(0)
	s_add_i32 s56, s27, 2
	s_add_u32 s44, s42, 0x80
	s_addc_u32 s45, s43, 0
	s_add_i32 s57, 0, 0x10000
	v_add_u32_e32 v140, s57, v207
	ds_read_b128 v[128:131], v140
	ds_read_b128 v[132:135], v140 offset:1024
	ds_read_b128 v[136:139], v140 offset:2048
	ds_read_b128 v[140:143], v140 offset:3072
	s_cmp_eq_u32 s82, s27
	s_cselect_b32 s45, s77, s45
	s_cselect_b32 s44, s76, s44
	s_cselect_b32 s79, s1, s37
	s_cselect_b32 s78, s0, s33
	v_lshl_add_u64 v[176:177], s[42:43], 0, v[190:191]
	s_add_i32 m0, s85, 0xc000
	ds_read_b128 v[146:149], v217
	ds_read_b128 v[150:153], v217 offset:1024
	ds_read_b128 v[154:157], v217 offset:2048
	ds_read_b128 v[158:161], v217 offset:3072
	ds_read_b128 v[162:165], v217 offset:4096
	ds_read_b128 v[166:169], v217 offset:5120
	ds_read_b128 v[194:197], v217 offset:6144
	ds_read_b128 v[198:201], v217 offset:7168
	global_load_lds_dwordx4 v[176:177], off
	v_lshl_add_u64 v[176:177], s[42:43], 0, v[192:193]
	s_add_i32 m0, s85, 0xe000
	s_nop 0
	global_load_lds_dwordx4 v[176:177], off
	s_waitcnt lgkmcnt(8)
	s_setprio 1
	s_barrier
	s_waitcnt lgkmcnt(0)
	v_mfma_f32_16x16x32_bf16 v[124:127], v[128:131], v[146:149], 0
	v_mfma_f32_16x16x32_bf16 v[120:123], v[136:139], v[146:149], 0
	v_mfma_f32_16x16x32_bf16 v[108:111], v[128:131], v[154:157], 0
	v_mfma_f32_16x16x32_bf16 v[104:107], v[136:139], v[154:157], 0
	v_mfma_f32_16x16x32_bf16 v[92:95], v[128:131], v[162:165], 0
	v_mfma_f32_16x16x32_bf16 v[88:91], v[136:139], v[162:165], 0
	v_mfma_f32_16x16x32_bf16 v[76:79], v[128:131], v[194:197], 0
	v_mfma_f32_16x16x32_bf16 v[72:75], v[136:139], v[194:197], 0
	v_mfma_f32_16x16x32_bf16 v[124:127], v[132:135], v[150:153], v[124:127]
	v_mfma_f32_16x16x32_bf16 v[120:123], v[140:143], v[150:153], v[120:123]
	v_mfma_f32_16x16x32_bf16 v[108:111], v[132:135], v[158:161], v[108:111]
	v_mfma_f32_16x16x32_bf16 v[104:107], v[140:143], v[158:161], v[104:107]
	v_mfma_f32_16x16x32_bf16 v[92:95], v[132:135], v[166:169], v[92:95]
	v_mfma_f32_16x16x32_bf16 v[88:91], v[140:143], v[166:169], v[88:91]
	v_mfma_f32_16x16x32_bf16 v[76:79], v[132:135], v[198:201], v[76:79]
	v_mfma_f32_16x16x32_bf16 v[72:75], v[140:143], v[198:201], v[72:75]
	s_barrier
	s_setprio 0
	s_add_i32 s27, 0, 0x14000
	v_add_u32_e32 v176, s27, v207
	s_add_i32 s57, s57, s84
	ds_read_b128 v[202:205], v176
	ds_read_b128 v[218:221], v176 offset:1024
	ds_read_b128 v[222:225], v176 offset:2048
	ds_read_b128 v[228:231], v176 offset:3072
	v_lshl_add_u64 v[176:177], s[78:79], 0, v[144:145]
	s_mov_b32 m0, s57
	v_lshl_add_u64 v[232:233], s[78:79], 0, v[188:189]
	global_load_lds_dwordx4 v[176:177], off
	s_add_i32 m0, s57, 0x2000
	s_nop 0
	global_load_lds_dwordx4 v[232:233], off
	s_setprio 1
	s_barrier
	s_waitcnt lgkmcnt(0)
	v_mfma_f32_16x16x32_bf16 v[116:119], v[202:205], v[146:149], 0
	v_mfma_f32_16x16x32_bf16 v[112:115], v[222:225], v[146:149], 0
	v_mfma_f32_16x16x32_bf16 v[100:103], v[202:205], v[154:157], 0
	v_mfma_f32_16x16x32_bf16 v[96:99], v[222:225], v[154:157], 0
	v_mfma_f32_16x16x32_bf16 v[84:87], v[202:205], v[162:165], 0
	v_mfma_f32_16x16x32_bf16 v[80:83], v[222:225], v[162:165], 0
	v_mfma_f32_16x16x32_bf16 v[68:71], v[202:205], v[194:197], 0
	v_mfma_f32_16x16x32_bf16 v[64:67], v[222:225], v[194:197], 0
	v_mfma_f32_16x16x32_bf16 v[116:119], v[218:221], v[150:153], v[116:119]
	v_mfma_f32_16x16x32_bf16 v[112:115], v[228:231], v[150:153], v[112:115]
	v_mfma_f32_16x16x32_bf16 v[100:103], v[218:221], v[158:161], v[100:103]
	v_mfma_f32_16x16x32_bf16 v[96:99], v[228:231], v[158:161], v[96:99]
	v_mfma_f32_16x16x32_bf16 v[84:87], v[218:221], v[166:169], v[84:87]
	v_mfma_f32_16x16x32_bf16 v[80:83], v[228:231], v[166:169], v[80:83]
	v_mfma_f32_16x16x32_bf16 v[68:71], v[218:221], v[198:201], v[68:71]
	v_mfma_f32_16x16x32_bf16 v[64:67], v[228:231], v[198:201], v[64:67]
	s_setprio 0
	s_mov_b32 m0, s85
	v_lshl_add_u64 v[234:235], s[44:45], 0, v[144:145]
	s_barrier
	ds_read_b128 v[146:149], v217 offset:16384
	ds_read_b128 v[150:153], v217 offset:17408
	ds_read_b128 v[154:157], v217 offset:18432
	ds_read_b128 v[158:161], v217 offset:19456
	ds_read_b128 v[162:165], v217 offset:20480
	ds_read_b128 v[166:169], v217 offset:21504
	ds_read_b128 v[194:197], v217 offset:22528
	ds_read_b128 v[198:201], v217 offset:23552
	global_load_lds_dwordx4 v[234:235], off
	v_lshl_add_u64 v[236:237], s[44:45], 0, v[188:189]
	s_mov_b32 m0, s86
	s_nop 0
	global_load_lds_dwordx4 v[236:237], off
	s_setprio 1
	s_barrier
	s_waitcnt lgkmcnt(0)
	v_mfma_f32_16x16x32_bf16 v[60:63], v[128:131], v[146:149], 0
	v_mfma_f32_16x16x32_bf16 v[56:59], v[136:139], v[146:149], 0
	v_mfma_f32_16x16x32_bf16 v[44:47], v[128:131], v[154:157], 0
	v_mfma_f32_16x16x32_bf16 v[40:43], v[136:139], v[154:157], 0
	v_mfma_f32_16x16x32_bf16 v[28:31], v[128:131], v[162:165], 0
	v_mfma_f32_16x16x32_bf16 v[24:27], v[136:139], v[162:165], 0
	v_mfma_f32_16x16x32_bf16 v[12:15], v[128:131], v[194:197], 0
	v_mfma_f32_16x16x32_bf16 v[8:11], v[136:139], v[194:197], 0
	v_mfma_f32_16x16x32_bf16 v[60:63], v[132:135], v[150:153], v[60:63]
	v_mfma_f32_16x16x32_bf16 v[56:59], v[140:143], v[150:153], v[56:59]
	v_mfma_f32_16x16x32_bf16 v[44:47], v[132:135], v[158:161], v[44:47]
	v_mfma_f32_16x16x32_bf16 v[40:43], v[140:143], v[158:161], v[40:43]
	v_mfma_f32_16x16x32_bf16 v[28:31], v[132:135], v[166:169], v[28:31]
	v_mfma_f32_16x16x32_bf16 v[24:27], v[140:143], v[166:169], v[24:27]
	v_mfma_f32_16x16x32_bf16 v[12:15], v[132:135], v[198:201], v[12:15]
	v_mfma_f32_16x16x32_bf16 v[8:11], v[140:143], v[198:201], v[8:11]
	s_barrier
	s_setprio 0
	s_add_u32 s58, s78, s98
	s_addc_u32 s59, s79, 0
	s_add_i32 s27, s27, s84
	v_lshl_add_u64 v[238:239], s[58:59], 0, v[144:145]
	s_mov_b32 m0, s27
	v_lshl_add_u64 v[240:241], s[58:59], 0, v[188:189]
	global_load_lds_dwordx4 v[238:239], off
	s_add_i32 m0, s27, 0x2000
	s_nop 0
	global_load_lds_dwordx4 v[240:241], off
	s_waitcnt vmcnt(6)
	s_setprio 1
	s_barrier
	v_mfma_f32_16x16x32_bf16 v[52:55], v[202:205], v[146:149], 0
	v_mfma_f32_16x16x32_bf16 v[48:51], v[222:225], v[146:149], 0
	v_mfma_f32_16x16x32_bf16 v[36:39], v[202:205], v[154:157], 0
	v_mfma_f32_16x16x32_bf16 v[32:35], v[222:225], v[154:157], 0
	v_mfma_f32_16x16x32_bf16 v[20:23], v[202:205], v[162:165], 0
	v_mfma_f32_16x16x32_bf16 v[16:19], v[222:225], v[162:165], 0
	v_mfma_f32_16x16x32_bf16 v[4:7], v[202:205], v[194:197], 0
	v_mfma_f32_16x16x32_bf16 v[0:3], v[222:225], v[194:197], 0
	v_mfma_f32_16x16x32_bf16 v[52:55], v[218:221], v[150:153], v[52:55]
	v_mfma_f32_16x16x32_bf16 v[48:51], v[228:231], v[150:153], v[48:51]
	v_mfma_f32_16x16x32_bf16 v[36:39], v[218:221], v[158:161], v[36:39]
	v_mfma_f32_16x16x32_bf16 v[32:35], v[228:231], v[158:161], v[32:35]
	v_mfma_f32_16x16x32_bf16 v[20:23], v[218:221], v[166:169], v[20:23]
	v_mfma_f32_16x16x32_bf16 v[16:19], v[228:231], v[166:169], v[16:19]
	v_mfma_f32_16x16x32_bf16 v[4:7], v[218:221], v[198:201], v[4:7]
	v_mfma_f32_16x16x32_bf16 v[0:3], v[228:231], v[198:201], v[0:3]
	s_setprio 0
	s_add_i32 s27, 0, 0x18000
	v_add_u32_e32 v140, s27, v207
	s_barrier
	ds_read_b128 v[128:131], v140
	ds_read_b128 v[132:135], v140 offset:1024
	ds_read_b128 v[136:139], v140 offset:2048
	ds_read_b128 v[140:143], v140 offset:3072
	s_add_u32 s44, s44, s98
	s_addc_u32 s45, s45, 0
	s_mov_b32 m0, s87
	v_lshl_add_u64 v[202:203], s[44:45], 0, v[144:145]
	ds_read_b128 v[146:149], v217 offset:32768
	ds_read_b128 v[150:153], v217 offset:33792
	ds_read_b128 v[154:157], v217 offset:34816
	ds_read_b128 v[158:161], v217 offset:35840
	ds_read_b128 v[162:165], v217 offset:36864
	ds_read_b128 v[166:169], v217 offset:37888
	ds_read_b128 v[194:197], v217 offset:38912
	ds_read_b128 v[198:201], v217 offset:39936
	global_load_lds_dwordx4 v[202:203], off
	v_lshl_add_u64 v[202:203], s[44:45], 0, v[188:189]
	s_mov_b32 m0, s80
	s_nop 0
	global_load_lds_dwordx4 v[202:203], off
	s_waitcnt lgkmcnt(8)
	s_setprio 1
	s_barrier
	s_waitcnt lgkmcnt(0)
	v_mfma_f32_16x16x32_bf16 v[124:127], v[128:131], v[146:149], v[124:127]
	v_mfma_f32_16x16x32_bf16 v[120:123], v[136:139], v[146:149], v[120:123]
	v_mfma_f32_16x16x32_bf16 v[108:111], v[128:131], v[154:157], v[108:111]
	v_mfma_f32_16x16x32_bf16 v[104:107], v[136:139], v[154:157], v[104:107]
	v_mfma_f32_16x16x32_bf16 v[92:95], v[128:131], v[162:165], v[92:95]
	v_mfma_f32_16x16x32_bf16 v[88:91], v[136:139], v[162:165], v[88:91]
	v_mfma_f32_16x16x32_bf16 v[76:79], v[128:131], v[194:197], v[76:79]
	v_mfma_f32_16x16x32_bf16 v[72:75], v[136:139], v[194:197], v[72:75]
	v_mfma_f32_16x16x32_bf16 v[124:127], v[132:135], v[150:153], v[124:127]
	v_mfma_f32_16x16x32_bf16 v[120:123], v[140:143], v[150:153], v[120:123]
	v_mfma_f32_16x16x32_bf16 v[108:111], v[132:135], v[158:161], v[108:111]
	v_mfma_f32_16x16x32_bf16 v[104:107], v[140:143], v[158:161], v[104:107]
	v_mfma_f32_16x16x32_bf16 v[92:95], v[132:135], v[166:169], v[92:95]
	v_mfma_f32_16x16x32_bf16 v[88:91], v[140:143], v[166:169], v[88:91]
	v_mfma_f32_16x16x32_bf16 v[76:79], v[132:135], v[198:201], v[76:79]
	v_mfma_f32_16x16x32_bf16 v[72:75], v[140:143], v[198:201], v[72:75]
	s_barrier
	s_setprio 0
	s_add_i32 s44, 0, 0x1c000
	s_add_i32 s27, s27, s84
	v_add_u32_e32 v228, s44, v207
	v_lshl_add_u64 v[176:177], v[176:177], 0, s[18:19]
	s_mov_b32 m0, s27
	ds_read_b128 v[202:205], v228
	ds_read_b128 v[218:221], v228 offset:1024
	ds_read_b128 v[222:225], v228 offset:2048
	ds_read_b128 v[228:231], v228 offset:3072
	global_load_lds_dwordx4 v[176:177], off
	v_lshl_add_u64 v[176:177], v[232:233], 0, s[18:19]
	s_add_i32 m0, s27, 0x2000
	s_nop 0
	global_load_lds_dwordx4 v[176:177], off
	s_setprio 1
	s_barrier
	s_waitcnt lgkmcnt(0)
	v_mfma_f32_16x16x32_bf16 v[116:119], v[202:205], v[146:149], v[116:119]
	v_mfma_f32_16x16x32_bf16 v[112:115], v[222:225], v[146:149], v[112:115]
	v_mfma_f32_16x16x32_bf16 v[100:103], v[202:205], v[154:157], v[100:103]
	v_mfma_f32_16x16x32_bf16 v[96:99], v[222:225], v[154:157], v[96:99]
	v_mfma_f32_16x16x32_bf16 v[84:87], v[202:205], v[162:165], v[84:87]
	v_mfma_f32_16x16x32_bf16 v[80:83], v[222:225], v[162:165], v[80:83]
	v_mfma_f32_16x16x32_bf16 v[68:71], v[202:205], v[194:197], v[68:71]
	v_mfma_f32_16x16x32_bf16 v[64:67], v[222:225], v[194:197], v[64:67]
	v_mfma_f32_16x16x32_bf16 v[116:119], v[218:221], v[150:153], v[116:119]
	v_mfma_f32_16x16x32_bf16 v[112:115], v[228:231], v[150:153], v[112:115]
	v_mfma_f32_16x16x32_bf16 v[100:103], v[218:221], v[158:161], v[100:103]
	v_mfma_f32_16x16x32_bf16 v[96:99], v[228:231], v[158:161], v[96:99]
	v_mfma_f32_16x16x32_bf16 v[84:87], v[218:221], v[166:169], v[84:87]
	v_mfma_f32_16x16x32_bf16 v[80:83], v[228:231], v[166:169], v[80:83]
	v_mfma_f32_16x16x32_bf16 v[68:71], v[218:221], v[198:201], v[68:71]
	v_mfma_f32_16x16x32_bf16 v[64:67], v[228:231], v[198:201], v[64:67]
	s_setprio 0
	s_mov_b32 m0, s30
	v_lshl_add_u64 v[176:177], v[234:235], 0, s[18:19]
	s_barrier
	ds_read_b128 v[146:149], v217 offset:49152
	ds_read_b128 v[150:153], v217 offset:50176
	ds_read_b128 v[154:157], v217 offset:51200
	ds_read_b128 v[158:161], v217 offset:52224
	ds_read_b128 v[162:165], v217 offset:53248
	ds_read_b128 v[166:169], v217 offset:54272
	ds_read_b128 v[194:197], v217 offset:55296
	ds_read_b128 v[198:201], v217 offset:56320
	global_load_lds_dwordx4 v[176:177], off
	v_lshl_add_u64 v[176:177], v[236:237], 0, s[18:19]
	s_mov_b32 m0, s31
	s_nop 0
	global_load_lds_dwordx4 v[176:177], off
	s_setprio 1
	s_barrier
	s_waitcnt lgkmcnt(0)
	v_mfma_f32_16x16x32_bf16 v[60:63], v[128:131], v[146:149], v[60:63]
	v_mfma_f32_16x16x32_bf16 v[56:59], v[136:139], v[146:149], v[56:59]
	v_mfma_f32_16x16x32_bf16 v[44:47], v[128:131], v[154:157], v[44:47]
	v_mfma_f32_16x16x32_bf16 v[40:43], v[136:139], v[154:157], v[40:43]
	v_mfma_f32_16x16x32_bf16 v[28:31], v[128:131], v[162:165], v[28:31]
	v_mfma_f32_16x16x32_bf16 v[24:27], v[136:139], v[162:165], v[24:27]
	v_mfma_f32_16x16x32_bf16 v[12:15], v[128:131], v[194:197], v[12:15]
	v_mfma_f32_16x16x32_bf16 v[8:11], v[136:139], v[194:197], v[8:11]
	v_mfma_f32_16x16x32_bf16 v[60:63], v[132:135], v[150:153], v[60:63]
	v_mfma_f32_16x16x32_bf16 v[56:59], v[140:143], v[150:153], v[56:59]
	v_mfma_f32_16x16x32_bf16 v[44:47], v[132:135], v[158:161], v[44:47]
	v_mfma_f32_16x16x32_bf16 v[40:43], v[140:143], v[158:161], v[40:43]
	v_mfma_f32_16x16x32_bf16 v[28:31], v[132:135], v[166:169], v[28:31]
	v_mfma_f32_16x16x32_bf16 v[24:27], v[140:143], v[166:169], v[24:27]
	v_mfma_f32_16x16x32_bf16 v[12:15], v[132:135], v[198:201], v[12:15]
	v_mfma_f32_16x16x32_bf16 v[8:11], v[140:143], v[198:201], v[8:11]
	s_barrier
	s_setprio 0
	s_add_i32 s27, s44, s84
	v_lshl_add_u64 v[128:129], v[238:239], 0, s[18:19]
	s_mov_b32 m0, s27
	s_nop 0
	global_load_lds_dwordx4 v[128:129], off
	v_lshl_add_u64 v[128:129], v[240:241], 0, s[18:19]
	s_add_i32 m0, s27, 0x2000
	s_nop 0
	global_load_lds_dwordx4 v[128:129], off
	s_waitcnt vmcnt(6)
	s_setprio 1
	s_barrier
	v_mfma_f32_16x16x32_bf16 v[52:55], v[202:205], v[146:149], v[52:55]
	v_mfma_f32_16x16x32_bf16 v[48:51], v[222:225], v[146:149], v[48:51]
	v_mfma_f32_16x16x32_bf16 v[36:39], v[202:205], v[154:157], v[36:39]
	v_mfma_f32_16x16x32_bf16 v[32:35], v[222:225], v[154:157], v[32:35]
	v_mfma_f32_16x16x32_bf16 v[20:23], v[202:205], v[162:165], v[20:23]
	v_mfma_f32_16x16x32_bf16 v[16:19], v[222:225], v[162:165], v[16:19]
	v_mfma_f32_16x16x32_bf16 v[4:7], v[202:205], v[194:197], v[4:7]
	v_mfma_f32_16x16x32_bf16 v[0:3], v[222:225], v[194:197], v[0:3]
	v_mfma_f32_16x16x32_bf16 v[52:55], v[218:221], v[150:153], v[52:55]
	v_mfma_f32_16x16x32_bf16 v[48:51], v[228:231], v[150:153], v[48:51]
	v_mfma_f32_16x16x32_bf16 v[36:39], v[218:221], v[158:161], v[36:39]
	v_mfma_f32_16x16x32_bf16 v[32:35], v[228:231], v[158:161], v[32:35]
	v_mfma_f32_16x16x32_bf16 v[20:23], v[218:221], v[166:169], v[20:23]
	v_mfma_f32_16x16x32_bf16 v[16:19], v[228:231], v[166:169], v[16:19]
	v_mfma_f32_16x16x32_bf16 v[4:7], v[218:221], v[198:201], v[4:7]
	v_mfma_f32_16x16x32_bf16 v[0:3], v[228:231], v[198:201], v[0:3]
	s_setprio 0
	s_add_u32 s42, s42, 0x100
	s_addc_u32 s43, s43, 0
	s_add_u32 s33, s33, 0x100
	s_addc_u32 s37, s37, 0
	s_cmp_ge_u32 s56, s34
	s_mov_b32 s27, s56
	s_barrier
.LBB0_196:
	s_add_i32 s56, s27, 2
	s_add_u32 s44, s42, 0x80
	s_addc_u32 s45, s43, 0
	s_add_i32 s57, 0, 0x10000
	v_add_u32_e32 v140, s57, v207
	ds_read_b128 v[128:131], v140
	ds_read_b128 v[132:135], v140 offset:1024
	ds_read_b128 v[136:139], v140 offset:2048
	ds_read_b128 v[140:143], v140 offset:3072
	s_cmp_eq_u32 s82, s27
	s_cselect_b32 s45, s77, s45
	s_cselect_b32 s44, s76, s44
	s_cselect_b32 s79, s1, s37
	s_cselect_b32 s78, s0, s33
	v_lshl_add_u64 v[176:177], s[42:43], 0, v[190:191]
	s_add_i32 m0, s85, 0xc000
	ds_read_b128 v[146:149], v217
	ds_read_b128 v[150:153], v217 offset:1024
	ds_read_b128 v[154:157], v217 offset:2048
	ds_read_b128 v[158:161], v217 offset:3072
	ds_read_b128 v[162:165], v217 offset:4096
	ds_read_b128 v[166:169], v217 offset:5120
	ds_read_b128 v[194:197], v217 offset:6144
	ds_read_b128 v[198:201], v217 offset:7168
	global_load_lds_dwordx4 v[176:177], off
	v_lshl_add_u64 v[176:177], s[42:43], 0, v[192:193]
	s_add_i32 m0, s85, 0xe000
	s_nop 0
	global_load_lds_dwordx4 v[176:177], off
	s_waitcnt lgkmcnt(8)
	s_barrier
	s_waitcnt lgkmcnt(0)
	s_setprio 1
	s_waitcnt lgkmcnt(0)
	v_mfma_f32_16x16x32_bf16 v[124:127], v[128:131], v[146:149], v[124:127]
	v_mfma_f32_16x16x32_bf16 v[120:123], v[136:139], v[146:149], v[120:123]
	v_mfma_f32_16x16x32_bf16 v[108:111], v[128:131], v[154:157], v[108:111]
	v_mfma_f32_16x16x32_bf16 v[104:107], v[136:139], v[154:157], v[104:107]
	v_mfma_f32_16x16x32_bf16 v[92:95], v[128:131], v[162:165], v[92:95]
	v_mfma_f32_16x16x32_bf16 v[88:91], v[136:139], v[162:165], v[88:91]
	v_mfma_f32_16x16x32_bf16 v[76:79], v[128:131], v[194:197], v[76:79]
	v_mfma_f32_16x16x32_bf16 v[72:75], v[136:139], v[194:197], v[72:75]
	v_mfma_f32_16x16x32_bf16 v[124:127], v[132:135], v[150:153], v[124:127]
	v_mfma_f32_16x16x32_bf16 v[120:123], v[140:143], v[150:153], v[120:123]
	v_mfma_f32_16x16x32_bf16 v[108:111], v[132:135], v[158:161], v[108:111]
	v_mfma_f32_16x16x32_bf16 v[104:107], v[140:143], v[158:161], v[104:107]
	v_mfma_f32_16x16x32_bf16 v[92:95], v[132:135], v[166:169], v[92:95]
	v_mfma_f32_16x16x32_bf16 v[88:91], v[140:143], v[166:169], v[88:91]
	v_mfma_f32_16x16x32_bf16 v[76:79], v[132:135], v[198:201], v[76:79]
	v_mfma_f32_16x16x32_bf16 v[72:75], v[140:143], v[198:201], v[72:75]
	s_barrier
	s_setprio 0
	s_add_i32 s27, 0, 0x14000
	v_add_u32_e32 v176, s27, v207
	s_add_i32 s57, s57, s84
	ds_read_b128 v[202:205], v176
	ds_read_b128 v[218:221], v176 offset:1024
	ds_read_b128 v[222:225], v176 offset:2048
	ds_read_b128 v[228:231], v176 offset:3072
	v_lshl_add_u64 v[176:177], s[78:79], 0, v[144:145]
	s_mov_b32 m0, s57
	v_lshl_add_u64 v[232:233], s[78:79], 0, v[188:189]
	global_load_lds_dwordx4 v[176:177], off
	s_add_i32 m0, s57, 0x2000
	s_nop 0
	global_load_lds_dwordx4 v[232:233], off
	s_barrier
	s_waitcnt lgkmcnt(0)
	s_setprio 1
	s_waitcnt lgkmcnt(0)
	v_mfma_f32_16x16x32_bf16 v[116:119], v[202:205], v[146:149], v[116:119]
	v_mfma_f32_16x16x32_bf16 v[112:115], v[222:225], v[146:149], v[112:115]
	v_mfma_f32_16x16x32_bf16 v[100:103], v[202:205], v[154:157], v[100:103]
	v_mfma_f32_16x16x32_bf16 v[96:99], v[222:225], v[154:157], v[96:99]
	v_mfma_f32_16x16x32_bf16 v[84:87], v[202:205], v[162:165], v[84:87]
	v_mfma_f32_16x16x32_bf16 v[80:83], v[222:225], v[162:165], v[80:83]
	v_mfma_f32_16x16x32_bf16 v[68:71], v[202:205], v[194:197], v[68:71]
	v_mfma_f32_16x16x32_bf16 v[64:67], v[222:225], v[194:197], v[64:67]
	v_mfma_f32_16x16x32_bf16 v[116:119], v[218:221], v[150:153], v[116:119]
	v_mfma_f32_16x16x32_bf16 v[112:115], v[228:231], v[150:153], v[112:115]
	v_mfma_f32_16x16x32_bf16 v[100:103], v[218:221], v[158:161], v[100:103]
	v_mfma_f32_16x16x32_bf16 v[96:99], v[228:231], v[158:161], v[96:99]
	v_mfma_f32_16x16x32_bf16 v[84:87], v[218:221], v[166:169], v[84:87]
	v_mfma_f32_16x16x32_bf16 v[80:83], v[228:231], v[166:169], v[80:83]
	v_mfma_f32_16x16x32_bf16 v[68:71], v[218:221], v[198:201], v[68:71]
	v_mfma_f32_16x16x32_bf16 v[64:67], v[228:231], v[198:201], v[64:67]
	s_setprio 0
	s_mov_b32 m0, s85
	v_lshl_add_u64 v[234:235], s[44:45], 0, v[144:145]
	s_barrier
	ds_read_b128 v[146:149], v217 offset:16384
	ds_read_b128 v[150:153], v217 offset:17408
	ds_read_b128 v[154:157], v217 offset:18432
	ds_read_b128 v[158:161], v217 offset:19456
	ds_read_b128 v[162:165], v217 offset:20480
	ds_read_b128 v[166:169], v217 offset:21504
	ds_read_b128 v[194:197], v217 offset:22528
	ds_read_b128 v[198:201], v217 offset:23552
	global_load_lds_dwordx4 v[234:235], off
	v_lshl_add_u64 v[236:237], s[44:45], 0, v[188:189]
	s_mov_b32 m0, s86
	s_nop 0
	global_load_lds_dwordx4 v[236:237], off
	s_barrier
	s_waitcnt lgkmcnt(0)
	s_setprio 1
	s_waitcnt lgkmcnt(0)
	v_mfma_f32_16x16x32_bf16 v[60:63], v[128:131], v[146:149], v[60:63]
	v_mfma_f32_16x16x32_bf16 v[56:59], v[136:139], v[146:149], v[56:59]
	v_mfma_f32_16x16x32_bf16 v[44:47], v[128:131], v[154:157], v[44:47]
	v_mfma_f32_16x16x32_bf16 v[40:43], v[136:139], v[154:157], v[40:43]
	v_mfma_f32_16x16x32_bf16 v[28:31], v[128:131], v[162:165], v[28:31]
	v_mfma_f32_16x16x32_bf16 v[24:27], v[136:139], v[162:165], v[24:27]
	v_mfma_f32_16x16x32_bf16 v[12:15], v[128:131], v[194:197], v[12:15]
	v_mfma_f32_16x16x32_bf16 v[8:11], v[136:139], v[194:197], v[8:11]
	v_mfma_f32_16x16x32_bf16 v[60:63], v[132:135], v[150:153], v[60:63]
	v_mfma_f32_16x16x32_bf16 v[56:59], v[140:143], v[150:153], v[56:59]
	v_mfma_f32_16x16x32_bf16 v[44:47], v[132:135], v[158:161], v[44:47]
	v_mfma_f32_16x16x32_bf16 v[40:43], v[140:143], v[158:161], v[40:43]
	v_mfma_f32_16x16x32_bf16 v[28:31], v[132:135], v[166:169], v[28:31]
	v_mfma_f32_16x16x32_bf16 v[24:27], v[140:143], v[166:169], v[24:27]
	v_mfma_f32_16x16x32_bf16 v[12:15], v[132:135], v[198:201], v[12:15]
	v_mfma_f32_16x16x32_bf16 v[8:11], v[140:143], v[198:201], v[8:11]
	s_barrier
	s_setprio 0
	s_add_u32 s58, s78, s98
	s_addc_u32 s59, s79, 0
	s_add_i32 s27, s27, s84
	v_lshl_add_u64 v[238:239], s[58:59], 0, v[144:145]
	s_mov_b32 m0, s27
	v_lshl_add_u64 v[240:241], s[58:59], 0, v[188:189]
	global_load_lds_dwordx4 v[238:239], off
	s_add_i32 m0, s27, 0x2000
	s_nop 0
	global_load_lds_dwordx4 v[240:241], off
	s_waitcnt vmcnt(6)
	s_setprio 1
	s_barrier
	v_mfma_f32_16x16x32_bf16 v[52:55], v[202:205], v[146:149], v[52:55]
	v_mfma_f32_16x16x32_bf16 v[48:51], v[222:225], v[146:149], v[48:51]
	v_mfma_f32_16x16x32_bf16 v[36:39], v[202:205], v[154:157], v[36:39]
	v_mfma_f32_16x16x32_bf16 v[32:35], v[222:225], v[154:157], v[32:35]
	v_mfma_f32_16x16x32_bf16 v[20:23], v[202:205], v[162:165], v[20:23]
	v_mfma_f32_16x16x32_bf16 v[16:19], v[222:225], v[162:165], v[16:19]
	v_mfma_f32_16x16x32_bf16 v[4:7], v[202:205], v[194:197], v[4:7]
	v_mfma_f32_16x16x32_bf16 v[0:3], v[222:225], v[194:197], v[0:3]
	v_mfma_f32_16x16x32_bf16 v[52:55], v[218:221], v[150:153], v[52:55]
	v_mfma_f32_16x16x32_bf16 v[48:51], v[228:231], v[150:153], v[48:51]
	v_mfma_f32_16x16x32_bf16 v[36:39], v[218:221], v[158:161], v[36:39]
	v_mfma_f32_16x16x32_bf16 v[32:35], v[228:231], v[158:161], v[32:35]
	v_mfma_f32_16x16x32_bf16 v[20:23], v[218:221], v[166:169], v[20:23]
	v_mfma_f32_16x16x32_bf16 v[16:19], v[228:231], v[166:169], v[16:19]
	v_mfma_f32_16x16x32_bf16 v[4:7], v[218:221], v[198:201], v[4:7]
	v_mfma_f32_16x16x32_bf16 v[0:3], v[228:231], v[198:201], v[0:3]
	s_setprio 0
	s_add_i32 s27, 0, 0x18000
	v_add_u32_e32 v140, s27, v207
	s_barrier
	ds_read_b128 v[128:131], v140
	ds_read_b128 v[132:135], v140 offset:1024
	ds_read_b128 v[136:139], v140 offset:2048
	ds_read_b128 v[140:143], v140 offset:3072
	s_add_u32 s44, s44, s98
	s_addc_u32 s45, s45, 0
	s_mov_b32 m0, s87
	v_lshl_add_u64 v[202:203], s[44:45], 0, v[144:145]
	ds_read_b128 v[146:149], v217 offset:32768
	ds_read_b128 v[150:153], v217 offset:33792
	ds_read_b128 v[154:157], v217 offset:34816
	ds_read_b128 v[158:161], v217 offset:35840
	ds_read_b128 v[162:165], v217 offset:36864
	ds_read_b128 v[166:169], v217 offset:37888
	ds_read_b128 v[194:197], v217 offset:38912
	ds_read_b128 v[198:201], v217 offset:39936
	global_load_lds_dwordx4 v[202:203], off
	v_lshl_add_u64 v[202:203], s[44:45], 0, v[188:189]
	s_mov_b32 m0, s80
	s_nop 0
	global_load_lds_dwordx4 v[202:203], off
	s_waitcnt lgkmcnt(8)
	s_barrier
	s_waitcnt lgkmcnt(0)
	s_setprio 1
	s_waitcnt lgkmcnt(0)
	v_mfma_f32_16x16x32_bf16 v[124:127], v[128:131], v[146:149], v[124:127]
	v_mfma_f32_16x16x32_bf16 v[120:123], v[136:139], v[146:149], v[120:123]
	v_mfma_f32_16x16x32_bf16 v[108:111], v[128:131], v[154:157], v[108:111]
	v_mfma_f32_16x16x32_bf16 v[104:107], v[136:139], v[154:157], v[104:107]
	v_mfma_f32_16x16x32_bf16 v[92:95], v[128:131], v[162:165], v[92:95]
	v_mfma_f32_16x16x32_bf16 v[88:91], v[136:139], v[162:165], v[88:91]
	v_mfma_f32_16x16x32_bf16 v[76:79], v[128:131], v[194:197], v[76:79]
	v_mfma_f32_16x16x32_bf16 v[72:75], v[136:139], v[194:197], v[72:75]
	v_mfma_f32_16x16x32_bf16 v[124:127], v[132:135], v[150:153], v[124:127]
	v_mfma_f32_16x16x32_bf16 v[120:123], v[140:143], v[150:153], v[120:123]
	v_mfma_f32_16x16x32_bf16 v[108:111], v[132:135], v[158:161], v[108:111]
	v_mfma_f32_16x16x32_bf16 v[104:107], v[140:143], v[158:161], v[104:107]
	v_mfma_f32_16x16x32_bf16 v[92:95], v[132:135], v[166:169], v[92:95]
	v_mfma_f32_16x16x32_bf16 v[88:91], v[140:143], v[166:169], v[88:91]
	v_mfma_f32_16x16x32_bf16 v[76:79], v[132:135], v[198:201], v[76:79]
	v_mfma_f32_16x16x32_bf16 v[72:75], v[140:143], v[198:201], v[72:75]
	s_barrier
	s_setprio 0
	s_add_i32 s44, 0, 0x1c000
	s_add_i32 s27, s27, s84
	v_add_u32_e32 v228, s44, v207
	v_lshl_add_u64 v[176:177], v[176:177], 0, s[18:19]
	s_mov_b32 m0, s27
	ds_read_b128 v[202:205], v228
	ds_read_b128 v[218:221], v228 offset:1024
	ds_read_b128 v[222:225], v228 offset:2048
	ds_read_b128 v[228:231], v228 offset:3072
	global_load_lds_dwordx4 v[176:177], off
	v_lshl_add_u64 v[176:177], v[232:233], 0, s[18:19]
	s_add_i32 m0, s27, 0x2000
	s_nop 0
	global_load_lds_dwordx4 v[176:177], off
	s_barrier
	s_waitcnt lgkmcnt(0)
	s_setprio 1
	s_waitcnt lgkmcnt(0)
	v_mfma_f32_16x16x32_bf16 v[116:119], v[202:205], v[146:149], v[116:119]
	v_mfma_f32_16x16x32_bf16 v[112:115], v[222:225], v[146:149], v[112:115]
	v_mfma_f32_16x16x32_bf16 v[100:103], v[202:205], v[154:157], v[100:103]
	v_mfma_f32_16x16x32_bf16 v[96:99], v[222:225], v[154:157], v[96:99]
	v_mfma_f32_16x16x32_bf16 v[84:87], v[202:205], v[162:165], v[84:87]
	v_mfma_f32_16x16x32_bf16 v[80:83], v[222:225], v[162:165], v[80:83]
	v_mfma_f32_16x16x32_bf16 v[68:71], v[202:205], v[194:197], v[68:71]
	v_mfma_f32_16x16x32_bf16 v[64:67], v[222:225], v[194:197], v[64:67]
	v_mfma_f32_16x16x32_bf16 v[116:119], v[218:221], v[150:153], v[116:119]
	v_mfma_f32_16x16x32_bf16 v[112:115], v[228:231], v[150:153], v[112:115]
	v_mfma_f32_16x16x32_bf16 v[100:103], v[218:221], v[158:161], v[100:103]
	v_mfma_f32_16x16x32_bf16 v[96:99], v[228:231], v[158:161], v[96:99]
	v_mfma_f32_16x16x32_bf16 v[84:87], v[218:221], v[166:169], v[84:87]
	v_mfma_f32_16x16x32_bf16 v[80:83], v[228:231], v[166:169], v[80:83]
	v_mfma_f32_16x16x32_bf16 v[68:71], v[218:221], v[198:201], v[68:71]
	v_mfma_f32_16x16x32_bf16 v[64:67], v[228:231], v[198:201], v[64:67]
	s_setprio 0
	s_mov_b32 m0, s30
	v_lshl_add_u64 v[176:177], v[234:235], 0, s[18:19]
	s_barrier
	ds_read_b128 v[146:149], v217 offset:49152
	ds_read_b128 v[150:153], v217 offset:50176
	ds_read_b128 v[154:157], v217 offset:51200
	ds_read_b128 v[158:161], v217 offset:52224
	ds_read_b128 v[162:165], v217 offset:53248
	ds_read_b128 v[166:169], v217 offset:54272
	ds_read_b128 v[194:197], v217 offset:55296
	ds_read_b128 v[198:201], v217 offset:56320
	global_load_lds_dwordx4 v[176:177], off
	v_lshl_add_u64 v[176:177], v[236:237], 0, s[18:19]
	s_mov_b32 m0, s31
	s_nop 0
	global_load_lds_dwordx4 v[176:177], off
	s_barrier
	s_waitcnt lgkmcnt(0)
	s_setprio 1
	s_waitcnt lgkmcnt(0)
	v_mfma_f32_16x16x32_bf16 v[60:63], v[128:131], v[146:149], v[60:63]
	v_mfma_f32_16x16x32_bf16 v[56:59], v[136:139], v[146:149], v[56:59]
	v_mfma_f32_16x16x32_bf16 v[44:47], v[128:131], v[154:157], v[44:47]
	v_mfma_f32_16x16x32_bf16 v[40:43], v[136:139], v[154:157], v[40:43]
	v_mfma_f32_16x16x32_bf16 v[28:31], v[128:131], v[162:165], v[28:31]
	v_mfma_f32_16x16x32_bf16 v[24:27], v[136:139], v[162:165], v[24:27]
	v_mfma_f32_16x16x32_bf16 v[12:15], v[128:131], v[194:197], v[12:15]
	v_mfma_f32_16x16x32_bf16 v[8:11], v[136:139], v[194:197], v[8:11]
	v_mfma_f32_16x16x32_bf16 v[60:63], v[132:135], v[150:153], v[60:63]
	v_mfma_f32_16x16x32_bf16 v[56:59], v[140:143], v[150:153], v[56:59]
	v_mfma_f32_16x16x32_bf16 v[44:47], v[132:135], v[158:161], v[44:47]
	v_mfma_f32_16x16x32_bf16 v[40:43], v[140:143], v[158:161], v[40:43]
	v_mfma_f32_16x16x32_bf16 v[28:31], v[132:135], v[166:169], v[28:31]
	v_mfma_f32_16x16x32_bf16 v[24:27], v[140:143], v[166:169], v[24:27]
	v_mfma_f32_16x16x32_bf16 v[12:15], v[132:135], v[198:201], v[12:15]
	v_mfma_f32_16x16x32_bf16 v[8:11], v[140:143], v[198:201], v[8:11]
	s_barrier
	s_setprio 0
	s_add_i32 s27, s44, s84
	v_lshl_add_u64 v[128:129], v[238:239], 0, s[18:19]
	s_mov_b32 m0, s27
	s_nop 0
	global_load_lds_dwordx4 v[128:129], off
	v_lshl_add_u64 v[128:129], v[240:241], 0, s[18:19]
	s_add_i32 m0, s27, 0x2000
	s_nop 0
	global_load_lds_dwordx4 v[128:129], off
	s_waitcnt vmcnt(6)
	s_setprio 1
	s_barrier
	v_mfma_f32_16x16x32_bf16 v[52:55], v[202:205], v[146:149], v[52:55]
	v_mfma_f32_16x16x32_bf16 v[48:51], v[222:225], v[146:149], v[48:51]
	v_mfma_f32_16x16x32_bf16 v[36:39], v[202:205], v[154:157], v[36:39]
	v_mfma_f32_16x16x32_bf16 v[32:35], v[222:225], v[154:157], v[32:35]
	v_mfma_f32_16x16x32_bf16 v[20:23], v[202:205], v[162:165], v[20:23]
	v_mfma_f32_16x16x32_bf16 v[16:19], v[222:225], v[162:165], v[16:19]
	v_mfma_f32_16x16x32_bf16 v[4:7], v[202:205], v[194:197], v[4:7]
	v_mfma_f32_16x16x32_bf16 v[0:3], v[222:225], v[194:197], v[0:3]
	v_mfma_f32_16x16x32_bf16 v[52:55], v[218:221], v[150:153], v[52:55]
	v_mfma_f32_16x16x32_bf16 v[48:51], v[228:231], v[150:153], v[48:51]
	v_mfma_f32_16x16x32_bf16 v[36:39], v[218:221], v[158:161], v[36:39]
	v_mfma_f32_16x16x32_bf16 v[32:35], v[228:231], v[158:161], v[32:35]
	v_mfma_f32_16x16x32_bf16 v[20:23], v[218:221], v[166:169], v[20:23]
	v_mfma_f32_16x16x32_bf16 v[16:19], v[228:231], v[166:169], v[16:19]
	v_mfma_f32_16x16x32_bf16 v[4:7], v[218:221], v[198:201], v[4:7]
	v_mfma_f32_16x16x32_bf16 v[0:3], v[228:231], v[198:201], v[0:3]
	s_setprio 0
	s_add_u32 s42, s42, 0x100
	s_addc_u32 s43, s43, 0
	s_add_u32 s33, s33, 0x100
	s_addc_u32 s37, s37, 0
	s_cmp_ge_u32 s56, s34
	s_mov_b32 s27, s56
	s_barrier
	s_cbranch_scc0 .LBB0_196
	v_lshl_add_u32 v194, s11, 8, v206
	v_ashrrev_i32_e32 v195, 31, v194
	v_lshl_or_b32 v196, s10, 8, v216
	v_lshlrev_b64 v[128:129], 11, v[194:195]
	v_ashrrev_i32_e32 v197, 31, v196
	s_and_b64 vcc, exec, s[92:93]
	v_or_b32_e32 v198, 16, v194
	v_lshl_add_u64 v[200:201], s[54:55], 0, v[128:129]
	s_cbranch_vccz .LBB0_215
	v_lshlrev_b64 v[128:129], 12, v[194:195]
	v_lshl_add_u64 v[128:129], s[50:51], 0, v[128:129]
	v_lshlrev_b64 v[130:131], 2, v[196:197]
	v_lshl_add_u64 v[128:129], v[128:129], 0, v[130:131]
	global_load_dwordx4 v[146:149], v[128:129], off offset:16
	global_load_dwordx4 v[150:153], v[128:129], off
	global_load_dwordx4 v[154:157], v[128:129], off offset:528
	global_load_dwordx4 v[158:161], v[128:129], off offset:512
	v_ashrrev_i32_e32 v199, 31, v198
	v_lshlrev_b64 v[128:129], 12, v[198:199]
	v_lshl_add_u64 v[128:129], s[50:51], 0, v[128:129]
	v_lshl_add_u64 v[132:133], v[128:129], 0, v[130:131]
	global_load_dwordx4 v[136:139], v[132:133], off offset:16
	global_load_dwordx4 v[140:143], v[132:133], off
	global_load_dwordx4 v[128:131], v[132:133], off offset:528
	s_nop 0
	global_load_dwordx4 v[132:135], v[132:133], off offset:512
	v_lshl_add_u64 v[166:167], v[196:197], 1, v[200:201]
	s_waitcnt vmcnt(0)
	v_pk_add_f32 v[164:165], v[120:121], v[146:147]
	v_pk_add_f32 v[152:153], v[126:127], v[152:153]
	v_pk_add_f32 v[150:151], v[124:125], v[150:151]
	v_pk_add_f32 v[162:163], v[122:123], v[148:149]
	v_cvt_pk_bf16_f32 v146, v150, v151
	v_cvt_pk_bf16_f32 v147, v152, v153
	v_cvt_pk_bf16_f32 v148, v164, v165
	v_pk_add_f32 v[156:157], v[114:115], v[156:157]
	v_cvt_pk_bf16_f32 v149, v162, v163
	global_store_dwordx4 v[166:167], v[146:149], off
	v_pk_add_f32 v[154:155], v[112:113], v[154:155]
	s_nop 0
	v_mul_f32_e32 v146, v151, v151
	v_mul_f32_e32 v147, v153, v153
	v_fmac_f32_e32 v146, v150, v150
	v_fmac_f32_e32 v147, v152, v152
	v_add_f32_e32 v146, v146, v147
	v_mul_f32_e32 v147, v165, v165
	v_mul_f32_e32 v148, v163, v163
	v_fmac_f32_e32 v147, v164, v164
	v_fmac_f32_e32 v148, v162, v162
	v_add_f32_e32 v147, v147, v148
	v_add_f32_e32 v162, v146, v147
	v_pk_add_f32 v[150:151], v[118:119], v[160:161]
	v_pk_add_f32 v[152:153], v[116:117], v[158:159]
	s_nop 0
	v_cvt_pk_bf16_f32 v146, v152, v153
	v_cvt_pk_bf16_f32 v147, v150, v151
	v_cvt_pk_bf16_f32 v148, v154, v155
	v_cvt_pk_bf16_f32 v149, v156, v157
	global_store_dwordx4 v[166:167], v[146:149], off offset:256
	s_nop 1
	v_mul_f32_e32 v146, v153, v153
	v_mul_f32_e32 v147, v151, v151
	v_fmac_f32_e32 v146, v152, v152
	v_fmac_f32_e32 v147, v150, v150
	v_add_f32_e32 v146, v146, v147
	v_mul_f32_e32 v147, v155, v155
	v_mul_f32_e32 v148, v157, v157
	v_fmac_f32_e32 v147, v154, v154
	v_fmac_f32_e32 v148, v156, v156
	v_add_f32_e32 v147, v147, v148
	v_and_b32_e32 v148, 64, v214
	v_add_f32_e32 v146, v146, v147
	v_xor_b32_e32 v147, 16, v214
	v_add_u32_e32 v148, 64, v148
	v_cmp_lt_i32_e32 vcc, v147, v148
	v_add_f32_e32 v146, v162, v146
	s_nop 0
	v_cndmask_b32_e32 v147, v214, v147, vcc
	v_lshlrev_b32_e32 v218, 2, v147
	ds_bpermute_b32 v147, v218, v146
	s_waitcnt lgkmcnt(0)
	v_add_f32_e32 v146, v146, v147
	v_xor_b32_e32 v147, 32, v214
	v_cmp_lt_i32_e32 vcc, v147, v148
	s_nop 1
	v_cndmask_b32_e32 v147, v214, v147, vcc
	v_lshlrev_b32_e32 v219, 2, v147
	ds_bpermute_b32 v147, v219, v146
	s_and_saveexec_b64 s[42:43], s[38:39]
	s_cbranch_execz .LBB0_200
	s_waitcnt lgkmcnt(0)
	v_add_f32_e32 v146, v146, v147
	v_fma_f32 v146, v146, s91, 0.5
	v_trunc_f32_e32 v146, v146
	v_mul_f32_e32 v147, 0x2f800000, v146
	v_floor_f32_e32 v147, v147
	v_fmac_f32_e32 v146, 0xcf800000, v147
	v_cvt_u32_f32_e32 v146, v146
	v_cvt_u32_f32_e32 v147, v147
	v_lshl_add_u64 v[148:149], v[194:195], 3, s[52:53]
	global_atomic_add_x2 v[148:149], v[146:147], off

.LBB0_325:
	s_ashr_i32 s93, s92, 31
	s_lshl_b64 s[30:31], s[92:93], 19
	s_add_u32 s94, s54, s30
	v_cmp_lt_i64_e32 vcc, s[50:51], v[186:187]
	s_addc_u32 s95, s55, s31
	s_and_b64 s[30:31], vcc, exec
	s_cselect_b32 s1, s95, s53
	s_cselect_b32 s11, s94, s52
	s_ashr_i32 s9, s8, 31
	s_lshl_b64 s[30:31], s[8:9], 19
	s_add_u32 s28, s80, s30
	s_addc_u32 s29, s78, s31
	s_and_b64 s[30:31], vcc, exec
	s_cselect_b32 s25, s29, s73
	s_cselect_b32 s30, s28, s72
	s_add_u32 s52, s52, 0x40080
	s_addc_u32 s53, s53, 0
	s_add_u32 s31, s72, 0x100
	s_addc_u32 s33, s73, 0
	s_mov_b32 s34, -2
	s_add_u32 s27, s52, 0xfffc0080
	s_addc_u32 s35, s53, -1
	s_add_i32 s36, 0, 0x10000
	v_add_u32_e32 v140, s36, v216
	ds_read_b128 v[128:131], v140
	ds_read_b128 v[132:135], v140 offset:1024
	ds_read_b128 v[136:139], v140 offset:2048
	ds_read_b128 v[140:143], v140 offset:3072
	s_cmp_eq_u32 s34, 12
	s_cselect_b32 s75, s1, s35
	s_cselect_b32 s74, s11, s27
	s_cselect_b32 s73, s25, s33
	s_cselect_b32 s72, s30, s31
	v_lshl_add_u64 v[168:169], s[52:53], 0, v[152:153]
	s_add_i32 m0, s83, 0xc000
	ds_read_b128 v[156:159], v217
	ds_read_b128 v[160:163], v217 offset:1024
	ds_read_b128 v[164:167], v217 offset:2048
	ds_read_b128 v[188:191], v217 offset:3072
	ds_read_b128 v[192:195], v217 offset:4096
	ds_read_b128 v[196:199], v217 offset:5120
	ds_read_b128 v[200:203], v217 offset:6144
	ds_read_b128 v[204:207], v217 offset:7168
	global_load_lds_dwordx4 v[168:169], off
	v_lshl_add_u64 v[168:169], s[52:53], 0, v[154:155]
	s_add_i32 m0, s83, 0xe000
	s_nop 0
	global_load_lds_dwordx4 v[168:169], off
	s_waitcnt lgkmcnt(8)
	s_setprio 1
	s_barrier
	s_waitcnt lgkmcnt(0)
	v_mfma_f32_16x16x32_bf16 v[124:127], v[128:131], v[156:159], 0
	v_mfma_f32_16x16x32_bf16 v[120:123], v[136:139], v[156:159], 0
	v_mfma_f32_16x16x32_bf16 v[108:111], v[128:131], v[164:167], 0
	v_mfma_f32_16x16x32_bf16 v[104:107], v[136:139], v[164:167], 0
	v_mfma_f32_16x16x32_bf16 v[92:95], v[128:131], v[192:195], 0
	v_mfma_f32_16x16x32_bf16 v[88:91], v[136:139], v[192:195], 0
	v_mfma_f32_16x16x32_bf16 v[76:79], v[128:131], v[200:203], 0
	v_mfma_f32_16x16x32_bf16 v[72:75], v[136:139], v[200:203], 0
	v_mfma_f32_16x16x32_bf16 v[124:127], v[132:135], v[160:163], v[124:127]
	v_mfma_f32_16x16x32_bf16 v[120:123], v[140:143], v[160:163], v[120:123]
	v_mfma_f32_16x16x32_bf16 v[108:111], v[132:135], v[188:191], v[108:111]
	v_mfma_f32_16x16x32_bf16 v[104:107], v[140:143], v[188:191], v[104:107]
	v_mfma_f32_16x16x32_bf16 v[92:95], v[132:135], v[196:199], v[92:95]
	v_mfma_f32_16x16x32_bf16 v[88:91], v[140:143], v[196:199], v[88:91]
	v_mfma_f32_16x16x32_bf16 v[76:79], v[132:135], v[204:207], v[76:79]
	v_mfma_f32_16x16x32_bf16 v[72:75], v[140:143], v[204:207], v[72:75]
	s_barrier
	s_setprio 0
	s_add_i32 s27, 0, 0x14000
	s_add_i32 s35, s36, s81
	v_add_u32_e32 v144, s27, v216
	v_lshl_add_u64 v[168:169], s[72:73], 0, v[148:149]
	s_mov_b32 m0, s35
	ds_read_b128 v[220:223], v144
	ds_read_b128 v[228:231], v144 offset:1024
	ds_read_b128 v[232:235], v144 offset:2048
	ds_read_b128 v[236:239], v144 offset:3072
	global_load_lds_dwordx4 v[168:169], off
	v_lshl_add_u64 v[176:177], s[72:73], 0, v[146:147]
	s_add_i32 m0, s35, 0x2000
	s_nop 0
	global_load_lds_dwordx4 v[176:177], off
	s_setprio 1
	s_barrier
	s_waitcnt lgkmcnt(0)
	v_mfma_f32_16x16x32_bf16 v[116:119], v[220:223], v[156:159], 0
	v_mfma_f32_16x16x32_bf16 v[112:115], v[232:235], v[156:159], 0
	v_mfma_f32_16x16x32_bf16 v[100:103], v[220:223], v[164:167], 0
	v_mfma_f32_16x16x32_bf16 v[96:99], v[232:235], v[164:167], 0
	v_mfma_f32_16x16x32_bf16 v[84:87], v[220:223], v[192:195], 0
	v_mfma_f32_16x16x32_bf16 v[80:83], v[232:235], v[192:195], 0
	v_mfma_f32_16x16x32_bf16 v[68:71], v[220:223], v[200:203], 0
	v_mfma_f32_16x16x32_bf16 v[64:67], v[232:235], v[200:203], 0
	v_mfma_f32_16x16x32_bf16 v[116:119], v[228:231], v[160:163], v[116:119]
	v_mfma_f32_16x16x32_bf16 v[112:115], v[236:239], v[160:163], v[112:115]
	v_mfma_f32_16x16x32_bf16 v[100:103], v[228:231], v[188:191], v[100:103]
	v_mfma_f32_16x16x32_bf16 v[96:99], v[236:239], v[188:191], v[96:99]
	v_mfma_f32_16x16x32_bf16 v[84:87], v[228:231], v[196:199], v[84:87]
	v_mfma_f32_16x16x32_bf16 v[80:83], v[236:239], v[196:199], v[80:83]
	v_mfma_f32_16x16x32_bf16 v[68:71], v[228:231], v[204:207], v[68:71]
	v_mfma_f32_16x16x32_bf16 v[64:67], v[236:239], v[204:207], v[64:67]
	s_setprio 0
	s_mov_b32 m0, s83
	v_lshl_add_u64 v[224:225], s[74:75], 0, v[148:149]
	s_barrier
	ds_read_b128 v[156:159], v217 offset:16384
	ds_read_b128 v[160:163], v217 offset:17408
	ds_read_b128 v[164:167], v217 offset:18432
	ds_read_b128 v[188:191], v217 offset:19456
	ds_read_b128 v[192:195], v217 offset:20480
	ds_read_b128 v[196:199], v217 offset:21504
	ds_read_b128 v[200:203], v217 offset:22528
	ds_read_b128 v[204:207], v217 offset:23552
	global_load_lds_dwordx4 v[224:225], off
	v_lshl_add_u64 v[240:241], s[74:75], 0, v[146:147]
	s_mov_b32 m0, s84
	s_nop 0
	global_load_lds_dwordx4 v[240:241], off
	s_setprio 1
	s_barrier
	s_waitcnt lgkmcnt(0)
	v_mfma_f32_16x16x32_bf16 v[60:63], v[128:131], v[156:159], 0
	v_mfma_f32_16x16x32_bf16 v[56:59], v[136:139], v[156:159], 0
	v_mfma_f32_16x16x32_bf16 v[44:47], v[128:131], v[164:167], 0
	v_mfma_f32_16x16x32_bf16 v[40:43], v[136:139], v[164:167], 0
	v_mfma_f32_16x16x32_bf16 v[28:31], v[128:131], v[192:195], 0
	v_mfma_f32_16x16x32_bf16 v[24:27], v[136:139], v[192:195], 0
	v_mfma_f32_16x16x32_bf16 v[12:15], v[128:131], v[200:203], 0
	v_mfma_f32_16x16x32_bf16 v[8:11], v[136:139], v[200:203], 0
	v_mfma_f32_16x16x32_bf16 v[60:63], v[132:135], v[160:163], v[60:63]
	v_mfma_f32_16x16x32_bf16 v[56:59], v[140:143], v[160:163], v[56:59]
	v_mfma_f32_16x16x32_bf16 v[44:47], v[132:135], v[188:191], v[44:47]
	v_mfma_f32_16x16x32_bf16 v[40:43], v[140:143], v[188:191], v[40:43]
	v_mfma_f32_16x16x32_bf16 v[28:31], v[132:135], v[196:199], v[28:31]
	v_mfma_f32_16x16x32_bf16 v[24:27], v[140:143], v[196:199], v[24:27]
	v_mfma_f32_16x16x32_bf16 v[12:15], v[132:135], v[204:207], v[12:15]
	v_mfma_f32_16x16x32_bf16 v[8:11], v[140:143], v[204:207], v[8:11]
	s_barrier
	s_setprio 0
	s_add_u32 s36, s72, 0x40000
	s_addc_u32 s37, s73, 0
	s_add_i32 s27, s27, s81
	v_lshl_add_u64 v[128:129], s[36:37], 0, v[148:149]
	s_mov_b32 m0, s27
	s_nop 0
	global_load_lds_dwordx4 v[128:129], off
	v_lshl_add_u64 v[128:129], s[36:37], 0, v[146:147]
	s_add_i32 m0, s27, 0x2000
	s_nop 0
	global_load_lds_dwordx4 v[128:129], off
	s_waitcnt vmcnt(6)
	s_setprio 1
	s_barrier
	v_mfma_f32_16x16x32_bf16 v[52:55], v[220:223], v[156:159], 0
	v_mfma_f32_16x16x32_bf16 v[48:51], v[232:235], v[156:159], 0
	v_mfma_f32_16x16x32_bf16 v[36:39], v[220:223], v[164:167], 0
	v_mfma_f32_16x16x32_bf16 v[32:35], v[232:235], v[164:167], 0
	v_mfma_f32_16x16x32_bf16 v[20:23], v[220:223], v[192:195], 0
	v_mfma_f32_16x16x32_bf16 v[16:19], v[232:235], v[192:195], 0
	v_mfma_f32_16x16x32_bf16 v[4:7], v[220:223], v[200:203], 0
	v_mfma_f32_16x16x32_bf16 v[0:3], v[232:235], v[200:203], 0
	v_mfma_f32_16x16x32_bf16 v[52:55], v[228:231], v[160:163], v[52:55]
	v_mfma_f32_16x16x32_bf16 v[48:51], v[236:239], v[160:163], v[48:51]
	v_mfma_f32_16x16x32_bf16 v[36:39], v[228:231], v[188:191], v[36:39]
	v_mfma_f32_16x16x32_bf16 v[32:35], v[236:239], v[188:191], v[32:35]
	v_mfma_f32_16x16x32_bf16 v[20:23], v[228:231], v[196:199], v[20:23]
	v_mfma_f32_16x16x32_bf16 v[16:19], v[236:239], v[196:199], v[16:19]
	v_mfma_f32_16x16x32_bf16 v[4:7], v[228:231], v[204:207], v[4:7]
	v_mfma_f32_16x16x32_bf16 v[0:3], v[236:239], v[204:207], v[0:3]
	s_setprio 0
	s_add_i32 s27, 0, 0x18000
	v_add_u32_e32 v140, s27, v216
	s_barrier
	ds_read_b128 v[128:131], v140
	ds_read_b128 v[132:135], v140 offset:1024
	ds_read_b128 v[136:139], v140 offset:2048
	ds_read_b128 v[140:143], v140 offset:3072
	s_add_u32 s36, s74, 0x40000
	s_addc_u32 s37, s75, 0
	s_mov_b32 m0, s85
	v_lshl_add_u64 v[220:221], s[36:37], 0, v[148:149]
	ds_read_b128 v[156:159], v217 offset:32768
	ds_read_b128 v[160:163], v217 offset:33792
	ds_read_b128 v[164:167], v217 offset:34816
	ds_read_b128 v[188:191], v217 offset:35840
	ds_read_b128 v[192:195], v217 offset:36864
	ds_read_b128 v[196:199], v217 offset:37888
	ds_read_b128 v[200:203], v217 offset:38912
	ds_read_b128 v[204:207], v217 offset:39936
	global_load_lds_dwordx4 v[220:221], off
	v_lshl_add_u64 v[220:221], s[36:37], 0, v[146:147]
	s_mov_b32 m0, s86
	s_nop 0
	global_load_lds_dwordx4 v[220:221], off
	s_waitcnt lgkmcnt(8)
	s_setprio 1
	s_barrier
	s_waitcnt lgkmcnt(0)
	v_mfma_f32_16x16x32_bf16 v[124:127], v[128:131], v[156:159], v[124:127]
	v_mfma_f32_16x16x32_bf16 v[120:123], v[136:139], v[156:159], v[120:123]
	v_mfma_f32_16x16x32_bf16 v[108:111], v[128:131], v[164:167], v[108:111]
	v_mfma_f32_16x16x32_bf16 v[104:107], v[136:139], v[164:167], v[104:107]
	v_mfma_f32_16x16x32_bf16 v[92:95], v[128:131], v[192:195], v[92:95]
	v_mfma_f32_16x16x32_bf16 v[88:91], v[136:139], v[192:195], v[88:91]
	v_mfma_f32_16x16x32_bf16 v[76:79], v[128:131], v[200:203], v[76:79]
	v_mfma_f32_16x16x32_bf16 v[72:75], v[136:139], v[200:203], v[72:75]
	v_mfma_f32_16x16x32_bf16 v[124:127], v[132:135], v[160:163], v[124:127]
	v_mfma_f32_16x16x32_bf16 v[120:123], v[140:143], v[160:163], v[120:123]
	v_mfma_f32_16x16x32_bf16 v[108:111], v[132:135], v[188:191], v[108:111]
	v_mfma_f32_16x16x32_bf16 v[104:107], v[140:143], v[188:191], v[104:107]
	v_mfma_f32_16x16x32_bf16 v[92:95], v[132:135], v[196:199], v[92:95]
	v_mfma_f32_16x16x32_bf16 v[88:91], v[140:143], v[196:199], v[88:91]
	v_mfma_f32_16x16x32_bf16 v[76:79], v[132:135], v[204:207], v[76:79]
	v_mfma_f32_16x16x32_bf16 v[72:75], v[140:143], v[204:207], v[72:75]
	s_barrier
	s_setprio 0
	s_add_i32 s35, 0, 0x1c000
	s_add_i32 s27, s27, s81
	v_add_u32_e32 v144, s35, v216
	v_lshl_add_u64 v[168:169], v[168:169], 0, s[18:19]
	s_mov_b32 m0, s27
	ds_read_b128 v[220:223], v144
	ds_read_b128 v[228:231], v144 offset:1024
	ds_read_b128 v[232:235], v144 offset:2048
	ds_read_b128 v[236:239], v144 offset:3072
	global_load_lds_dwordx4 v[168:169], off
	v_lshl_add_u64 v[168:169], v[176:177], 0, s[18:19]
	s_add_i32 m0, s27, 0x2000
	s_nop 0
	global_load_lds_dwordx4 v[168:169], off
	s_setprio 1
	s_barrier
	s_waitcnt lgkmcnt(0)
	v_mfma_f32_16x16x32_bf16 v[116:119], v[220:223], v[156:159], v[116:119]
	v_mfma_f32_16x16x32_bf16 v[112:115], v[232:235], v[156:159], v[112:115]
	v_mfma_f32_16x16x32_bf16 v[100:103], v[220:223], v[164:167], v[100:103]
	v_mfma_f32_16x16x32_bf16 v[96:99], v[232:235], v[164:167], v[96:99]
	v_mfma_f32_16x16x32_bf16 v[84:87], v[220:223], v[192:195], v[84:87]
	v_mfma_f32_16x16x32_bf16 v[80:83], v[232:235], v[192:195], v[80:83]
	v_mfma_f32_16x16x32_bf16 v[68:71], v[220:223], v[200:203], v[68:71]
	v_mfma_f32_16x16x32_bf16 v[64:67], v[232:235], v[200:203], v[64:67]
	v_mfma_f32_16x16x32_bf16 v[116:119], v[228:231], v[160:163], v[116:119]
	v_mfma_f32_16x16x32_bf16 v[112:115], v[236:239], v[160:163], v[112:115]
	v_mfma_f32_16x16x32_bf16 v[100:103], v[228:231], v[188:191], v[100:103]
	v_mfma_f32_16x16x32_bf16 v[96:99], v[236:239], v[188:191], v[96:99]
	v_mfma_f32_16x16x32_bf16 v[84:87], v[228:231], v[196:199], v[84:87]
	v_mfma_f32_16x16x32_bf16 v[80:83], v[236:239], v[196:199], v[80:83]
	v_mfma_f32_16x16x32_bf16 v[68:71], v[228:231], v[204:207], v[68:71]
	v_mfma_f32_16x16x32_bf16 v[64:67], v[236:239], v[204:207], v[64:67]
	s_setprio 0
	s_mov_b32 m0, s87
	v_lshl_add_u64 v[168:169], v[224:225], 0, s[18:19]
	s_barrier
	ds_read_b128 v[156:159], v217 offset:49152
	ds_read_b128 v[160:163], v217 offset:50176
	ds_read_b128 v[164:167], v217 offset:51200
	ds_read_b128 v[188:191], v217 offset:52224
	ds_read_b128 v[192:195], v217 offset:53248
	ds_read_b128 v[196:199], v217 offset:54272
	ds_read_b128 v[200:203], v217 offset:55296
	ds_read_b128 v[204:207], v217 offset:56320
	global_load_lds_dwordx4 v[168:169], off
	v_lshl_add_u64 v[168:169], v[240:241], 0, s[18:19]
	s_mov_b32 m0, s79
	s_nop 0
	global_load_lds_dwordx4 v[168:169], off
	s_setprio 1
	s_barrier
	s_waitcnt lgkmcnt(0)
	v_mfma_f32_16x16x32_bf16 v[60:63], v[128:131], v[156:159], v[60:63]
	v_mfma_f32_16x16x32_bf16 v[56:59], v[136:139], v[156:159], v[56:59]
	v_mfma_f32_16x16x32_bf16 v[44:47], v[128:131], v[164:167], v[44:47]
	v_mfma_f32_16x16x32_bf16 v[40:43], v[136:139], v[164:167], v[40:43]
	v_mfma_f32_16x16x32_bf16 v[28:31], v[128:131], v[192:195], v[28:31]
	v_mfma_f32_16x16x32_bf16 v[24:27], v[136:139], v[192:195], v[24:27]
	v_mfma_f32_16x16x32_bf16 v[12:15], v[128:131], v[200:203], v[12:15]
	v_mfma_f32_16x16x32_bf16 v[8:11], v[136:139], v[200:203], v[8:11]
	v_mfma_f32_16x16x32_bf16 v[60:63], v[132:135], v[160:163], v[60:63]
	v_mfma_f32_16x16x32_bf16 v[56:59], v[140:143], v[160:163], v[56:59]
	v_mfma_f32_16x16x32_bf16 v[44:47], v[132:135], v[188:191], v[44:47]
	v_mfma_f32_16x16x32_bf16 v[40:43], v[140:143], v[188:191], v[40:43]
	v_mfma_f32_16x16x32_bf16 v[28:31], v[132:135], v[196:199], v[28:31]
	v_mfma_f32_16x16x32_bf16 v[24:27], v[140:143], v[196:199], v[24:27]
	v_mfma_f32_16x16x32_bf16 v[12:15], v[132:135], v[204:207], v[12:15]
	v_mfma_f32_16x16x32_bf16 v[8:11], v[140:143], v[204:207], v[8:11]
	s_barrier
	s_setprio 0
	s_add_u32 s36, s72, 0x40080
	s_addc_u32 s37, s73, 0
	s_add_i32 s27, s35, s81
	v_lshl_add_u64 v[128:129], s[36:37], 0, v[148:149]
	s_mov_b32 m0, s27
	s_nop 0
	global_load_lds_dwordx4 v[128:129], off
	v_lshl_add_u64 v[128:129], s[36:37], 0, v[146:147]
	s_add_i32 m0, s27, 0x2000
	s_nop 0
	global_load_lds_dwordx4 v[128:129], off
	s_waitcnt vmcnt(6)
	s_setprio 1
	s_barrier
	v_mfma_f32_16x16x32_bf16 v[52:55], v[220:223], v[156:159], v[52:55]
	v_mfma_f32_16x16x32_bf16 v[48:51], v[232:235], v[156:159], v[48:51]
	v_mfma_f32_16x16x32_bf16 v[36:39], v[220:223], v[164:167], v[36:39]
	v_mfma_f32_16x16x32_bf16 v[32:35], v[232:235], v[164:167], v[32:35]
	v_mfma_f32_16x16x32_bf16 v[20:23], v[220:223], v[192:195], v[20:23]
	v_mfma_f32_16x16x32_bf16 v[16:19], v[232:235], v[192:195], v[16:19]
	v_mfma_f32_16x16x32_bf16 v[4:7], v[220:223], v[200:203], v[4:7]
	v_mfma_f32_16x16x32_bf16 v[0:3], v[232:235], v[200:203], v[0:3]
	v_mfma_f32_16x16x32_bf16 v[52:55], v[228:231], v[160:163], v[52:55]
	v_mfma_f32_16x16x32_bf16 v[48:51], v[236:239], v[160:163], v[48:51]
	v_mfma_f32_16x16x32_bf16 v[36:39], v[228:231], v[188:191], v[36:39]
	v_mfma_f32_16x16x32_bf16 v[32:35], v[236:239], v[188:191], v[32:35]
	v_mfma_f32_16x16x32_bf16 v[20:23], v[228:231], v[196:199], v[20:23]
	v_mfma_f32_16x16x32_bf16 v[16:19], v[236:239], v[196:199], v[16:19]
	v_mfma_f32_16x16x32_bf16 v[4:7], v[228:231], v[204:207], v[4:7]
	v_mfma_f32_16x16x32_bf16 v[0:3], v[236:239], v[204:207], v[0:3]
	s_setprio 0
	s_add_i32 s34, s34, 2
	s_add_u32 s52, s52, 0x100
	s_addc_u32 s53, s53, 0
	s_add_u32 s31, s31, 0x100
	s_addc_u32 s33, s33, 0
	s_cmp_gt_u32 s34, 13
	s_barrier
.LBB0_326:
	s_add_u32 s27, s52, 0xfffc0080
	s_addc_u32 s35, s53, -1
	s_add_i32 s36, 0, 0x10000
	v_add_u32_e32 v140, s36, v216
	ds_read_b128 v[128:131], v140
	ds_read_b128 v[132:135], v140 offset:1024
	ds_read_b128 v[136:139], v140 offset:2048
	ds_read_b128 v[140:143], v140 offset:3072
	s_cmp_eq_u32 s34, 12
	s_cselect_b32 s75, s1, s35
	s_cselect_b32 s74, s11, s27
	s_cselect_b32 s73, s25, s33
	s_cselect_b32 s72, s30, s31
	v_lshl_add_u64 v[168:169], s[52:53], 0, v[152:153]
	s_add_i32 m0, s83, 0xc000
	ds_read_b128 v[156:159], v217
	ds_read_b128 v[160:163], v217 offset:1024
	ds_read_b128 v[164:167], v217 offset:2048
	ds_read_b128 v[188:191], v217 offset:3072
	ds_read_b128 v[192:195], v217 offset:4096
	ds_read_b128 v[196:199], v217 offset:5120
	ds_read_b128 v[200:203], v217 offset:6144
	ds_read_b128 v[204:207], v217 offset:7168
	global_load_lds_dwordx4 v[168:169], off
	v_lshl_add_u64 v[168:169], s[52:53], 0, v[154:155]
	s_add_i32 m0, s83, 0xe000
	s_nop 0
	global_load_lds_dwordx4 v[168:169], off
	s_waitcnt lgkmcnt(8)
	s_barrier
	s_waitcnt lgkmcnt(0)
	s_setprio 1
	s_waitcnt lgkmcnt(0)
	v_mfma_f32_16x16x32_bf16 v[124:127], v[128:131], v[156:159], v[124:127]
	v_mfma_f32_16x16x32_bf16 v[120:123], v[136:139], v[156:159], v[120:123]
	v_mfma_f32_16x16x32_bf16 v[108:111], v[128:131], v[164:167], v[108:111]
	v_mfma_f32_16x16x32_bf16 v[104:107], v[136:139], v[164:167], v[104:107]
	v_mfma_f32_16x16x32_bf16 v[92:95], v[128:131], v[192:195], v[92:95]
	v_mfma_f32_16x16x32_bf16 v[88:91], v[136:139], v[192:195], v[88:91]
	v_mfma_f32_16x16x32_bf16 v[76:79], v[128:131], v[200:203], v[76:79]
	v_mfma_f32_16x16x32_bf16 v[72:75], v[136:139], v[200:203], v[72:75]
	v_mfma_f32_16x16x32_bf16 v[124:127], v[132:135], v[160:163], v[124:127]
	v_mfma_f32_16x16x32_bf16 v[120:123], v[140:143], v[160:163], v[120:123]
	v_mfma_f32_16x16x32_bf16 v[108:111], v[132:135], v[188:191], v[108:111]
	v_mfma_f32_16x16x32_bf16 v[104:107], v[140:143], v[188:191], v[104:107]
	v_mfma_f32_16x16x32_bf16 v[92:95], v[132:135], v[196:199], v[92:95]
	v_mfma_f32_16x16x32_bf16 v[88:91], v[140:143], v[196:199], v[88:91]
	v_mfma_f32_16x16x32_bf16 v[76:79], v[132:135], v[204:207], v[76:79]
	v_mfma_f32_16x16x32_bf16 v[72:75], v[140:143], v[204:207], v[72:75]
	s_barrier
	s_setprio 0
	s_add_i32 s27, 0, 0x14000
	s_add_i32 s35, s36, s81
	v_add_u32_e32 v144, s27, v216
	v_lshl_add_u64 v[168:169], s[72:73], 0, v[148:149]
	s_mov_b32 m0, s35
	ds_read_b128 v[220:223], v144
	ds_read_b128 v[228:231], v144 offset:1024
	ds_read_b128 v[232:235], v144 offset:2048
	ds_read_b128 v[236:239], v144 offset:3072
	global_load_lds_dwordx4 v[168:169], off
	v_lshl_add_u64 v[176:177], s[72:73], 0, v[146:147]
	s_add_i32 m0, s35, 0x2000
	s_nop 0
	global_load_lds_dwordx4 v[176:177], off
	s_barrier
	s_waitcnt lgkmcnt(0)
	s_setprio 1
	s_waitcnt lgkmcnt(0)
	v_mfma_f32_16x16x32_bf16 v[116:119], v[220:223], v[156:159], v[116:119]
	v_mfma_f32_16x16x32_bf16 v[112:115], v[232:235], v[156:159], v[112:115]
	v_mfma_f32_16x16x32_bf16 v[100:103], v[220:223], v[164:167], v[100:103]
	v_mfma_f32_16x16x32_bf16 v[96:99], v[232:235], v[164:167], v[96:99]
	v_mfma_f32_16x16x32_bf16 v[84:87], v[220:223], v[192:195], v[84:87]
	v_mfma_f32_16x16x32_bf16 v[80:83], v[232:235], v[192:195], v[80:83]
	v_mfma_f32_16x16x32_bf16 v[68:71], v[220:223], v[200:203], v[68:71]
	v_mfma_f32_16x16x32_bf16 v[64:67], v[232:235], v[200:203], v[64:67]
	v_mfma_f32_16x16x32_bf16 v[116:119], v[228:231], v[160:163], v[116:119]
	v_mfma_f32_16x16x32_bf16 v[112:115], v[236:239], v[160:163], v[112:115]
	v_mfma_f32_16x16x32_bf16 v[100:103], v[228:231], v[188:191], v[100:103]
	v_mfma_f32_16x16x32_bf16 v[96:99], v[236:239], v[188:191], v[96:99]
	v_mfma_f32_16x16x32_bf16 v[84:87], v[228:231], v[196:199], v[84:87]
	v_mfma_f32_16x16x32_bf16 v[80:83], v[236:239], v[196:199], v[80:83]
	v_mfma_f32_16x16x32_bf16 v[68:71], v[228:231], v[204:207], v[68:71]
	v_mfma_f32_16x16x32_bf16 v[64:67], v[236:239], v[204:207], v[64:67]
	s_setprio 0
	s_mov_b32 m0, s83
	v_lshl_add_u64 v[224:225], s[74:75], 0, v[148:149]
	s_barrier
	ds_read_b128 v[156:159], v217 offset:16384
	ds_read_b128 v[160:163], v217 offset:17408
	ds_read_b128 v[164:167], v217 offset:18432
	ds_read_b128 v[188:191], v217 offset:19456
	ds_read_b128 v[192:195], v217 offset:20480
	ds_read_b128 v[196:199], v217 offset:21504
	ds_read_b128 v[200:203], v217 offset:22528
	ds_read_b128 v[204:207], v217 offset:23552
	global_load_lds_dwordx4 v[224:225], off
	v_lshl_add_u64 v[240:241], s[74:75], 0, v[146:147]
	s_mov_b32 m0, s84
	s_nop 0
	global_load_lds_dwordx4 v[240:241], off
	s_barrier
	s_waitcnt lgkmcnt(0)
	s_setprio 1
	s_waitcnt lgkmcnt(0)
	v_mfma_f32_16x16x32_bf16 v[60:63], v[128:131], v[156:159], v[60:63]
	v_mfma_f32_16x16x32_bf16 v[56:59], v[136:139], v[156:159], v[56:59]
	v_mfma_f32_16x16x32_bf16 v[44:47], v[128:131], v[164:167], v[44:47]
	v_mfma_f32_16x16x32_bf16 v[40:43], v[136:139], v[164:167], v[40:43]
	v_mfma_f32_16x16x32_bf16 v[28:31], v[128:131], v[192:195], v[28:31]
	v_mfma_f32_16x16x32_bf16 v[24:27], v[136:139], v[192:195], v[24:27]
	v_mfma_f32_16x16x32_bf16 v[12:15], v[128:131], v[200:203], v[12:15]
	v_mfma_f32_16x16x32_bf16 v[8:11], v[136:139], v[200:203], v[8:11]
	v_mfma_f32_16x16x32_bf16 v[60:63], v[132:135], v[160:163], v[60:63]
	v_mfma_f32_16x16x32_bf16 v[56:59], v[140:143], v[160:163], v[56:59]
	v_mfma_f32_16x16x32_bf16 v[44:47], v[132:135], v[188:191], v[44:47]
	v_mfma_f32_16x16x32_bf16 v[40:43], v[140:143], v[188:191], v[40:43]
	v_mfma_f32_16x16x32_bf16 v[28:31], v[132:135], v[196:199], v[28:31]
	v_mfma_f32_16x16x32_bf16 v[24:27], v[140:143], v[196:199], v[24:27]
	v_mfma_f32_16x16x32_bf16 v[12:15], v[132:135], v[204:207], v[12:15]
	v_mfma_f32_16x16x32_bf16 v[8:11], v[140:143], v[204:207], v[8:11]
	s_barrier
	s_setprio 0
	s_add_u32 s36, s72, 0x40000
	s_addc_u32 s37, s73, 0
	s_add_i32 s27, s27, s81
	v_lshl_add_u64 v[128:129], s[36:37], 0, v[148:149]
	s_mov_b32 m0, s27
	s_nop 0
	global_load_lds_dwordx4 v[128:129], off
	v_lshl_add_u64 v[128:129], s[36:37], 0, v[146:147]
	s_add_i32 m0, s27, 0x2000
	s_nop 0
	global_load_lds_dwordx4 v[128:129], off
	s_waitcnt vmcnt(6)
	s_setprio 1
	s_barrier
	v_mfma_f32_16x16x32_bf16 v[52:55], v[220:223], v[156:159], v[52:55]
	v_mfma_f32_16x16x32_bf16 v[48:51], v[232:235], v[156:159], v[48:51]
	v_mfma_f32_16x16x32_bf16 v[36:39], v[220:223], v[164:167], v[36:39]
	v_mfma_f32_16x16x32_bf16 v[32:35], v[232:235], v[164:167], v[32:35]
	v_mfma_f32_16x16x32_bf16 v[20:23], v[220:223], v[192:195], v[20:23]
	v_mfma_f32_16x16x32_bf16 v[16:19], v[232:235], v[192:195], v[16:19]
	v_mfma_f32_16x16x32_bf16 v[4:7], v[220:223], v[200:203], v[4:7]
	v_mfma_f32_16x16x32_bf16 v[0:3], v[232:235], v[200:203], v[0:3]
	v_mfma_f32_16x16x32_bf16 v[52:55], v[228:231], v[160:163], v[52:55]
	v_mfma_f32_16x16x32_bf16 v[48:51], v[236:239], v[160:163], v[48:51]
	v_mfma_f32_16x16x32_bf16 v[36:39], v[228:231], v[188:191], v[36:39]
	v_mfma_f32_16x16x32_bf16 v[32:35], v[236:239], v[188:191], v[32:35]
	v_mfma_f32_16x16x32_bf16 v[20:23], v[228:231], v[196:199], v[20:23]
	v_mfma_f32_16x16x32_bf16 v[16:19], v[236:239], v[196:199], v[16:19]
	v_mfma_f32_16x16x32_bf16 v[4:7], v[228:231], v[204:207], v[4:7]
	v_mfma_f32_16x16x32_bf16 v[0:3], v[236:239], v[204:207], v[0:3]
	s_setprio 0
	s_add_i32 s27, 0, 0x18000
	v_add_u32_e32 v140, s27, v216
	s_barrier
	ds_read_b128 v[128:131], v140
	ds_read_b128 v[132:135], v140 offset:1024
	ds_read_b128 v[136:139], v140 offset:2048
	ds_read_b128 v[140:143], v140 offset:3072
	s_add_u32 s36, s74, 0x40000
	s_addc_u32 s37, s75, 0
	s_mov_b32 m0, s85
	v_lshl_add_u64 v[220:221], s[36:37], 0, v[148:149]
	ds_read_b128 v[156:159], v217 offset:32768
	ds_read_b128 v[160:163], v217 offset:33792
	ds_read_b128 v[164:167], v217 offset:34816
	ds_read_b128 v[188:191], v217 offset:35840
	ds_read_b128 v[192:195], v217 offset:36864
	ds_read_b128 v[196:199], v217 offset:37888
	ds_read_b128 v[200:203], v217 offset:38912
	ds_read_b128 v[204:207], v217 offset:39936
	global_load_lds_dwordx4 v[220:221], off
	v_lshl_add_u64 v[220:221], s[36:37], 0, v[146:147]
	s_mov_b32 m0, s86
	s_nop 0
	global_load_lds_dwordx4 v[220:221], off
	s_waitcnt lgkmcnt(8)
	s_barrier
	s_waitcnt lgkmcnt(0)
	s_setprio 1
	s_waitcnt lgkmcnt(0)
	v_mfma_f32_16x16x32_bf16 v[124:127], v[128:131], v[156:159], v[124:127]
	v_mfma_f32_16x16x32_bf16 v[120:123], v[136:139], v[156:159], v[120:123]
	v_mfma_f32_16x16x32_bf16 v[108:111], v[128:131], v[164:167], v[108:111]
	v_mfma_f32_16x16x32_bf16 v[104:107], v[136:139], v[164:167], v[104:107]
	v_mfma_f32_16x16x32_bf16 v[92:95], v[128:131], v[192:195], v[92:95]
	v_mfma_f32_16x16x32_bf16 v[88:91], v[136:139], v[192:195], v[88:91]
	v_mfma_f32_16x16x32_bf16 v[76:79], v[128:131], v[200:203], v[76:79]
	v_mfma_f32_16x16x32_bf16 v[72:75], v[136:139], v[200:203], v[72:75]
	v_mfma_f32_16x16x32_bf16 v[124:127], v[132:135], v[160:163], v[124:127]
	v_mfma_f32_16x16x32_bf16 v[120:123], v[140:143], v[160:163], v[120:123]
	v_mfma_f32_16x16x32_bf16 v[108:111], v[132:135], v[188:191], v[108:111]
	v_mfma_f32_16x16x32_bf16 v[104:107], v[140:143], v[188:191], v[104:107]
	v_mfma_f32_16x16x32_bf16 v[92:95], v[132:135], v[196:199], v[92:95]
	v_mfma_f32_16x16x32_bf16 v[88:91], v[140:143], v[196:199], v[88:91]
	v_mfma_f32_16x16x32_bf16 v[76:79], v[132:135], v[204:207], v[76:79]
	v_mfma_f32_16x16x32_bf16 v[72:75], v[140:143], v[204:207], v[72:75]
	s_barrier
	s_setprio 0
	s_add_i32 s35, 0, 0x1c000
	s_add_i32 s27, s27, s81
	v_add_u32_e32 v144, s35, v216
	v_lshl_add_u64 v[168:169], v[168:169], 0, s[18:19]
	s_mov_b32 m0, s27
	ds_read_b128 v[220:223], v144
	ds_read_b128 v[228:231], v144 offset:1024
	ds_read_b128 v[232:235], v144 offset:2048
	ds_read_b128 v[236:239], v144 offset:3072
	global_load_lds_dwordx4 v[168:169], off
	v_lshl_add_u64 v[168:169], v[176:177], 0, s[18:19]
	s_add_i32 m0, s27, 0x2000
	s_nop 0
	global_load_lds_dwordx4 v[168:169], off
	s_barrier
	s_waitcnt lgkmcnt(0)
	s_setprio 1
	s_waitcnt lgkmcnt(0)
	v_mfma_f32_16x16x32_bf16 v[116:119], v[220:223], v[156:159], v[116:119]
	v_mfma_f32_16x16x32_bf16 v[112:115], v[232:235], v[156:159], v[112:115]
	v_mfma_f32_16x16x32_bf16 v[100:103], v[220:223], v[164:167], v[100:103]
	v_mfma_f32_16x16x32_bf16 v[96:99], v[232:235], v[164:167], v[96:99]
	v_mfma_f32_16x16x32_bf16 v[84:87], v[220:223], v[192:195], v[84:87]
	v_mfma_f32_16x16x32_bf16 v[80:83], v[232:235], v[192:195], v[80:83]
	v_mfma_f32_16x16x32_bf16 v[68:71], v[220:223], v[200:203], v[68:71]
	v_mfma_f32_16x16x32_bf16 v[64:67], v[232:235], v[200:203], v[64:67]
	v_mfma_f32_16x16x32_bf16 v[116:119], v[228:231], v[160:163], v[116:119]
	v_mfma_f32_16x16x32_bf16 v[112:115], v[236:239], v[160:163], v[112:115]
	v_mfma_f32_16x16x32_bf16 v[100:103], v[228:231], v[188:191], v[100:103]
	v_mfma_f32_16x16x32_bf16 v[96:99], v[236:239], v[188:191], v[96:99]
	v_mfma_f32_16x16x32_bf16 v[84:87], v[228:231], v[196:199], v[84:87]
	v_mfma_f32_16x16x32_bf16 v[80:83], v[236:239], v[196:199], v[80:83]
	v_mfma_f32_16x16x32_bf16 v[68:71], v[228:231], v[204:207], v[68:71]
	v_mfma_f32_16x16x32_bf16 v[64:67], v[236:239], v[204:207], v[64:67]
	s_setprio 0
	s_mov_b32 m0, s87
	v_lshl_add_u64 v[168:169], v[224:225], 0, s[18:19]
	s_barrier
	ds_read_b128 v[156:159], v217 offset:49152
	ds_read_b128 v[160:163], v217 offset:50176
	ds_read_b128 v[164:167], v217 offset:51200
	ds_read_b128 v[188:191], v217 offset:52224
	ds_read_b128 v[192:195], v217 offset:53248
	ds_read_b128 v[196:199], v217 offset:54272
	ds_read_b128 v[200:203], v217 offset:55296
	ds_read_b128 v[204:207], v217 offset:56320
	global_load_lds_dwordx4 v[168:169], off
	v_lshl_add_u64 v[168:169], v[240:241], 0, s[18:19]
	s_mov_b32 m0, s79
	s_nop 0
	global_load_lds_dwordx4 v[168:169], off
	s_barrier
	s_waitcnt lgkmcnt(0)
	s_setprio 1
	s_waitcnt lgkmcnt(0)
	v_mfma_f32_16x16x32_bf16 v[60:63], v[128:131], v[156:159], v[60:63]
	v_mfma_f32_16x16x32_bf16 v[56:59], v[136:139], v[156:159], v[56:59]
	v_mfma_f32_16x16x32_bf16 v[44:47], v[128:131], v[164:167], v[44:47]
	v_mfma_f32_16x16x32_bf16 v[40:43], v[136:139], v[164:167], v[40:43]
	v_mfma_f32_16x16x32_bf16 v[28:31], v[128:131], v[192:195], v[28:31]
	v_mfma_f32_16x16x32_bf16 v[24:27], v[136:139], v[192:195], v[24:27]
	v_mfma_f32_16x16x32_bf16 v[12:15], v[128:131], v[200:203], v[12:15]
	v_mfma_f32_16x16x32_bf16 v[8:11], v[136:139], v[200:203], v[8:11]
	v_mfma_f32_16x16x32_bf16 v[60:63], v[132:135], v[160:163], v[60:63]
	v_mfma_f32_16x16x32_bf16 v[56:59], v[140:143], v[160:163], v[56:59]
	v_mfma_f32_16x16x32_bf16 v[44:47], v[132:135], v[188:191], v[44:47]
	v_mfma_f32_16x16x32_bf16 v[40:43], v[140:143], v[188:191], v[40:43]
	v_mfma_f32_16x16x32_bf16 v[28:31], v[132:135], v[196:199], v[28:31]
	v_mfma_f32_16x16x32_bf16 v[24:27], v[140:143], v[196:199], v[24:27]
	v_mfma_f32_16x16x32_bf16 v[12:15], v[132:135], v[204:207], v[12:15]
	v_mfma_f32_16x16x32_bf16 v[8:11], v[140:143], v[204:207], v[8:11]
	s_barrier
	s_setprio 0
	s_add_u32 s36, s72, 0x40080
	s_addc_u32 s37, s73, 0
	s_add_i32 s27, s35, s81
	v_lshl_add_u64 v[128:129], s[36:37], 0, v[148:149]
	s_mov_b32 m0, s27
	s_nop 0
	global_load_lds_dwordx4 v[128:129], off
	v_lshl_add_u64 v[128:129], s[36:37], 0, v[146:147]
	s_add_i32 m0, s27, 0x2000
	s_nop 0
	global_load_lds_dwordx4 v[128:129], off
	s_waitcnt vmcnt(6)
	s_setprio 1
	s_barrier
	v_mfma_f32_16x16x32_bf16 v[52:55], v[220:223], v[156:159], v[52:55]
	v_mfma_f32_16x16x32_bf16 v[48:51], v[232:235], v[156:159], v[48:51]
	v_mfma_f32_16x16x32_bf16 v[36:39], v[220:223], v[164:167], v[36:39]
	v_mfma_f32_16x16x32_bf16 v[32:35], v[232:235], v[164:167], v[32:35]
	v_mfma_f32_16x16x32_bf16 v[20:23], v[220:223], v[192:195], v[20:23]
	v_mfma_f32_16x16x32_bf16 v[16:19], v[232:235], v[192:195], v[16:19]
	v_mfma_f32_16x16x32_bf16 v[4:7], v[220:223], v[200:203], v[4:7]
	v_mfma_f32_16x16x32_bf16 v[0:3], v[232:235], v[200:203], v[0:3]
	v_mfma_f32_16x16x32_bf16 v[52:55], v[228:231], v[160:163], v[52:55]
	v_mfma_f32_16x16x32_bf16 v[48:51], v[236:239], v[160:163], v[48:51]
	v_mfma_f32_16x16x32_bf16 v[36:39], v[228:231], v[188:191], v[36:39]
	v_mfma_f32_16x16x32_bf16 v[32:35], v[236:239], v[188:191], v[32:35]
	v_mfma_f32_16x16x32_bf16 v[20:23], v[228:231], v[196:199], v[20:23]
	v_mfma_f32_16x16x32_bf16 v[16:19], v[236:239], v[196:199], v[16:19]
	v_mfma_f32_16x16x32_bf16 v[4:7], v[228:231], v[204:207], v[4:7]
	v_mfma_f32_16x16x32_bf16 v[0:3], v[236:239], v[204:207], v[0:3]
	s_setprio 0
	s_add_i32 s34, s34, 2
	s_add_u32 s52, s52, 0x100
	s_addc_u32 s53, s53, 0
	s_add_u32 s31, s31, 0x100
	s_addc_u32 s33, s33, 0
	s_cmp_gt_u32 s34, 13
	s_barrier
	s_cbranch_scc0 .LBB0_326
	v_lshl_add_u32 v128, s0, 8, v151
	v_readlane_b32 s0, v252, 36
	v_ashrrev_i32_e32 v129, 31, v128
	v_readlane_b32 s1, v252, 37
	v_or_b32_e32 v132, 16, v128
	v_or_b32_e32 v136, 32, v128
	v_lshl_add_u64 v[130:131], v[128:129], 3, s[0:1]
	v_ashrrev_i32_e32 v133, 31, v132
	v_ashrrev_i32_e32 v137, 31, v136
	v_or_b32_e32 v140, 48, v128
	v_lshl_add_u64 v[134:135], v[132:133], 3, s[0:1]
	v_lshl_add_u64 v[138:139], v[136:137], 3, s[0:1]
	v_ashrrev_i32_e32 v141, 31, v140
	global_load_dwordx2 v[202:203], v[130:131], off
	global_load_dwordx2 v[200:201], v[134:135], off
	global_load_dwordx2 v[192:193], v[138:139], off
	global_load_dwordx2 v[166:167], v[130:131], off offset:1024
	v_add_u32_e32 v164, 0x90, v128
	v_add_u32_e32 v158, 0xa0, v128
	v_add_u32_e32 v156, 0xb0, v128
	v_lshl_add_u64 v[142:143], v[140:141], 3, s[0:1]
	v_ashrrev_i32_e32 v165, 31, v164
	v_ashrrev_i32_e32 v159, 31, v158
	v_ashrrev_i32_e32 v157, 31, v156
	v_lshl_add_u64 v[130:131], v[164:165], 3, s[0:1]
	v_lshl_add_u64 v[134:135], v[158:159], 3, s[0:1]
	v_lshl_add_u64 v[138:139], v[156:157], 3, s[0:1]
	global_load_dwordx2 v[196:197], v[142:143], off
	global_load_dwordx2 v[188:189], v[130:131], off
	global_load_dwordx2 v[162:163], v[134:135], off
	global_load_dwordx2 v[160:161], v[138:139], off
	v_add_u32_e32 v168, 0x80, v128
	s_mov_b64 s[0:1], -1
	s_cmp_gt_u32 s10, 1
	v_lshlrev_b32_e32 v144, 1, v150
	v_ashrrev_i32_e32 v169, 31, v168
	v_lshlrev_b64 v[204:205], 10, v[128:129]
	v_lshlrev_b64 v[198:199], 10, v[132:133]
	v_lshlrev_b64 v[194:195], 10, v[136:137]
	v_lshlrev_b64 v[190:191], 10, v[140:141]
	s_waitcnt vmcnt(0)
	v_ffbh_u32_e32 v222, v203
	v_ffbh_u32_e32 v221, v201
	v_ffbh_u32_e32 v220, v193
	v_ffbh_u32_e32 v219, v197
	s_cbranch_scc0 .LBB0_329
	s_cmp_lt_u32 s10, 4
	s_cselect_b64 vcc, -1, 0
	v_readlane_b32 s56, v254, 23
	s_and_b64 s[0:1], vcc, exec
	v_readlane_b32 s70, v254, 37
	v_readlane_b32 s36, v252, 15
	v_readlane_b32 s71, v254, 38
	v_readlane_b32 s37, v252, 16
	s_cselect_b32 s0, s70, s36
	s_mov_b32 s11, 0x4400000
	v_readlane_b32 s30, v254, 62
	s_cselect_b32 s1, s71, s37
	s_cselect_b32 s11, s11, 0x4800000
	v_readlane_b32 s31, v254, 63
	s_add_u32 s0, s0, s30
	s_addc_u32 s1, s1, s31
	global_load_dwordx4 v[136:139], v218, s[0:1] offset:16
	global_load_dwordx4 v[140:143], v218, s[0:1]
	global_load_dwordx4 v[128:131], v218, s[0:1] offset:144
	global_load_dwordx4 v[132:135], v218, s[0:1] offset:128
	v_and_b32_e32 v177, 64, v214
	v_xor_b32_e32 v176, 16, v214
	v_add_u32_e32 v177, 64, v177
	v_cndmask_b32_e32 v223, 1.0, v215, vcc
	v_cmp_lt_i32_e32 vcc, v176, v177
	v_readlane_b32 s9, v254, 52
	s_add_u32 s11, s9, s11
	v_cndmask_b32_e32 v176, v214, v176, vcc
	v_lshlrev_b32_e32 v225, 2, v176
	v_xor_b32_e32 v176, 32, v214
	v_cmp_lt_i32_e32 vcc, v176, v177
	v_readlane_b32 s9, v254, 61
	s_addc_u32 s25, s9, 0
	v_cndmask_b32_e32 v176, v214, v176, vcc
	v_lshlrev_b32_e32 v224, 2, v176
	v_min_u32_e32 v176, 32, v222
	v_lshlrev_b64 v[228:229], v176, v[202:203]
	v_min_u32_e32 v177, 1, v228
	v_or_b32_e32 v177, v229, v177
	v_cvt_f32_u32_e32 v177, v177
	v_sub_u32_e32 v176, 32, v176
	s_lshl_b32 s0, s10, 9
	s_and_b32 s0, s0, 0x200
	v_ldexp_f32 v176, v177, v176
	v_mul_f32_e32 v176, 0x35800000, v176
	v_fmamk_f32 v176, v176, 0x3a800000, v210
	s_add_u32 s0, s11, s0
	v_rsq_f32_e32 v176, v176
	s_addc_u32 s1, s25, 0
	v_lshl_add_u64 v[206:207], s[0:1], 0, v[144:145]
	v_readlane_b32 s48, v252, 27
	v_mov_b32_e32 v228, v176
	v_pk_mul_f32 v[230:231], v[124:125], v[228:229] op_sel_hi:[1,0]
	v_pk_mul_f32 v[232:233], v[126:127], v[228:229] op_sel_hi:[1,0]
	v_pk_mul_f32 v[236:237], v[230:231], v[230:231]
	v_pk_mul_f32 v[234:235], v[232:233], v[232:233]
	v_pk_mul_f32 v[250:251], v[114:115], v[228:229] op_sel_hi:[1,0]
	v_pk_mov_b32 v[238:239], v[236:237], v[234:235] op_sel:[1,0]
	v_mov_b32_e32 v237, v235
	v_pk_add_f32 v[234:235], v[238:239], v[236:237]
	v_pk_mul_f32 v[236:237], v[120:121], v[228:229] op_sel_hi:[1,0]
	v_pk_mul_f32 v[238:239], v[122:123], v[228:229] op_sel_hi:[1,0]
	v_pk_mul_f32 v[242:243], v[236:237], v[236:237]
	v_pk_mul_f32 v[240:241], v[238:239], v[238:239]
	v_pk_add_f32 v[234:235], v[234:235], v[234:235] op_sel_hi:[0,1]
	v_pk_mov_b32 v[244:245], v[242:243], v[240:241] op_sel:[1,0]
	v_mov_b32_e32 v243, v241
	v_pk_add_f32 v[240:241], v[244:245], v[242:243]
	v_pk_mul_f32 v[244:245], v[116:117], v[228:229] op_sel_hi:[1,0]
	v_pk_mul_f32 v[242:243], v[118:119], v[228:229] op_sel_hi:[1,0]
	v_mul_f32_e32 v234, v244, v244
	v_pk_fma_f32 v[246:247], v[244:245], v[244:245], v[234:235] op_sel_hi:[1,1,0]
	v_mul_f32_e32 v234, v242, v242
	v_pk_add_f32 v[240:241], v[240:241], v[240:241] op_sel_hi:[0,1]
	v_pk_fma_f32 v[248:249], v[242:243], v[242:243], v[234:235] op_sel_hi:[1,1,0]
	v_pk_mul_f32 v[176:177], v[112:113], v[228:229] op_sel_hi:[1,0]
	v_mul_f32_e32 v234, v250, v250
	v_mul_f32_e32 v246, v176, v176
	v_mul_f32_e32 v248, v177, v177
	v_mul_f32_e32 v240, v251, v251
	v_pk_add_f32 v[228:229], v[246:247], v[248:249]
	v_pk_add_f32 v[234:235], v[234:235], v[240:241]
	v_lshl_add_u64 v[240:241], v[206:207], 0, v[204:205]
	v_pk_add_f32 v[228:229], v[228:229], v[234:235]
	v_readlane_b32 s57, v254, 24
	v_add_f32_e32 v228, v228, v229
	ds_bpermute_b32 v229, v225, v228
	v_readlane_b32 s58, v254, 25
	v_readlane_b32 s59, v254, 26
	v_readlane_b32 s60, v254, 27
	v_readlane_b32 s61, v254, 28
	s_waitcnt lgkmcnt(0)
	v_add_f32_e32 v228, v228, v229
	ds_bpermute_b32 v229, v224, v228
	v_readlane_b32 s62, v254, 29
	v_readlane_b32 s63, v254, 30
	v_readlane_b32 s64, v254, 31
	v_readlane_b32 s65, v254, 32
	s_waitcnt lgkmcnt(0)
	v_add_f32_e32 v228, v228, v229
	v_fmamk_f32 v228, v228, 0x3c800000, v210
	v_readlane_b32 s66, v254, 33
	v_rsq_f32_e32 v228, v228
	v_readlane_b32 s67, v254, 34
	v_readlane_b32 s68, v254, 35
	v_readlane_b32 s69, v254, 36
	v_mul_f32_e32 v234, v223, v228
	v_pk_mul_f32 v[228:229], v[230:231], v[234:235] op_sel_hi:[1,0]
	v_pk_mul_f32 v[230:231], v[232:233], v[234:235] op_sel_hi:[1,0]
	s_waitcnt vmcnt(2)
	v_pk_mul_f32 v[228:229], v[140:141], v[228:229]
	v_pk_mul_f32 v[230:231], v[142:143], v[230:231]
	v_pk_mul_f32 v[232:233], v[236:237], v[234:235] op_sel_hi:[1,0]
	v_pk_mul_f32 v[236:237], v[238:239], v[234:235] op_sel_hi:[1,0]
	v_cvt_pk_bf16_f32 v228, v228, v229
	v_cvt_pk_bf16_f32 v229, v230, v231
	v_pk_mul_f32 v[232:233], v[136:137], v[232:233]
	v_pk_mul_f32 v[236:237], v[138:139], v[236:237]
	v_cvt_pk_bf16_f32 v230, v232, v233
	v_pk_mul_f32 v[176:177], v[176:177], v[234:235] op_sel_hi:[1,0]
	v_cvt_pk_bf16_f32 v231, v236, v237
	global_store_dwordx4 v[240:241], v[228:231], off
	v_pk_mul_f32 v[232:233], v[250:251], v[234:235] op_sel_hi:[1,0]
	s_waitcnt vmcnt(2)
	v_pk_mul_f32 v[176:177], v[128:129], v[176:177]
	v_pk_mul_f32 v[228:229], v[244:245], v[234:235] op_sel_hi:[1,0]
	v_pk_mul_f32 v[230:231], v[242:243], v[234:235] op_sel_hi:[1,0]
	s_waitcnt vmcnt(1)
	v_pk_mul_f32 v[228:229], v[132:133], v[228:229]
	v_pk_mul_f32 v[230:231], v[134:135], v[230:231]
	v_cvt_pk_bf16_f32 v228, v228, v229
	v_pk_mul_f32 v[232:233], v[130:131], v[232:233]
	v_cvt_pk_bf16_f32 v229, v230, v231
	v_cvt_pk_bf16_f32 v230, v176, v177
	s_nop 1
	v_readlane_b32 s38, v252, 17
	v_cvt_pk_bf16_f32 v231, v232, v233
	s_nop 1
	global_store_dwordx4 v[240:241], v[228:231], off offset:64
	v_readlane_b32 s39, v252, 18
	v_readlane_b32 s40, v252, 19
	v_min_u32_e32 v228, 32, v221
	v_lshlrev_b64 v[176:177], v228, v[200:201]
	v_min_u32_e32 v176, 1, v176
	v_or_b32_e32 v176, v177, v176
	v_cvt_f32_u32_e32 v176, v176
	v_sub_u32_e32 v177, 32, v228
	v_readlane_b32 s41, v252, 20
	v_readlane_b32 s42, v252, 21
	v_ldexp_f32 v176, v176, v177
	v_mul_f32_e32 v176, 0x35800000, v176
	v_fmamk_f32 v176, v176, 0x3a800000, v210
	v_readlane_b32 s43, v252, 22
	v_rsq_f32_e32 v176, v176
	v_readlane_b32 s44, v252, 23
	v_readlane_b32 s45, v252, 24
	v_readlane_b32 s46, v252, 25
	v_pk_mul_f32 v[228:229], v[108:109], v[176:177] op_sel_hi:[1,0]
	v_pk_mul_f32 v[230:231], v[110:111], v[176:177] op_sel_hi:[1,0]
	v_pk_mul_f32 v[234:235], v[228:229], v[228:229]
	v_pk_mul_f32 v[232:233], v[230:231], v[230:231]
	v_pk_mul_f32 v[248:249], v[98:99], v[176:177] op_sel_hi:[1,0]
	v_pk_mov_b32 v[236:237], v[234:235], v[232:233] op_sel:[1,0]
	v_mov_b32_e32 v235, v233
	v_pk_add_f32 v[232:233], v[236:237], v[234:235]
	v_pk_mul_f32 v[234:235], v[104:105], v[176:177] op_sel_hi:[1,0]
	v_pk_mul_f32 v[236:237], v[106:107], v[176:177] op_sel_hi:[1,0]
	v_pk_mul_f32 v[240:241], v[234:235], v[234:235]
	v_pk_mul_f32 v[238:239], v[236:237], v[236:237]
	v_pk_add_f32 v[232:233], v[232:233], v[232:233] op_sel_hi:[0,1]
	v_pk_mov_b32 v[242:243], v[240:241], v[238:239] op_sel:[1,0]
	v_mov_b32_e32 v241, v239
	v_pk_add_f32 v[238:239], v[242:243], v[240:241]
	v_pk_mul_f32 v[242:243], v[100:101], v[176:177] op_sel_hi:[1,0]
	v_pk_mul_f32 v[240:241], v[102:103], v[176:177] op_sel_hi:[1,0]
	v_mul_f32_e32 v232, v242, v242
	v_pk_fma_f32 v[244:245], v[242:243], v[242:243], v[232:233] op_sel_hi:[1,1,0]
	v_mul_f32_e32 v232, v240, v240
	v_pk_add_f32 v[238:239], v[238:239], v[238:239] op_sel_hi:[0,1]
	v_pk_fma_f32 v[246:247], v[240:241], v[240:241], v[232:233] op_sel_hi:[1,1,0]
	v_pk_mul_f32 v[176:177], v[96:97], v[176:177] op_sel_hi:[1,0]
	v_mul_f32_e32 v232, v248, v248
	v_mul_f32_e32 v244, v176, v176
	v_mul_f32_e32 v246, v177, v177
	v_mul_f32_e32 v238, v249, v249
	v_pk_add_f32 v[244:245], v[244:245], v[246:247]
	v_pk_add_f32 v[232:233], v[232:233], v[238:239]
	v_lshl_add_u64 v[238:239], v[206:207], 0, v[198:199]
	v_pk_add_f32 v[232:233], v[244:245], v[232:233]
	v_readlane_b32 s47, v252, 26
	v_add_f32_e32 v232, v232, v233
	ds_bpermute_b32 v233, v225, v232
	v_readlane_b32 s49, v252, 28
	v_readlane_b32 s50, v252, 29
	v_readlane_b32 s51, v252, 30
	v_readlane_b32 s48, v252, 40
	s_waitcnt lgkmcnt(0)
	v_add_f32_e32 v232, v232, v233
	ds_bpermute_b32 v233, v224, v232
	s_mov_b64 s[0:1], 0
	s_waitcnt lgkmcnt(0)
	v_add_f32_e32 v232, v232, v233
	v_fmamk_f32 v232, v232, 0x3c800000, v210
	s_nop 0
	v_rsq_f32_e32 v232, v232
	s_nop 0
	v_mul_f32_e32 v232, v223, v232
	v_pk_mul_f32 v[228:229], v[228:229], v[232:233] op_sel_hi:[1,0]
	v_pk_mul_f32 v[230:231], v[230:231], v[232:233] op_sel_hi:[1,0]
	v_pk_mul_f32 v[228:229], v[140:141], v[228:229]
	v_pk_mul_f32 v[230:231], v[142:143], v[230:231]
	v_pk_mul_f32 v[234:235], v[234:235], v[232:233] op_sel_hi:[1,0]
	v_pk_mul_f32 v[236:237], v[236:237], v[232:233] op_sel_hi:[1,0]
	v_cvt_pk_bf16_f32 v228, v228, v229
	v_cvt_pk_bf16_f32 v229, v230, v231
	v_pk_mul_f32 v[234:235], v[136:137], v[234:235]
	v_pk_mul_f32 v[236:237], v[138:139], v[236:237]
	v_cvt_pk_bf16_f32 v230, v234, v235
	v_pk_mul_f32 v[176:177], v[176:177], v[232:233] op_sel_hi:[1,0]
	v_cvt_pk_bf16_f32 v231, v236, v237
	global_store_dwordx4 v[238:239], v[228:231], off
	v_pk_mul_f32 v[176:177], v[128:129], v[176:177]
	s_nop 0
	v_pk_mul_f32 v[228:229], v[242:243], v[232:233] op_sel_hi:[1,0]
	v_pk_mul_f32 v[230:231], v[240:241], v[232:233] op_sel_hi:[1,0]
	v_pk_mul_f32 v[228:229], v[132:133], v[228:229]
	v_pk_mul_f32 v[230:231], v[134:135], v[230:231]
	v_pk_mul_f32 v[232:233], v[248:249], v[232:233] op_sel_hi:[1,0]
	v_cvt_pk_bf16_f32 v228, v228, v229
	v_cvt_pk_bf16_f32 v229, v230, v231
	v_cvt_pk_bf16_f32 v230, v176, v177
	s_nop 0
	v_pk_mul_f32 v[232:233], v[130:131], v[232:233]
	s_nop 0
	v_cvt_pk_bf16_f32 v231, v232, v233
	global_store_dwordx4 v[238:239], v[228:231], off offset:64
	s_nop 1
	v_min_u32_e32 v228, 32, v220
	v_lshlrev_b64 v[176:177], v228, v[192:193]
	v_min_u32_e32 v176, 1, v176
	v_or_b32_e32 v176, v177, v176
	v_cvt_f32_u32_e32 v176, v176
	v_sub_u32_e32 v177, 32, v228
	v_ldexp_f32 v176, v176, v177
	v_mul_f32_e32 v176, 0x35800000, v176
	v_fmamk_f32 v176, v176, 0x3a800000, v210
	s_nop 0
	v_rsq_f32_e32 v176, v176
	s_nop 0
	v_pk_mul_f32 v[228:229], v[92:93], v[176:177] op_sel_hi:[1,0]
	v_pk_mul_f32 v[230:231], v[94:95], v[176:177] op_sel_hi:[1,0]
	v_pk_mul_f32 v[234:235], v[228:229], v[228:229]
	v_pk_mul_f32 v[232:233], v[230:231], v[230:231]
	v_pk_mul_f32 v[248:249], v[82:83], v[176:177] op_sel_hi:[1,0]
	v_pk_mov_b32 v[236:237], v[234:235], v[232:233] op_sel:[1,0]
	v_mov_b32_e32 v235, v233
	v_pk_add_f32 v[232:233], v[236:237], v[234:235]
	v_pk_mul_f32 v[234:235], v[88:89], v[176:177] op_sel_hi:[1,0]
	v_pk_mul_f32 v[236:237], v[90:91], v[176:177] op_sel_hi:[1,0]
	v_pk_mul_f32 v[240:241], v[234:235], v[234:235]
	v_pk_mul_f32 v[238:239], v[236:237], v[236:237]
	v_pk_add_f32 v[232:233], v[232:233], v[232:233] op_sel_hi:[0,1]
	v_pk_mov_b32 v[242:243], v[240:241], v[238:239] op_sel:[1,0]
	v_mov_b32_e32 v241, v239
	v_pk_add_f32 v[238:239], v[242:243], v[240:241]
	v_pk_mul_f32 v[242:243], v[84:85], v[176:177] op_sel_hi:[1,0]
	v_pk_mul_f32 v[240:241], v[86:87], v[176:177] op_sel_hi:[1,0]
	v_mul_f32_e32 v232, v242, v242
	v_pk_fma_f32 v[244:245], v[242:243], v[242:243], v[232:233] op_sel_hi:[1,1,0]
	v_mul_f32_e32 v232, v240, v240
	v_pk_add_f32 v[238:239], v[238:239], v[238:239] op_sel_hi:[0,1]
	v_pk_fma_f32 v[246:247], v[240:241], v[240:241], v[232:233] op_sel_hi:[1,1,0]
	v_pk_mul_f32 v[176:177], v[80:81], v[176:177] op_sel_hi:[1,0]
	v_mul_f32_e32 v232, v248, v248
	v_mul_f32_e32 v244, v176, v176
	v_mul_f32_e32 v246, v177, v177
	v_mul_f32_e32 v238, v249, v249
	v_pk_add_f32 v[244:245], v[244:245], v[246:247]
	v_pk_add_f32 v[232:233], v[232:233], v[238:239]
	v_lshl_add_u64 v[238:239], v[206:207], 0, v[194:195]
	v_pk_add_f32 v[232:233], v[244:245], v[232:233]
	s_nop 0
	v_add_f32_e32 v232, v232, v233
	ds_bpermute_b32 v233, v225, v232
	s_waitcnt lgkmcnt(0)
	v_add_f32_e32 v232, v232, v233
	ds_bpermute_b32 v233, v224, v232
	s_waitcnt lgkmcnt(0)
	v_add_f32_e32 v232, v232, v233
	v_fmamk_f32 v232, v232, 0x3c800000, v210
	s_nop 0
	v_rsq_f32_e32 v232, v232
	s_nop 0
	v_mul_f32_e32 v232, v223, v232
	v_pk_mul_f32 v[228:229], v[228:229], v[232:233] op_sel_hi:[1,0]
	v_pk_mul_f32 v[230:231], v[230:231], v[232:233] op_sel_hi:[1,0]
	v_pk_mul_f32 v[228:229], v[140:141], v[228:229]
	v_pk_mul_f32 v[230:231], v[142:143], v[230:231]
	v_pk_mul_f32 v[234:235], v[234:235], v[232:233] op_sel_hi:[1,0]
	v_pk_mul_f32 v[236:237], v[236:237], v[232:233] op_sel_hi:[1,0]
	v_cvt_pk_bf16_f32 v228, v228, v229
	v_cvt_pk_bf16_f32 v229, v230, v231
	v_pk_mul_f32 v[234:235], v[136:137], v[234:235]
	v_pk_mul_f32 v[236:237], v[138:139], v[236:237]
	v_cvt_pk_bf16_f32 v230, v234, v235
	v_pk_mul_f32 v[176:177], v[176:177], v[232:233] op_sel_hi:[1,0]
	v_cvt_pk_bf16_f32 v231, v236, v237
	global_store_dwordx4 v[238:239], v[228:231], off
	v_pk_mul_f32 v[176:177], v[128:129], v[176:177]
	s_nop 0
	v_pk_mul_f32 v[228:229], v[242:243], v[232:233] op_sel_hi:[1,0]
	v_pk_mul_f32 v[230:231], v[240:241], v[232:233] op_sel_hi:[1,0]
	v_pk_mul_f32 v[228:229], v[132:133], v[228:229]
	v_pk_mul_f32 v[230:231], v[134:135], v[230:231]
	v_pk_mul_f32 v[232:233], v[248:249], v[232:233] op_sel_hi:[1,0]
	v_cvt_pk_bf16_f32 v228, v228, v229
	v_cvt_pk_bf16_f32 v229, v230, v231
	v_cvt_pk_bf16_f32 v230, v176, v177
	s_nop 0
	v_pk_mul_f32 v[232:233], v[130:131], v[232:233]
	s_nop 0
	v_cvt_pk_bf16_f32 v231, v232, v233
	global_store_dwordx4 v[238:239], v[228:231], off offset:64
	s_nop 1
	v_min_u32_e32 v228, 32, v219
	v_lshlrev_b64 v[176:177], v228, v[196:197]
	v_min_u32_e32 v176, 1, v176
	v_or_b32_e32 v176, v177, v176
	v_cvt_f32_u32_e32 v176, v176
	v_sub_u32_e32 v177, 32, v228
	v_ldexp_f32 v176, v176, v177
	v_mul_f32_e32 v176, 0x35800000, v176
	v_fmamk_f32 v176, v176, 0x3a800000, v210
	s_nop 0
	v_rsq_f32_e32 v176, v176
	s_nop 0
	v_pk_mul_f32 v[228:229], v[76:77], v[176:177] op_sel_hi:[1,0]
	v_pk_mul_f32 v[230:231], v[78:79], v[176:177] op_sel_hi:[1,0]
	v_pk_mul_f32 v[234:235], v[228:229], v[228:229]
	v_pk_mul_f32 v[232:233], v[230:231], v[230:231]
	v_pk_mul_f32 v[248:249], v[66:67], v[176:177] op_sel_hi:[1,0]
	v_pk_mov_b32 v[236:237], v[234:235], v[232:233] op_sel:[1,0]
	v_mov_b32_e32 v235, v233
	v_pk_add_f32 v[232:233], v[236:237], v[234:235]
	v_pk_mul_f32 v[234:235], v[72:73], v[176:177] op_sel_hi:[1,0]
	v_pk_mul_f32 v[236:237], v[74:75], v[176:177] op_sel_hi:[1,0]
	v_pk_mul_f32 v[240:241], v[234:235], v[234:235]
	v_pk_mul_f32 v[238:239], v[236:237], v[236:237]
	v_pk_add_f32 v[232:233], v[232:233], v[232:233] op_sel_hi:[0,1]
	v_pk_mov_b32 v[242:243], v[240:241], v[238:239] op_sel:[1,0]
	v_mov_b32_e32 v241, v239
	v_pk_add_f32 v[238:239], v[242:243], v[240:241]
	v_pk_mul_f32 v[242:243], v[68:69], v[176:177] op_sel_hi:[1,0]
	v_pk_mul_f32 v[240:241], v[70:71], v[176:177] op_sel_hi:[1,0]
	v_mul_f32_e32 v232, v242, v242
	v_pk_fma_f32 v[244:245], v[242:243], v[242:243], v[232:233] op_sel_hi:[1,1,0]
	v_mul_f32_e32 v232, v240, v240
	v_pk_add_f32 v[238:239], v[238:239], v[238:239] op_sel_hi:[0,1]
	v_pk_fma_f32 v[246:247], v[240:241], v[240:241], v[232:233] op_sel_hi:[1,1,0]
	v_pk_mul_f32 v[176:177], v[64:65], v[176:177] op_sel_hi:[1,0]
	v_mul_f32_e32 v232, v248, v248
	v_mul_f32_e32 v244, v176, v176
	v_mul_f32_e32 v246, v177, v177
	v_mul_f32_e32 v238, v249, v249
	v_pk_add_f32 v[244:245], v[244:245], v[246:247]
	v_pk_add_f32 v[232:233], v[232:233], v[238:239]
	v_lshl_add_u64 v[238:239], v[206:207], 0, v[190:191]
	v_pk_add_f32 v[232:233], v[244:245], v[232:233]
	s_nop 0
	v_add_f32_e32 v232, v232, v233
	ds_bpermute_b32 v233, v225, v232
	s_waitcnt lgkmcnt(0)
	v_add_f32_e32 v232, v232, v233
	ds_bpermute_b32 v233, v224, v232
	s_waitcnt lgkmcnt(0)
	v_add_f32_e32 v232, v232, v233
	v_fmamk_f32 v232, v232, 0x3c800000, v210
	s_nop 0
	v_rsq_f32_e32 v232, v232
	s_nop 0
	v_mul_f32_e32 v232, v223, v232
	v_pk_mul_f32 v[228:229], v[228:229], v[232:233] op_sel_hi:[1,0]
	v_pk_mul_f32 v[230:231], v[230:231], v[232:233] op_sel_hi:[1,0]
	v_pk_mul_f32 v[228:229], v[140:141], v[228:229]
	v_pk_mul_f32 v[230:231], v[142:143], v[230:231]
	v_pk_mul_f32 v[234:235], v[234:235], v[232:233] op_sel_hi:[1,0]
	v_pk_mul_f32 v[236:237], v[236:237], v[232:233] op_sel_hi:[1,0]
	v_pk_mul_f32 v[234:235], v[136:137], v[234:235]
	v_pk_mul_f32 v[236:237], v[138:139], v[236:237]
	v_cvt_pk_bf16_f32 v228, v228, v229
	v_cvt_pk_bf16_f32 v229, v230, v231
	v_cvt_pk_bf16_f32 v230, v234, v235
	v_pk_mul_f32 v[176:177], v[176:177], v[232:233] op_sel_hi:[1,0]
	v_cvt_pk_bf16_f32 v231, v236, v237
	global_store_dwordx4 v[238:239], v[228:231], off
	v_pk_mul_f32 v[176:177], v[128:129], v[176:177]
	s_nop 0
	v_pk_mul_f32 v[228:229], v[242:243], v[232:233] op_sel_hi:[1,0]
	v_pk_mul_f32 v[230:231], v[240:241], v[232:233] op_sel_hi:[1,0]
	v_pk_mul_f32 v[228:229], v[132:133], v[228:229]
	v_pk_mul_f32 v[230:231], v[134:135], v[230:231]
	v_pk_mul_f32 v[232:233], v[248:249], v[232:233] op_sel_hi:[1,0]
	v_cvt_pk_bf16_f32 v228, v228, v229
	v_cvt_pk_bf16_f32 v229, v230, v231
	v_cvt_pk_bf16_f32 v230, v176, v177
	v_ffbh_u32_e32 v176, v167
	v_pk_mul_f32 v[232:233], v[130:131], v[232:233]
	s_nop 0
	v_cvt_pk_bf16_f32 v231, v232, v233
	global_store_dwordx4 v[238:239], v[228:231], off offset:64
	s_nop 1
	v_min_u32_e32 v228, 32, v176
	v_lshlrev_b64 v[176:177], v228, v[166:167]
	v_min_u32_e32 v176, 1, v176
	v_or_b32_e32 v176, v177, v176
	v_cvt_f32_u32_e32 v176, v176
	v_sub_u32_e32 v177, 32, v228
	v_ldexp_f32 v176, v176, v177
	v_mul_f32_e32 v176, 0x35800000, v176
	v_fmamk_f32 v176, v176, 0x3a800000, v210
	s_nop 0
	v_rsq_f32_e32 v176, v176
	s_nop 0
	v_pk_mul_f32 v[228:229], v[60:61], v[176:177] op_sel_hi:[1,0]
	v_pk_mul_f32 v[230:231], v[62:63], v[176:177] op_sel_hi:[1,0]
	v_pk_mul_f32 v[234:235], v[228:229], v[228:229]
	v_pk_mul_f32 v[232:233], v[230:231], v[230:231]
	v_pk_mul_f32 v[248:249], v[50:51], v[176:177] op_sel_hi:[1,0]
	v_pk_mov_b32 v[236:237], v[234:235], v[232:233] op_sel:[1,0]
	v_mov_b32_e32 v235, v233
	v_pk_add_f32 v[232:233], v[236:237], v[234:235]
	v_pk_mul_f32 v[234:235], v[56:57], v[176:177] op_sel_hi:[1,0]
	v_pk_mul_f32 v[236:237], v[58:59], v[176:177] op_sel_hi:[1,0]
	v_pk_mul_f32 v[240:241], v[234:235], v[234:235]
	v_pk_mul_f32 v[238:239], v[236:237], v[236:237]
	v_pk_add_f32 v[232:233], v[232:233], v[232:233] op_sel_hi:[0,1]
	v_pk_mov_b32 v[242:243], v[240:241], v[238:239] op_sel:[1,0]
	v_mov_b32_e32 v241, v239
	v_pk_add_f32 v[238:239], v[242:243], v[240:241]
	v_pk_mul_f32 v[242:243], v[52:53], v[176:177] op_sel_hi:[1,0]
	v_pk_mul_f32 v[240:241], v[54:55], v[176:177] op_sel_hi:[1,0]
	v_mul_f32_e32 v232, v242, v242
	v_pk_fma_f32 v[244:245], v[242:243], v[242:243], v[232:233] op_sel_hi:[1,1,0]
	v_mul_f32_e32 v232, v240, v240
	v_pk_add_f32 v[238:239], v[238:239], v[238:239] op_sel_hi:[0,1]
	v_pk_fma_f32 v[246:247], v[240:241], v[240:241], v[232:233] op_sel_hi:[1,1,0]
	v_pk_mul_f32 v[176:177], v[48:49], v[176:177] op_sel_hi:[1,0]
	v_mul_f32_e32 v232, v248, v248
	v_mul_f32_e32 v244, v176, v176
	v_mul_f32_e32 v246, v177, v177
	v_mul_f32_e32 v238, v249, v249
	v_pk_add_f32 v[244:245], v[244:245], v[246:247]
	v_pk_add_f32 v[232:233], v[232:233], v[238:239]
	v_lshlrev_b64 v[238:239], 10, v[168:169]
	v_pk_add_f32 v[232:233], v[244:245], v[232:233]
	v_lshl_add_u64 v[238:239], v[206:207], 0, v[238:239]
	v_add_f32_e32 v232, v232, v233
	ds_bpermute_b32 v233, v225, v232
	s_waitcnt lgkmcnt(0)
	v_add_f32_e32 v232, v232, v233
	ds_bpermute_b32 v233, v224, v232
	s_waitcnt lgkmcnt(0)
	v_add_f32_e32 v232, v232, v233
	v_fmamk_f32 v232, v232, 0x3c800000, v210
	s_nop 0
	v_rsq_f32_e32 v232, v232
	s_nop 0
	v_mul_f32_e32 v232, v223, v232
	v_pk_mul_f32 v[228:229], v[228:229], v[232:233] op_sel_hi:[1,0]
	v_pk_mul_f32 v[230:231], v[230:231], v[232:233] op_sel_hi:[1,0]
	v_pk_mul_f32 v[228:229], v[140:141], v[228:229]
	v_pk_mul_f32 v[230:231], v[142:143], v[230:231]
	v_pk_mul_f32 v[234:235], v[234:235], v[232:233] op_sel_hi:[1,0]
	v_pk_mul_f32 v[236:237], v[236:237], v[232:233] op_sel_hi:[1,0]
	v_pk_mul_f32 v[234:235], v[136:137], v[234:235]
	v_pk_mul_f32 v[236:237], v[138:139], v[236:237]
	v_cvt_pk_bf16_f32 v228, v228, v229
	v_cvt_pk_bf16_f32 v229, v230, v231
	v_cvt_pk_bf16_f32 v230, v234, v235
	v_pk_mul_f32 v[176:177], v[176:177], v[232:233] op_sel_hi:[1,0]
	v_cvt_pk_bf16_f32 v231, v236, v237
	global_store_dwordx4 v[238:239], v[228:231], off
	v_pk_mul_f32 v[176:177], v[128:129], v[176:177]
	s_nop 0
	v_pk_mul_f32 v[228:229], v[242:243], v[232:233] op_sel_hi:[1,0]
	v_pk_mul_f32 v[230:231], v[240:241], v[232:233] op_sel_hi:[1,0]
	v_pk_mul_f32 v[228:229], v[132:133], v[228:229]
	v_pk_mul_f32 v[230:231], v[134:135], v[230:231]
	v_pk_mul_f32 v[232:233], v[248:249], v[232:233] op_sel_hi:[1,0]
	v_cvt_pk_bf16_f32 v228, v228, v229
	v_cvt_pk_bf16_f32 v229, v230, v231
	v_cvt_pk_bf16_f32 v230, v176, v177
	v_ffbh_u32_e32 v176, v189
	v_pk_mul_f32 v[232:233], v[130:131], v[232:233]
	s_nop 0
	v_cvt_pk_bf16_f32 v231, v232, v233
	global_store_dwordx4 v[238:239], v[228:231], off offset:64
	s_nop 1
	v_min_u32_e32 v228, 32, v176
	v_lshlrev_b64 v[176:177], v228, v[188:189]
	v_min_u32_e32 v176, 1, v176
	v_or_b32_e32 v176, v177, v176
	v_cvt_f32_u32_e32 v176, v176
	v_sub_u32_e32 v177, 32, v228
	v_ldexp_f32 v176, v176, v177
	v_mul_f32_e32 v176, 0x35800000, v176
	v_fmamk_f32 v176, v176, 0x3a800000, v210
	s_nop 0
	v_rsq_f32_e32 v176, v176
	s_nop 0
	v_pk_mul_f32 v[228:229], v[44:45], v[176:177] op_sel_hi:[1,0]
	v_pk_mul_f32 v[230:231], v[46:47], v[176:177] op_sel_hi:[1,0]
	v_pk_mul_f32 v[234:235], v[228:229], v[228:229]
	v_pk_mul_f32 v[232:233], v[230:231], v[230:231]
	v_pk_mul_f32 v[248:249], v[34:35], v[176:177] op_sel_hi:[1,0]
	v_pk_mov_b32 v[236:237], v[234:235], v[232:233] op_sel:[1,0]
	v_mov_b32_e32 v235, v233
	v_pk_add_f32 v[232:233], v[236:237], v[234:235]
	v_pk_mul_f32 v[234:235], v[40:41], v[176:177] op_sel_hi:[1,0]
	v_pk_mul_f32 v[236:237], v[42:43], v[176:177] op_sel_hi:[1,0]
	v_pk_mul_f32 v[240:241], v[234:235], v[234:235]
	v_pk_mul_f32 v[238:239], v[236:237], v[236:237]
	v_pk_add_f32 v[232:233], v[232:233], v[232:233] op_sel_hi:[0,1]
	v_pk_mov_b32 v[242:243], v[240:241], v[238:239] op_sel:[1,0]
	v_mov_b32_e32 v241, v239
	v_pk_add_f32 v[238:239], v[242:243], v[240:241]
	v_pk_mul_f32 v[242:243], v[36:37], v[176:177] op_sel_hi:[1,0]
	v_pk_mul_f32 v[240:241], v[38:39], v[176:177] op_sel_hi:[1,0]
	v_mul_f32_e32 v232, v242, v242
	v_pk_fma_f32 v[244:245], v[242:243], v[242:243], v[232:233] op_sel_hi:[1,1,0]
	v_mul_f32_e32 v232, v240, v240
	v_pk_add_f32 v[238:239], v[238:239], v[238:239] op_sel_hi:[0,1]
	v_pk_fma_f32 v[246:247], v[240:241], v[240:241], v[232:233] op_sel_hi:[1,1,0]
	v_pk_mul_f32 v[176:177], v[32:33], v[176:177] op_sel_hi:[1,0]
	v_mul_f32_e32 v232, v248, v248
	v_mul_f32_e32 v244, v176, v176
	v_mul_f32_e32 v246, v177, v177
	v_mul_f32_e32 v238, v249, v249
	v_pk_add_f32 v[244:245], v[244:245], v[246:247]
	v_pk_add_f32 v[232:233], v[232:233], v[238:239]
	v_lshlrev_b64 v[238:239], 10, v[164:165]
	v_pk_add_f32 v[232:233], v[244:245], v[232:233]
	v_lshl_add_u64 v[238:239], v[206:207], 0, v[238:239]
	v_add_f32_e32 v232, v232, v233
	ds_bpermute_b32 v233, v225, v232
	s_waitcnt lgkmcnt(0)
	v_add_f32_e32 v232, v232, v233
	ds_bpermute_b32 v233, v224, v232
	s_waitcnt lgkmcnt(0)
	v_add_f32_e32 v232, v232, v233
	v_fmamk_f32 v232, v232, 0x3c800000, v210
	s_nop 0
	v_rsq_f32_e32 v232, v232
	s_nop 0
	v_mul_f32_e32 v232, v223, v232
	v_pk_mul_f32 v[228:229], v[228:229], v[232:233] op_sel_hi:[1,0]
	v_pk_mul_f32 v[230:231], v[230:231], v[232:233] op_sel_hi:[1,0]
	v_pk_mul_f32 v[228:229], v[140:141], v[228:229]
	v_pk_mul_f32 v[230:231], v[142:143], v[230:231]
	v_pk_mul_f32 v[234:235], v[234:235], v[232:233] op_sel_hi:[1,0]
	v_pk_mul_f32 v[236:237], v[236:237], v[232:233] op_sel_hi:[1,0]
	v_pk_mul_f32 v[234:235], v[136:137], v[234:235]
	v_pk_mul_f32 v[236:237], v[138:139], v[236:237]
	v_cvt_pk_bf16_f32 v228, v228, v229
	v_cvt_pk_bf16_f32 v229, v230, v231
	v_cvt_pk_bf16_f32 v230, v234, v235
	v_pk_mul_f32 v[176:177], v[176:177], v[232:233] op_sel_hi:[1,0]
	v_cvt_pk_bf16_f32 v231, v236, v237
	global_store_dwordx4 v[238:239], v[228:231], off
	v_pk_mul_f32 v[176:177], v[128:129], v[176:177]
	s_nop 0
	v_pk_mul_f32 v[228:229], v[242:243], v[232:233] op_sel_hi:[1,0]
	v_pk_mul_f32 v[230:231], v[240:241], v[232:233] op_sel_hi:[1,0]
	v_pk_mul_f32 v[228:229], v[132:133], v[228:229]
	v_pk_mul_f32 v[230:231], v[134:135], v[230:231]
	v_pk_mul_f32 v[232:233], v[248:249], v[232:233] op_sel_hi:[1,0]
	v_cvt_pk_bf16_f32 v228, v228, v229
	v_cvt_pk_bf16_f32 v229, v230, v231
	v_cvt_pk_bf16_f32 v230, v176, v177
	v_ffbh_u32_e32 v176, v163
	v_pk_mul_f32 v[232:233], v[130:131], v[232:233]
	s_nop 0
	v_cvt_pk_bf16_f32 v231, v232, v233
	global_store_dwordx4 v[238:239], v[228:231], off offset:64
	s_nop 1
	v_min_u32_e32 v228, 32, v176
	v_lshlrev_b64 v[176:177], v228, v[162:163]
	v_min_u32_e32 v176, 1, v176
	v_or_b32_e32 v176, v177, v176
	v_cvt_f32_u32_e32 v176, v176
	v_sub_u32_e32 v177, 32, v228
	v_ldexp_f32 v176, v176, v177
	v_mul_f32_e32 v176, 0x35800000, v176
	v_fmamk_f32 v176, v176, 0x3a800000, v210
	s_nop 0
	v_rsq_f32_e32 v176, v176
	s_nop 0
	v_pk_mul_f32 v[228:229], v[28:29], v[176:177] op_sel_hi:[1,0]
	v_pk_mul_f32 v[230:231], v[30:31], v[176:177] op_sel_hi:[1,0]
	v_pk_mul_f32 v[234:235], v[228:229], v[228:229]
	v_pk_mul_f32 v[232:233], v[230:231], v[230:231]
	v_pk_mul_f32 v[248:249], v[18:19], v[176:177] op_sel_hi:[1,0]
	v_pk_mov_b32 v[236:237], v[234:235], v[232:233] op_sel:[1,0]
	v_mov_b32_e32 v235, v233
	v_pk_add_f32 v[232:233], v[236:237], v[234:235]
	v_pk_mul_f32 v[234:235], v[24:25], v[176:177] op_sel_hi:[1,0]
	v_pk_mul_f32 v[236:237], v[26:27], v[176:177] op_sel_hi:[1,0]
	v_pk_mul_f32 v[240:241], v[234:235], v[234:235]
	v_pk_mul_f32 v[238:239], v[236:237], v[236:237]
	v_pk_add_f32 v[232:233], v[232:233], v[232:233] op_sel_hi:[0,1]
	v_pk_mov_b32 v[242:243], v[240:241], v[238:239] op_sel:[1,0]
	v_mov_b32_e32 v241, v239
	v_pk_add_f32 v[238:239], v[242:243], v[240:241]
	v_pk_mul_f32 v[242:243], v[20:21], v[176:177] op_sel_hi:[1,0]
	v_pk_mul_f32 v[240:241], v[22:23], v[176:177] op_sel_hi:[1,0]
	v_mul_f32_e32 v232, v242, v242
	v_pk_fma_f32 v[244:245], v[242:243], v[242:243], v[232:233] op_sel_hi:[1,1,0]
	v_mul_f32_e32 v232, v240, v240
	v_pk_add_f32 v[238:239], v[238:239], v[238:239] op_sel_hi:[0,1]
	v_pk_fma_f32 v[246:247], v[240:241], v[240:241], v[232:233] op_sel_hi:[1,1,0]
	v_pk_mul_f32 v[176:177], v[16:17], v[176:177] op_sel_hi:[1,0]
	v_mul_f32_e32 v232, v248, v248
	v_mul_f32_e32 v244, v176, v176
	v_mul_f32_e32 v246, v177, v177
	v_mul_f32_e32 v238, v249, v249
	v_pk_add_f32 v[244:245], v[244:245], v[246:247]
	v_pk_add_f32 v[232:233], v[232:233], v[238:239]
	v_lshlrev_b64 v[238:239], 10, v[158:159]
	v_pk_add_f32 v[232:233], v[244:245], v[232:233]
	v_lshl_add_u64 v[238:239], v[206:207], 0, v[238:239]
	v_add_f32_e32 v232, v232, v233
	ds_bpermute_b32 v233, v225, v232
	s_waitcnt lgkmcnt(0)
	v_add_f32_e32 v232, v232, v233
	ds_bpermute_b32 v233, v224, v232
	s_waitcnt lgkmcnt(0)
	v_add_f32_e32 v232, v232, v233
	v_fmamk_f32 v232, v232, 0x3c800000, v210
	s_nop 0
	v_rsq_f32_e32 v232, v232
	s_nop 0
	v_mul_f32_e32 v232, v223, v232
	v_pk_mul_f32 v[228:229], v[228:229], v[232:233] op_sel_hi:[1,0]
	v_pk_mul_f32 v[230:231], v[230:231], v[232:233] op_sel_hi:[1,0]
	v_pk_mul_f32 v[228:229], v[140:141], v[228:229]
	v_pk_mul_f32 v[230:231], v[142:143], v[230:231]
	v_pk_mul_f32 v[234:235], v[234:235], v[232:233] op_sel_hi:[1,0]
	v_pk_mul_f32 v[236:237], v[236:237], v[232:233] op_sel_hi:[1,0]
	v_pk_mul_f32 v[234:235], v[136:137], v[234:235]
	v_pk_mul_f32 v[236:237], v[138:139], v[236:237]
	v_cvt_pk_bf16_f32 v228, v228, v229
	v_cvt_pk_bf16_f32 v229, v230, v231
	v_cvt_pk_bf16_f32 v230, v234, v235
	v_pk_mul_f32 v[176:177], v[176:177], v[232:233] op_sel_hi:[1,0]
	v_cvt_pk_bf16_f32 v231, v236, v237
	global_store_dwordx4 v[238:239], v[228:231], off
	v_pk_mul_f32 v[176:177], v[128:129], v[176:177]
	s_nop 0
	v_pk_mul_f32 v[228:229], v[242:243], v[232:233] op_sel_hi:[1,0]
	v_pk_mul_f32 v[230:231], v[240:241], v[232:233] op_sel_hi:[1,0]
	v_pk_mul_f32 v[228:229], v[132:133], v[228:229]
	v_pk_mul_f32 v[230:231], v[134:135], v[230:231]
	v_pk_mul_f32 v[232:233], v[248:249], v[232:233] op_sel_hi:[1,0]
	v_cvt_pk_bf16_f32 v228, v228, v229
	v_cvt_pk_bf16_f32 v229, v230, v231
	v_cvt_pk_bf16_f32 v230, v176, v177
	v_ffbh_u32_e32 v176, v161
	v_pk_mul_f32 v[232:233], v[130:131], v[232:233]
	s_nop 0
	v_cvt_pk_bf16_f32 v231, v232, v233
	global_store_dwordx4 v[238:239], v[228:231], off offset:64
	s_nop 1
	v_min_u32_e32 v228, 32, v176
	v_lshlrev_b64 v[176:177], v228, v[160:161]
	v_min_u32_e32 v176, 1, v176
	v_or_b32_e32 v176, v177, v176
	v_cvt_f32_u32_e32 v176, v176
	v_sub_u32_e32 v177, 32, v228
	v_ldexp_f32 v176, v176, v177
	v_mul_f32_e32 v176, 0x35800000, v176
	v_fmamk_f32 v176, v176, 0x3a800000, v210
	s_nop 0
	v_rsq_f32_e32 v176, v176
	s_nop 0
	v_pk_mul_f32 v[228:229], v[12:13], v[176:177] op_sel_hi:[1,0]
	v_pk_mul_f32 v[230:231], v[14:15], v[176:177] op_sel_hi:[1,0]
	v_pk_mul_f32 v[234:235], v[228:229], v[228:229]
	v_pk_mul_f32 v[232:233], v[230:231], v[230:231]
	v_pk_mul_f32 v[248:249], v[2:3], v[176:177] op_sel_hi:[1,0]
	v_pk_mov_b32 v[236:237], v[234:235], v[232:233] op_sel:[1,0]
	v_mov_b32_e32 v235, v233
	v_pk_add_f32 v[232:233], v[236:237], v[234:235]
	v_pk_mul_f32 v[234:235], v[8:9], v[176:177] op_sel_hi:[1,0]
	v_pk_mul_f32 v[236:237], v[10:11], v[176:177] op_sel_hi:[1,0]
	v_pk_mul_f32 v[240:241], v[234:235], v[234:235]
	v_pk_mul_f32 v[238:239], v[236:237], v[236:237]
	v_pk_add_f32 v[232:233], v[232:233], v[232:233] op_sel_hi:[0,1]
	v_pk_mov_b32 v[242:243], v[240:241], v[238:239] op_sel:[1,0]
	v_mov_b32_e32 v241, v239
	v_pk_add_f32 v[238:239], v[242:243], v[240:241]
	v_pk_mul_f32 v[242:243], v[4:5], v[176:177] op_sel_hi:[1,0]
	v_pk_mul_f32 v[240:241], v[6:7], v[176:177] op_sel_hi:[1,0]
	v_mul_f32_e32 v232, v242, v242
	v_pk_fma_f32 v[244:245], v[242:243], v[242:243], v[232:233] op_sel_hi:[1,1,0]
	v_mul_f32_e32 v232, v240, v240
	v_pk_add_f32 v[238:239], v[238:239], v[238:239] op_sel_hi:[0,1]
	v_pk_fma_f32 v[246:247], v[240:241], v[240:241], v[232:233] op_sel_hi:[1,1,0]
	v_pk_mul_f32 v[176:177], v[0:1], v[176:177] op_sel_hi:[1,0]
	v_mul_f32_e32 v232, v248, v248
	v_mul_f32_e32 v244, v176, v176
	v_mul_f32_e32 v246, v177, v177
	v_mul_f32_e32 v238, v249, v249
	v_pk_add_f32 v[244:245], v[244:245], v[246:247]
	v_pk_add_f32 v[232:233], v[232:233], v[238:239]
	s_nop 0
	v_pk_add_f32 v[232:233], v[244:245], v[232:233]
	s_nop 0
	v_add_f32_e32 v232, v232, v233
	ds_bpermute_b32 v225, v225, v232
	s_waitcnt lgkmcnt(0)
	v_add_f32_e32 v225, v232, v225
	ds_bpermute_b32 v224, v224, v225
	v_lshlrev_b64 v[232:233], 10, v[156:157]
	v_lshl_add_u64 v[206:207], v[206:207], 0, v[232:233]
	s_waitcnt lgkmcnt(0)
	v_add_f32_e32 v224, v225, v224
	v_fmamk_f32 v224, v224, 0x3c800000, v210
	s_nop 0
	v_rsq_f32_e32 v224, v224
	s_nop 0
	v_mul_f32_e32 v224, v223, v224
	v_pk_mul_f32 v[228:229], v[228:229], v[224:225] op_sel_hi:[1,0]
	v_pk_mul_f32 v[230:231], v[230:231], v[224:225] op_sel_hi:[1,0]
	v_pk_mul_f32 v[140:141], v[140:141], v[228:229]
	v_pk_mul_f32 v[142:143], v[142:143], v[230:231]
	v_pk_mul_f32 v[228:229], v[234:235], v[224:225] op_sel_hi:[1,0]
	v_pk_mul_f32 v[230:231], v[236:237], v[224:225] op_sel_hi:[1,0]
	s_nop 0
	v_pk_mul_f32 v[230:231], v[138:139], v[230:231]
	v_pk_mul_f32 v[138:139], v[136:137], v[228:229]
	v_cvt_pk_bf16_f32 v136, v140, v141
	v_cvt_pk_bf16_f32 v137, v142, v143
	s_nop 0
	v_cvt_pk_bf16_f32 v138, v138, v139
	v_cvt_pk_bf16_f32 v139, v230, v231
	global_store_dwordx4 v[206:207], v[136:139], off
	s_nop 1
	v_pk_mul_f32 v[136:137], v[242:243], v[224:225] op_sel_hi:[1,0]
	v_pk_mul_f32 v[138:139], v[240:241], v[224:225] op_sel_hi:[1,0]
	v_pk_mul_f32 v[132:133], v[132:133], v[136:137]
	v_pk_mul_f32 v[134:135], v[134:135], v[138:139]
	v_pk_mul_f32 v[136:137], v[176:177], v[224:225] op_sel_hi:[1,0]
	v_pk_mul_f32 v[138:139], v[248:249], v[224:225] op_sel_hi:[1,0]
	s_nop 0
	v_pk_mul_f32 v[138:139], v[130:131], v[138:139]
	v_pk_mul_f32 v[130:131], v[128:129], v[136:137]
	v_cvt_pk_bf16_f32 v128, v132, v133
	v_cvt_pk_bf16_f32 v129, v134, v135
	s_nop 0
	v_cvt_pk_bf16_f32 v130, v130, v131
	v_cvt_pk_bf16_f32 v131, v138, v139
	s_nop 1

.LBB0_350:
	s_lshl_b32 s25, s84, 1
	s_add_i32 s25, s85, s25
	s_and_b32 s85, s25, 3
	s_lshl_b32 s25, s85, 19
	s_add_u32 s92, s74, s25
	v_cmp_lt_i64_e32 vcc, s[52:53], v[180:181]
	s_addc_u32 s93, s75, 0
	s_and_b64 s[30:31], vcc, exec
	s_cselect_b32 s25, s93, s1
	s_cselect_b32 s30, s92, s0
	s_ashr_i32 s47, s46, 31
	s_lshl_b64 s[34:35], s[46:47], 19
	s_add_u32 s94, s54, s34
	s_addc_u32 s95, s55, s35
	s_and_b64 s[34:35], vcc, exec
	s_cselect_b32 s31, s95, s51
	s_cselect_b32 s33, s94, s50
	s_add_u32 s0, s0, 0x40080
	s_addc_u32 s1, s1, 0
	s_add_u32 s34, s50, 0x100
	s_addc_u32 s35, s51, 0
	s_mov_b32 s36, -2
	s_add_u32 s27, s0, 0xfffc0080
	s_addc_u32 s37, s1, -1
	s_add_i32 s47, 0, 0x10000
	v_add_u32_e32 v140, s47, v192
	ds_read_b128 v[128:131], v140
	ds_read_b128 v[132:135], v140 offset:1024
	ds_read_b128 v[136:139], v140 offset:2048
	ds_read_b128 v[140:143], v140 offset:3072
	s_cmp_eq_u32 s36, 12
	s_cselect_b32 s53, s25, s37
	s_cselect_b32 s52, s30, s27
	s_cselect_b32 s51, s31, s35
	s_cselect_b32 s50, s33, s34
	v_lshl_add_u64 v[176:177], s[0:1], 0, v[156:157]
	s_add_i32 m0, s77, 0xc000
	ds_read_b128 v[162:165], v194
	ds_read_b128 v[166:169], v194 offset:1024
	ds_read_b128 v[196:199], v194 offset:2048
	ds_read_b128 v[200:203], v194 offset:3072
	ds_read_b128 v[204:207], v194 offset:4096
	ds_read_b128 v[216:219], v194 offset:5120
	ds_read_b128 v[220:223], v194 offset:6144
	ds_read_b128 v[228:231], v194 offset:7168
	global_load_lds_dwordx4 v[176:177], off
	v_lshl_add_u64 v[176:177], s[0:1], 0, v[158:159]
	s_add_i32 m0, s77, 0xe000
	s_nop 0
	global_load_lds_dwordx4 v[176:177], off
	s_waitcnt lgkmcnt(8)
	s_setprio 1
	s_barrier
	s_waitcnt lgkmcnt(0)
	v_mfma_f32_16x16x32_bf16 v[124:127], v[128:131], v[162:165], 0
	v_mfma_f32_16x16x32_bf16 v[120:123], v[136:139], v[162:165], 0
	v_mfma_f32_16x16x32_bf16 v[116:119], v[128:131], v[196:199], 0
	v_mfma_f32_16x16x32_bf16 v[112:115], v[136:139], v[196:199], 0
	v_mfma_f32_16x16x32_bf16 v[108:111], v[128:131], v[204:207], 0
	v_mfma_f32_16x16x32_bf16 v[104:107], v[136:139], v[204:207], 0
	v_mfma_f32_16x16x32_bf16 v[100:103], v[128:131], v[220:223], 0
	v_mfma_f32_16x16x32_bf16 v[96:99], v[136:139], v[220:223], 0
	v_mfma_f32_16x16x32_bf16 v[124:127], v[132:135], v[166:169], v[124:127]
	v_mfma_f32_16x16x32_bf16 v[120:123], v[140:143], v[166:169], v[120:123]
	v_mfma_f32_16x16x32_bf16 v[116:119], v[132:135], v[200:203], v[116:119]
	v_mfma_f32_16x16x32_bf16 v[112:115], v[140:143], v[200:203], v[112:115]
	v_mfma_f32_16x16x32_bf16 v[108:111], v[132:135], v[216:219], v[108:111]
	v_mfma_f32_16x16x32_bf16 v[104:107], v[140:143], v[216:219], v[104:107]
	v_mfma_f32_16x16x32_bf16 v[100:103], v[132:135], v[228:231], v[100:103]
	v_mfma_f32_16x16x32_bf16 v[96:99], v[140:143], v[228:231], v[96:99]
	s_barrier
	s_setprio 0
	s_add_i32 s27, 0, 0x14000
	s_add_i32 s37, s47, s76
	v_add_u32_e32 v161, s27, v192
	v_lshl_add_u64 v[176:177], s[50:51], 0, v[148:149]
	s_mov_b32 m0, s37
	ds_read_b128 v[232:235], v161
	ds_read_b128 v[236:239], v161 offset:1024
	ds_read_b128 v[240:243], v161 offset:2048
	ds_read_b128 v[244:247], v161 offset:3072
	global_load_lds_dwordx4 v[176:177], off
	v_lshl_add_u64 v[188:189], s[50:51], 0, v[152:153]
	s_add_i32 m0, s37, 0x2000
	s_nop 0
	global_load_lds_dwordx4 v[188:189], off
	s_setprio 1
	s_barrier
	s_waitcnt lgkmcnt(0)
	v_mfma_f32_16x16x32_bf16 v[92:95], v[232:235], v[162:165], 0
	v_mfma_f32_16x16x32_bf16 v[88:91], v[240:243], v[162:165], 0
	v_mfma_f32_16x16x32_bf16 v[84:87], v[232:235], v[196:199], 0
	v_mfma_f32_16x16x32_bf16 v[80:83], v[240:243], v[196:199], 0
	v_mfma_f32_16x16x32_bf16 v[76:79], v[232:235], v[204:207], 0
	v_mfma_f32_16x16x32_bf16 v[72:75], v[240:243], v[204:207], 0
	v_mfma_f32_16x16x32_bf16 v[68:71], v[232:235], v[220:223], 0
	v_mfma_f32_16x16x32_bf16 v[64:67], v[240:243], v[220:223], 0
	v_mfma_f32_16x16x32_bf16 v[92:95], v[236:239], v[166:169], v[92:95]
	v_mfma_f32_16x16x32_bf16 v[88:91], v[244:247], v[166:169], v[88:91]
	v_mfma_f32_16x16x32_bf16 v[84:87], v[236:239], v[200:203], v[84:87]
	v_mfma_f32_16x16x32_bf16 v[80:83], v[244:247], v[200:203], v[80:83]
	v_mfma_f32_16x16x32_bf16 v[76:79], v[236:239], v[216:219], v[76:79]
	v_mfma_f32_16x16x32_bf16 v[72:75], v[244:247], v[216:219], v[72:75]
	v_mfma_f32_16x16x32_bf16 v[68:71], v[236:239], v[228:231], v[68:71]
	v_mfma_f32_16x16x32_bf16 v[64:67], v[244:247], v[228:231], v[64:67]
	s_setprio 0
	s_mov_b32 m0, s77
	v_lshl_add_u64 v[224:225], s[52:53], 0, v[146:147]
	s_barrier
	ds_read_b128 v[162:165], v194 offset:16384
	ds_read_b128 v[166:169], v194 offset:17408
	ds_read_b128 v[196:199], v194 offset:18432
	ds_read_b128 v[200:203], v194 offset:19456
	ds_read_b128 v[204:207], v194 offset:20480
	ds_read_b128 v[216:219], v194 offset:21504
	ds_read_b128 v[220:223], v194 offset:22528
	ds_read_b128 v[228:231], v194 offset:23552
	global_load_lds_dwordx4 v[224:225], off
	v_lshl_add_u64 v[248:249], s[52:53], 0, v[150:151]
	s_mov_b32 m0, s78
	s_nop 0
	global_load_lds_dwordx4 v[248:249], off
	s_setprio 1
	s_barrier
	s_waitcnt lgkmcnt(0)
	v_mfma_f32_16x16x32_bf16 v[60:63], v[128:131], v[162:165], 0
	v_mfma_f32_16x16x32_bf16 v[56:59], v[136:139], v[162:165], 0
	v_mfma_f32_16x16x32_bf16 v[52:55], v[128:131], v[196:199], 0
	v_mfma_f32_16x16x32_bf16 v[48:51], v[136:139], v[196:199], 0
	v_mfma_f32_16x16x32_bf16 v[44:47], v[128:131], v[204:207], 0
	v_mfma_f32_16x16x32_bf16 v[40:43], v[136:139], v[204:207], 0
	v_mfma_f32_16x16x32_bf16 v[36:39], v[128:131], v[220:223], 0
	v_mfma_f32_16x16x32_bf16 v[32:35], v[136:139], v[220:223], 0
	v_mfma_f32_16x16x32_bf16 v[60:63], v[132:135], v[166:169], v[60:63]
	v_mfma_f32_16x16x32_bf16 v[56:59], v[140:143], v[166:169], v[56:59]
	v_mfma_f32_16x16x32_bf16 v[52:55], v[132:135], v[200:203], v[52:55]
	v_mfma_f32_16x16x32_bf16 v[48:51], v[140:143], v[200:203], v[48:51]
	v_mfma_f32_16x16x32_bf16 v[44:47], v[132:135], v[216:219], v[44:47]
	v_mfma_f32_16x16x32_bf16 v[40:43], v[140:143], v[216:219], v[40:43]
	v_mfma_f32_16x16x32_bf16 v[36:39], v[132:135], v[228:231], v[36:39]
	v_mfma_f32_16x16x32_bf16 v[32:35], v[140:143], v[228:231], v[32:35]
	s_barrier
	s_setprio 0
	s_add_u32 s56, s50, 0x40000
	s_addc_u32 s57, s51, 0
	s_add_i32 s27, s27, s76
	v_lshl_add_u64 v[128:129], s[56:57], 0, v[148:149]
	s_mov_b32 m0, s27
	s_nop 0
	global_load_lds_dwordx4 v[128:129], off
	v_lshl_add_u64 v[128:129], s[56:57], 0, v[152:153]
	s_add_i32 m0, s27, 0x2000
	s_nop 0
	global_load_lds_dwordx4 v[128:129], off
	s_waitcnt vmcnt(6)
	s_setprio 1
	s_barrier
	v_mfma_f32_16x16x32_bf16 v[28:31], v[232:235], v[162:165], 0
	v_mfma_f32_16x16x32_bf16 v[24:27], v[240:243], v[162:165], 0
	v_mfma_f32_16x16x32_bf16 v[20:23], v[232:235], v[196:199], 0
	v_mfma_f32_16x16x32_bf16 v[16:19], v[240:243], v[196:199], 0
	v_mfma_f32_16x16x32_bf16 v[12:15], v[232:235], v[204:207], 0
	v_mfma_f32_16x16x32_bf16 v[8:11], v[240:243], v[204:207], 0
	v_mfma_f32_16x16x32_bf16 v[4:7], v[232:235], v[220:223], 0
	v_mfma_f32_16x16x32_bf16 v[0:3], v[240:243], v[220:223], 0
	v_mfma_f32_16x16x32_bf16 v[28:31], v[236:239], v[166:169], v[28:31]
	v_mfma_f32_16x16x32_bf16 v[24:27], v[244:247], v[166:169], v[24:27]
	v_mfma_f32_16x16x32_bf16 v[20:23], v[236:239], v[200:203], v[20:23]
	v_mfma_f32_16x16x32_bf16 v[16:19], v[244:247], v[200:203], v[16:19]
	v_mfma_f32_16x16x32_bf16 v[12:15], v[236:239], v[216:219], v[12:15]
	v_mfma_f32_16x16x32_bf16 v[8:11], v[244:247], v[216:219], v[8:11]
	v_mfma_f32_16x16x32_bf16 v[4:7], v[236:239], v[228:231], v[4:7]
	v_mfma_f32_16x16x32_bf16 v[0:3], v[244:247], v[228:231], v[0:3]
	s_setprio 0
	s_add_i32 s27, 0, 0x18000
	v_add_u32_e32 v140, s27, v192
	s_barrier
	ds_read_b128 v[128:131], v140
	ds_read_b128 v[132:135], v140 offset:1024
	ds_read_b128 v[136:139], v140 offset:2048
	ds_read_b128 v[140:143], v140 offset:3072
	s_add_u32 s52, s52, 0x40000
	s_addc_u32 s53, s53, 0
	s_mov_b32 m0, s81
	v_lshl_add_u64 v[232:233], s[52:53], 0, v[146:147]
	ds_read_b128 v[162:165], v194 offset:32768
	ds_read_b128 v[166:169], v194 offset:33792
	ds_read_b128 v[196:199], v194 offset:34816
	ds_read_b128 v[200:203], v194 offset:35840
	ds_read_b128 v[204:207], v194 offset:36864
	ds_read_b128 v[216:219], v194 offset:37888
	ds_read_b128 v[220:223], v194 offset:38912
	ds_read_b128 v[228:231], v194 offset:39936
	global_load_lds_dwordx4 v[232:233], off
	v_lshl_add_u64 v[232:233], s[52:53], 0, v[150:151]
	s_mov_b32 m0, s82
	s_nop 0
	global_load_lds_dwordx4 v[232:233], off
	s_waitcnt lgkmcnt(8)
	s_setprio 1
	s_barrier
	s_waitcnt lgkmcnt(0)
	v_mfma_f32_16x16x32_bf16 v[124:127], v[128:131], v[162:165], v[124:127]
	v_mfma_f32_16x16x32_bf16 v[120:123], v[136:139], v[162:165], v[120:123]
	v_mfma_f32_16x16x32_bf16 v[116:119], v[128:131], v[196:199], v[116:119]
	v_mfma_f32_16x16x32_bf16 v[112:115], v[136:139], v[196:199], v[112:115]
	v_mfma_f32_16x16x32_bf16 v[108:111], v[128:131], v[204:207], v[108:111]
	v_mfma_f32_16x16x32_bf16 v[104:107], v[136:139], v[204:207], v[104:107]
	v_mfma_f32_16x16x32_bf16 v[100:103], v[128:131], v[220:223], v[100:103]
	v_mfma_f32_16x16x32_bf16 v[96:99], v[136:139], v[220:223], v[96:99]
	v_mfma_f32_16x16x32_bf16 v[124:127], v[132:135], v[166:169], v[124:127]
	v_mfma_f32_16x16x32_bf16 v[120:123], v[140:143], v[166:169], v[120:123]
	v_mfma_f32_16x16x32_bf16 v[116:119], v[132:135], v[200:203], v[116:119]
	v_mfma_f32_16x16x32_bf16 v[112:115], v[140:143], v[200:203], v[112:115]
	v_mfma_f32_16x16x32_bf16 v[108:111], v[132:135], v[216:219], v[108:111]
	v_mfma_f32_16x16x32_bf16 v[104:107], v[140:143], v[216:219], v[104:107]
	v_mfma_f32_16x16x32_bf16 v[100:103], v[132:135], v[228:231], v[100:103]
	v_mfma_f32_16x16x32_bf16 v[96:99], v[140:143], v[228:231], v[96:99]
	s_barrier
	s_setprio 0
	s_add_i32 s37, 0, 0x1c000
	s_add_i32 s27, s27, s76
	v_add_u32_e32 v161, s37, v192
	v_lshl_add_u64 v[176:177], v[176:177], 0, s[18:19]
	s_mov_b32 m0, s27
	ds_read_b128 v[232:235], v161
	ds_read_b128 v[236:239], v161 offset:1024
	ds_read_b128 v[240:243], v161 offset:2048
	ds_read_b128 v[244:247], v161 offset:3072
	global_load_lds_dwordx4 v[176:177], off
	v_lshl_add_u64 v[176:177], v[188:189], 0, s[18:19]
	s_add_i32 m0, s27, 0x2000
	s_nop 0
	global_load_lds_dwordx4 v[176:177], off
	s_setprio 1
	s_barrier
	s_waitcnt lgkmcnt(0)
	v_mfma_f32_16x16x32_bf16 v[92:95], v[232:235], v[162:165], v[92:95]
	v_mfma_f32_16x16x32_bf16 v[88:91], v[240:243], v[162:165], v[88:91]
	v_mfma_f32_16x16x32_bf16 v[84:87], v[232:235], v[196:199], v[84:87]
	v_mfma_f32_16x16x32_bf16 v[80:83], v[240:243], v[196:199], v[80:83]
	v_mfma_f32_16x16x32_bf16 v[76:79], v[232:235], v[204:207], v[76:79]
	v_mfma_f32_16x16x32_bf16 v[72:75], v[240:243], v[204:207], v[72:75]
	v_mfma_f32_16x16x32_bf16 v[68:71], v[232:235], v[220:223], v[68:71]
	v_mfma_f32_16x16x32_bf16 v[64:67], v[240:243], v[220:223], v[64:67]
	v_mfma_f32_16x16x32_bf16 v[92:95], v[236:239], v[166:169], v[92:95]
	v_mfma_f32_16x16x32_bf16 v[88:91], v[244:247], v[166:169], v[88:91]
	v_mfma_f32_16x16x32_bf16 v[84:87], v[236:239], v[200:203], v[84:87]
	v_mfma_f32_16x16x32_bf16 v[80:83], v[244:247], v[200:203], v[80:83]
	v_mfma_f32_16x16x32_bf16 v[76:79], v[236:239], v[216:219], v[76:79]
	v_mfma_f32_16x16x32_bf16 v[72:75], v[244:247], v[216:219], v[72:75]
	v_mfma_f32_16x16x32_bf16 v[68:71], v[236:239], v[228:231], v[68:71]
	v_mfma_f32_16x16x32_bf16 v[64:67], v[244:247], v[228:231], v[64:67]
	s_setprio 0
	s_mov_b32 m0, s80
	v_lshl_add_u64 v[176:177], v[224:225], 0, s[18:19]
	s_barrier
	ds_read_b128 v[162:165], v194 offset:49152
	ds_read_b128 v[166:169], v194 offset:50176
	ds_read_b128 v[196:199], v194 offset:51200
	ds_read_b128 v[200:203], v194 offset:52224
	ds_read_b128 v[204:207], v194 offset:53248
	ds_read_b128 v[216:219], v194 offset:54272
	ds_read_b128 v[220:223], v194 offset:55296
	ds_read_b128 v[228:231], v194 offset:56320
	global_load_lds_dwordx4 v[176:177], off
	v_lshl_add_u64 v[176:177], v[248:249], 0, s[18:19]
	s_mov_b32 m0, s83
	s_nop 0
	global_load_lds_dwordx4 v[176:177], off
	s_setprio 1
	s_barrier
	s_waitcnt lgkmcnt(0)
	v_mfma_f32_16x16x32_bf16 v[60:63], v[128:131], v[162:165], v[60:63]
	v_mfma_f32_16x16x32_bf16 v[56:59], v[136:139], v[162:165], v[56:59]
	v_mfma_f32_16x16x32_bf16 v[52:55], v[128:131], v[196:199], v[52:55]
	v_mfma_f32_16x16x32_bf16 v[48:51], v[136:139], v[196:199], v[48:51]
	v_mfma_f32_16x16x32_bf16 v[44:47], v[128:131], v[204:207], v[44:47]
	v_mfma_f32_16x16x32_bf16 v[40:43], v[136:139], v[204:207], v[40:43]
	v_mfma_f32_16x16x32_bf16 v[36:39], v[128:131], v[220:223], v[36:39]
	v_mfma_f32_16x16x32_bf16 v[32:35], v[136:139], v[220:223], v[32:35]
	v_mfma_f32_16x16x32_bf16 v[60:63], v[132:135], v[166:169], v[60:63]
	v_mfma_f32_16x16x32_bf16 v[56:59], v[140:143], v[166:169], v[56:59]
	v_mfma_f32_16x16x32_bf16 v[52:55], v[132:135], v[200:203], v[52:55]
	v_mfma_f32_16x16x32_bf16 v[48:51], v[140:143], v[200:203], v[48:51]
	v_mfma_f32_16x16x32_bf16 v[44:47], v[132:135], v[216:219], v[44:47]
	v_mfma_f32_16x16x32_bf16 v[40:43], v[140:143], v[216:219], v[40:43]
	v_mfma_f32_16x16x32_bf16 v[36:39], v[132:135], v[228:231], v[36:39]
	v_mfma_f32_16x16x32_bf16 v[32:35], v[140:143], v[228:231], v[32:35]
	s_barrier
	s_setprio 0
	s_add_u32 s50, s50, 0x40080
	s_addc_u32 s51, s51, 0
	s_add_i32 s27, s37, s76
	v_lshl_add_u64 v[128:129], s[50:51], 0, v[148:149]
	s_mov_b32 m0, s27
	s_nop 0
	global_load_lds_dwordx4 v[128:129], off
	v_lshl_add_u64 v[128:129], s[50:51], 0, v[152:153]
	s_add_i32 m0, s27, 0x2000
	s_nop 0
	global_load_lds_dwordx4 v[128:129], off
	s_waitcnt vmcnt(6)
	s_setprio 1
	s_barrier
	v_mfma_f32_16x16x32_bf16 v[28:31], v[232:235], v[162:165], v[28:31]
	v_mfma_f32_16x16x32_bf16 v[24:27], v[240:243], v[162:165], v[24:27]
	v_mfma_f32_16x16x32_bf16 v[20:23], v[232:235], v[196:199], v[20:23]
	v_mfma_f32_16x16x32_bf16 v[16:19], v[240:243], v[196:199], v[16:19]
	v_mfma_f32_16x16x32_bf16 v[12:15], v[232:235], v[204:207], v[12:15]
	v_mfma_f32_16x16x32_bf16 v[8:11], v[240:243], v[204:207], v[8:11]
	v_mfma_f32_16x16x32_bf16 v[4:7], v[232:235], v[220:223], v[4:7]
	v_mfma_f32_16x16x32_bf16 v[0:3], v[240:243], v[220:223], v[0:3]
	v_mfma_f32_16x16x32_bf16 v[28:31], v[236:239], v[166:169], v[28:31]
	v_mfma_f32_16x16x32_bf16 v[24:27], v[244:247], v[166:169], v[24:27]
	v_mfma_f32_16x16x32_bf16 v[20:23], v[236:239], v[200:203], v[20:23]
	v_mfma_f32_16x16x32_bf16 v[16:19], v[244:247], v[200:203], v[16:19]
	v_mfma_f32_16x16x32_bf16 v[12:15], v[236:239], v[216:219], v[12:15]
	v_mfma_f32_16x16x32_bf16 v[8:11], v[244:247], v[216:219], v[8:11]
	v_mfma_f32_16x16x32_bf16 v[4:7], v[236:239], v[228:231], v[4:7]
	v_mfma_f32_16x16x32_bf16 v[0:3], v[244:247], v[228:231], v[0:3]
	s_setprio 0
	s_add_i32 s36, s36, 2
	s_add_u32 s0, s0, 0x100
	s_addc_u32 s1, s1, 0
	s_add_u32 s34, s34, 0x100
	s_addc_u32 s35, s35, 0
	s_cmp_gt_u32 s36, 13
	s_barrier
.LBB0_351:
	s_add_u32 s27, s0, 0xfffc0080
	s_addc_u32 s37, s1, -1
	s_add_i32 s47, 0, 0x10000
	v_add_u32_e32 v140, s47, v192
	ds_read_b128 v[128:131], v140
	ds_read_b128 v[132:135], v140 offset:1024
	ds_read_b128 v[136:139], v140 offset:2048
	ds_read_b128 v[140:143], v140 offset:3072
	s_cmp_eq_u32 s36, 12
	s_cselect_b32 s53, s25, s37
	s_cselect_b32 s52, s30, s27
	s_cselect_b32 s51, s31, s35
	s_cselect_b32 s50, s33, s34
	v_lshl_add_u64 v[176:177], s[0:1], 0, v[156:157]
	s_add_i32 m0, s77, 0xc000
	ds_read_b128 v[162:165], v194
	ds_read_b128 v[166:169], v194 offset:1024
	ds_read_b128 v[196:199], v194 offset:2048
	ds_read_b128 v[200:203], v194 offset:3072
	ds_read_b128 v[204:207], v194 offset:4096
	ds_read_b128 v[216:219], v194 offset:5120
	ds_read_b128 v[220:223], v194 offset:6144
	ds_read_b128 v[228:231], v194 offset:7168
	global_load_lds_dwordx4 v[176:177], off
	v_lshl_add_u64 v[176:177], s[0:1], 0, v[158:159]
	s_add_i32 m0, s77, 0xe000
	s_nop 0
	global_load_lds_dwordx4 v[176:177], off
	s_waitcnt lgkmcnt(8)
	s_barrier
	s_waitcnt lgkmcnt(0)
	s_setprio 1
	s_waitcnt lgkmcnt(0)
	v_mfma_f32_16x16x32_bf16 v[124:127], v[128:131], v[162:165], v[124:127]
	v_mfma_f32_16x16x32_bf16 v[120:123], v[136:139], v[162:165], v[120:123]
	v_mfma_f32_16x16x32_bf16 v[116:119], v[128:131], v[196:199], v[116:119]
	v_mfma_f32_16x16x32_bf16 v[112:115], v[136:139], v[196:199], v[112:115]
	v_mfma_f32_16x16x32_bf16 v[108:111], v[128:131], v[204:207], v[108:111]
	v_mfma_f32_16x16x32_bf16 v[104:107], v[136:139], v[204:207], v[104:107]
	v_mfma_f32_16x16x32_bf16 v[100:103], v[128:131], v[220:223], v[100:103]
	v_mfma_f32_16x16x32_bf16 v[96:99], v[136:139], v[220:223], v[96:99]
	v_mfma_f32_16x16x32_bf16 v[124:127], v[132:135], v[166:169], v[124:127]
	v_mfma_f32_16x16x32_bf16 v[120:123], v[140:143], v[166:169], v[120:123]
	v_mfma_f32_16x16x32_bf16 v[116:119], v[132:135], v[200:203], v[116:119]
	v_mfma_f32_16x16x32_bf16 v[112:115], v[140:143], v[200:203], v[112:115]
	v_mfma_f32_16x16x32_bf16 v[108:111], v[132:135], v[216:219], v[108:111]
	v_mfma_f32_16x16x32_bf16 v[104:107], v[140:143], v[216:219], v[104:107]
	v_mfma_f32_16x16x32_bf16 v[100:103], v[132:135], v[228:231], v[100:103]
	v_mfma_f32_16x16x32_bf16 v[96:99], v[140:143], v[228:231], v[96:99]
	s_barrier
	s_setprio 0
	s_add_i32 s27, 0, 0x14000
	s_add_i32 s37, s47, s76
	v_add_u32_e32 v161, s27, v192
	v_lshl_add_u64 v[176:177], s[50:51], 0, v[148:149]
	s_mov_b32 m0, s37
	ds_read_b128 v[232:235], v161
	ds_read_b128 v[236:239], v161 offset:1024
	ds_read_b128 v[240:243], v161 offset:2048
	ds_read_b128 v[244:247], v161 offset:3072
	global_load_lds_dwordx4 v[176:177], off
	v_lshl_add_u64 v[188:189], s[50:51], 0, v[152:153]
	s_add_i32 m0, s37, 0x2000
	s_nop 0
	global_load_lds_dwordx4 v[188:189], off
	s_barrier
	s_waitcnt lgkmcnt(0)
	s_setprio 1
	s_waitcnt lgkmcnt(0)
	v_mfma_f32_16x16x32_bf16 v[92:95], v[232:235], v[162:165], v[92:95]
	v_mfma_f32_16x16x32_bf16 v[88:91], v[240:243], v[162:165], v[88:91]
	v_mfma_f32_16x16x32_bf16 v[84:87], v[232:235], v[196:199], v[84:87]
	v_mfma_f32_16x16x32_bf16 v[80:83], v[240:243], v[196:199], v[80:83]
	v_mfma_f32_16x16x32_bf16 v[76:79], v[232:235], v[204:207], v[76:79]
	v_mfma_f32_16x16x32_bf16 v[72:75], v[240:243], v[204:207], v[72:75]
	v_mfma_f32_16x16x32_bf16 v[68:71], v[232:235], v[220:223], v[68:71]
	v_mfma_f32_16x16x32_bf16 v[64:67], v[240:243], v[220:223], v[64:67]
	v_mfma_f32_16x16x32_bf16 v[92:95], v[236:239], v[166:169], v[92:95]
	v_mfma_f32_16x16x32_bf16 v[88:91], v[244:247], v[166:169], v[88:91]
	v_mfma_f32_16x16x32_bf16 v[84:87], v[236:239], v[200:203], v[84:87]
	v_mfma_f32_16x16x32_bf16 v[80:83], v[244:247], v[200:203], v[80:83]
	v_mfma_f32_16x16x32_bf16 v[76:79], v[236:239], v[216:219], v[76:79]
	v_mfma_f32_16x16x32_bf16 v[72:75], v[244:247], v[216:219], v[72:75]
	v_mfma_f32_16x16x32_bf16 v[68:71], v[236:239], v[228:231], v[68:71]
	v_mfma_f32_16x16x32_bf16 v[64:67], v[244:247], v[228:231], v[64:67]
	s_setprio 0
	s_mov_b32 m0, s77
	v_lshl_add_u64 v[224:225], s[52:53], 0, v[146:147]
	s_barrier
	ds_read_b128 v[162:165], v194 offset:16384
	ds_read_b128 v[166:169], v194 offset:17408
	ds_read_b128 v[196:199], v194 offset:18432
	ds_read_b128 v[200:203], v194 offset:19456
	ds_read_b128 v[204:207], v194 offset:20480
	ds_read_b128 v[216:219], v194 offset:21504
	ds_read_b128 v[220:223], v194 offset:22528
	ds_read_b128 v[228:231], v194 offset:23552
	global_load_lds_dwordx4 v[224:225], off
	v_lshl_add_u64 v[248:249], s[52:53], 0, v[150:151]
	s_mov_b32 m0, s78
	s_nop 0
	global_load_lds_dwordx4 v[248:249], off
	s_barrier
	s_waitcnt lgkmcnt(0)
	s_setprio 1
	s_waitcnt lgkmcnt(0)
	v_mfma_f32_16x16x32_bf16 v[60:63], v[128:131], v[162:165], v[60:63]
	v_mfma_f32_16x16x32_bf16 v[56:59], v[136:139], v[162:165], v[56:59]
	v_mfma_f32_16x16x32_bf16 v[52:55], v[128:131], v[196:199], v[52:55]
	v_mfma_f32_16x16x32_bf16 v[48:51], v[136:139], v[196:199], v[48:51]
	v_mfma_f32_16x16x32_bf16 v[44:47], v[128:131], v[204:207], v[44:47]
	v_mfma_f32_16x16x32_bf16 v[40:43], v[136:139], v[204:207], v[40:43]
	v_mfma_f32_16x16x32_bf16 v[36:39], v[128:131], v[220:223], v[36:39]
	v_mfma_f32_16x16x32_bf16 v[32:35], v[136:139], v[220:223], v[32:35]
	v_mfma_f32_16x16x32_bf16 v[60:63], v[132:135], v[166:169], v[60:63]
	v_mfma_f32_16x16x32_bf16 v[56:59], v[140:143], v[166:169], v[56:59]
	v_mfma_f32_16x16x32_bf16 v[52:55], v[132:135], v[200:203], v[52:55]
	v_mfma_f32_16x16x32_bf16 v[48:51], v[140:143], v[200:203], v[48:51]
	v_mfma_f32_16x16x32_bf16 v[44:47], v[132:135], v[216:219], v[44:47]
	v_mfma_f32_16x16x32_bf16 v[40:43], v[140:143], v[216:219], v[40:43]
	v_mfma_f32_16x16x32_bf16 v[36:39], v[132:135], v[228:231], v[36:39]
	v_mfma_f32_16x16x32_bf16 v[32:35], v[140:143], v[228:231], v[32:35]
	s_barrier
	s_setprio 0
	s_add_u32 s56, s50, 0x40000
	s_addc_u32 s57, s51, 0
	s_add_i32 s27, s27, s76
	v_lshl_add_u64 v[128:129], s[56:57], 0, v[148:149]
	s_mov_b32 m0, s27
	s_nop 0
	global_load_lds_dwordx4 v[128:129], off
	v_lshl_add_u64 v[128:129], s[56:57], 0, v[152:153]
	s_add_i32 m0, s27, 0x2000
	s_nop 0
	global_load_lds_dwordx4 v[128:129], off
	s_waitcnt vmcnt(6)
	s_setprio 1
	s_barrier
	v_mfma_f32_16x16x32_bf16 v[28:31], v[232:235], v[162:165], v[28:31]
	v_mfma_f32_16x16x32_bf16 v[24:27], v[240:243], v[162:165], v[24:27]
	v_mfma_f32_16x16x32_bf16 v[20:23], v[232:235], v[196:199], v[20:23]
	v_mfma_f32_16x16x32_bf16 v[16:19], v[240:243], v[196:199], v[16:19]
	v_mfma_f32_16x16x32_bf16 v[12:15], v[232:235], v[204:207], v[12:15]
	v_mfma_f32_16x16x32_bf16 v[8:11], v[240:243], v[204:207], v[8:11]
	v_mfma_f32_16x16x32_bf16 v[4:7], v[232:235], v[220:223], v[4:7]
	v_mfma_f32_16x16x32_bf16 v[0:3], v[240:243], v[220:223], v[0:3]
	v_mfma_f32_16x16x32_bf16 v[28:31], v[236:239], v[166:169], v[28:31]
	v_mfma_f32_16x16x32_bf16 v[24:27], v[244:247], v[166:169], v[24:27]
	v_mfma_f32_16x16x32_bf16 v[20:23], v[236:239], v[200:203], v[20:23]
	v_mfma_f32_16x16x32_bf16 v[16:19], v[244:247], v[200:203], v[16:19]
	v_mfma_f32_16x16x32_bf16 v[12:15], v[236:239], v[216:219], v[12:15]
	v_mfma_f32_16x16x32_bf16 v[8:11], v[244:247], v[216:219], v[8:11]
	v_mfma_f32_16x16x32_bf16 v[4:7], v[236:239], v[228:231], v[4:7]
	v_mfma_f32_16x16x32_bf16 v[0:3], v[244:247], v[228:231], v[0:3]
	s_setprio 0
	s_add_i32 s27, 0, 0x18000
	v_add_u32_e32 v140, s27, v192
	s_barrier
	ds_read_b128 v[128:131], v140
	ds_read_b128 v[132:135], v140 offset:1024
	ds_read_b128 v[136:139], v140 offset:2048
	ds_read_b128 v[140:143], v140 offset:3072
	s_add_u32 s52, s52, 0x40000
	s_addc_u32 s53, s53, 0
	s_mov_b32 m0, s81
	v_lshl_add_u64 v[232:233], s[52:53], 0, v[146:147]
	ds_read_b128 v[162:165], v194 offset:32768
	ds_read_b128 v[166:169], v194 offset:33792
	ds_read_b128 v[196:199], v194 offset:34816
	ds_read_b128 v[200:203], v194 offset:35840
	ds_read_b128 v[204:207], v194 offset:36864
	ds_read_b128 v[216:219], v194 offset:37888
	ds_read_b128 v[220:223], v194 offset:38912
	ds_read_b128 v[228:231], v194 offset:39936
	global_load_lds_dwordx4 v[232:233], off
	v_lshl_add_u64 v[232:233], s[52:53], 0, v[150:151]
	s_mov_b32 m0, s82
	s_nop 0
	global_load_lds_dwordx4 v[232:233], off
	s_waitcnt lgkmcnt(8)
	s_barrier
	s_waitcnt lgkmcnt(0)
	s_setprio 1
	s_waitcnt lgkmcnt(0)
	v_mfma_f32_16x16x32_bf16 v[124:127], v[128:131], v[162:165], v[124:127]
	v_mfma_f32_16x16x32_bf16 v[120:123], v[136:139], v[162:165], v[120:123]
	v_mfma_f32_16x16x32_bf16 v[116:119], v[128:131], v[196:199], v[116:119]
	v_mfma_f32_16x16x32_bf16 v[112:115], v[136:139], v[196:199], v[112:115]
	v_mfma_f32_16x16x32_bf16 v[108:111], v[128:131], v[204:207], v[108:111]
	v_mfma_f32_16x16x32_bf16 v[104:107], v[136:139], v[204:207], v[104:107]
	v_mfma_f32_16x16x32_bf16 v[100:103], v[128:131], v[220:223], v[100:103]
	v_mfma_f32_16x16x32_bf16 v[96:99], v[136:139], v[220:223], v[96:99]
	v_mfma_f32_16x16x32_bf16 v[124:127], v[132:135], v[166:169], v[124:127]
	v_mfma_f32_16x16x32_bf16 v[120:123], v[140:143], v[166:169], v[120:123]
	v_mfma_f32_16x16x32_bf16 v[116:119], v[132:135], v[200:203], v[116:119]
	v_mfma_f32_16x16x32_bf16 v[112:115], v[140:143], v[200:203], v[112:115]
	v_mfma_f32_16x16x32_bf16 v[108:111], v[132:135], v[216:219], v[108:111]
	v_mfma_f32_16x16x32_bf16 v[104:107], v[140:143], v[216:219], v[104:107]
	v_mfma_f32_16x16x32_bf16 v[100:103], v[132:135], v[228:231], v[100:103]
	v_mfma_f32_16x16x32_bf16 v[96:99], v[140:143], v[228:231], v[96:99]
	s_barrier
	s_setprio 0
	s_add_i32 s37, 0, 0x1c000
	s_add_i32 s27, s27, s76
	v_add_u32_e32 v161, s37, v192
	v_lshl_add_u64 v[176:177], v[176:177], 0, s[18:19]
	s_mov_b32 m0, s27
	ds_read_b128 v[232:235], v161
	ds_read_b128 v[236:239], v161 offset:1024
	ds_read_b128 v[240:243], v161 offset:2048
	ds_read_b128 v[244:247], v161 offset:3072
	global_load_lds_dwordx4 v[176:177], off
	v_lshl_add_u64 v[176:177], v[188:189], 0, s[18:19]
	s_add_i32 m0, s27, 0x2000
	s_nop 0
	global_load_lds_dwordx4 v[176:177], off
	s_barrier
	s_waitcnt lgkmcnt(0)
	s_setprio 1
	s_waitcnt lgkmcnt(0)
	v_mfma_f32_16x16x32_bf16 v[92:95], v[232:235], v[162:165], v[92:95]
	v_mfma_f32_16x16x32_bf16 v[88:91], v[240:243], v[162:165], v[88:91]
	v_mfma_f32_16x16x32_bf16 v[84:87], v[232:235], v[196:199], v[84:87]
	v_mfma_f32_16x16x32_bf16 v[80:83], v[240:243], v[196:199], v[80:83]
	v_mfma_f32_16x16x32_bf16 v[76:79], v[232:235], v[204:207], v[76:79]
	v_mfma_f32_16x16x32_bf16 v[72:75], v[240:243], v[204:207], v[72:75]
	v_mfma_f32_16x16x32_bf16 v[68:71], v[232:235], v[220:223], v[68:71]
	v_mfma_f32_16x16x32_bf16 v[64:67], v[240:243], v[220:223], v[64:67]
	v_mfma_f32_16x16x32_bf16 v[92:95], v[236:239], v[166:169], v[92:95]
	v_mfma_f32_16x16x32_bf16 v[88:91], v[244:247], v[166:169], v[88:91]
	v_mfma_f32_16x16x32_bf16 v[84:87], v[236:239], v[200:203], v[84:87]
	v_mfma_f32_16x16x32_bf16 v[80:83], v[244:247], v[200:203], v[80:83]
	v_mfma_f32_16x16x32_bf16 v[76:79], v[236:239], v[216:219], v[76:79]
	v_mfma_f32_16x16x32_bf16 v[72:75], v[244:247], v[216:219], v[72:75]
	v_mfma_f32_16x16x32_bf16 v[68:71], v[236:239], v[228:231], v[68:71]
	v_mfma_f32_16x16x32_bf16 v[64:67], v[244:247], v[228:231], v[64:67]
	s_setprio 0
	s_mov_b32 m0, s80
	v_lshl_add_u64 v[176:177], v[224:225], 0, s[18:19]
	s_barrier
	ds_read_b128 v[162:165], v194 offset:49152
	ds_read_b128 v[166:169], v194 offset:50176
	ds_read_b128 v[196:199], v194 offset:51200
	ds_read_b128 v[200:203], v194 offset:52224
	ds_read_b128 v[204:207], v194 offset:53248
	ds_read_b128 v[216:219], v194 offset:54272
	ds_read_b128 v[220:223], v194 offset:55296
	ds_read_b128 v[228:231], v194 offset:56320
	global_load_lds_dwordx4 v[176:177], off
	v_lshl_add_u64 v[176:177], v[248:249], 0, s[18:19]
	s_mov_b32 m0, s83
	s_nop 0
	global_load_lds_dwordx4 v[176:177], off
	s_barrier
	s_waitcnt lgkmcnt(0)
	s_setprio 1
	s_waitcnt lgkmcnt(0)
	v_mfma_f32_16x16x32_bf16 v[60:63], v[128:131], v[162:165], v[60:63]
	v_mfma_f32_16x16x32_bf16 v[56:59], v[136:139], v[162:165], v[56:59]
	v_mfma_f32_16x16x32_bf16 v[52:55], v[128:131], v[196:199], v[52:55]
	v_mfma_f32_16x16x32_bf16 v[48:51], v[136:139], v[196:199], v[48:51]
	v_mfma_f32_16x16x32_bf16 v[44:47], v[128:131], v[204:207], v[44:47]
	v_mfma_f32_16x16x32_bf16 v[40:43], v[136:139], v[204:207], v[40:43]
	v_mfma_f32_16x16x32_bf16 v[36:39], v[128:131], v[220:223], v[36:39]
	v_mfma_f32_16x16x32_bf16 v[32:35], v[136:139], v[220:223], v[32:35]
	v_mfma_f32_16x16x32_bf16 v[60:63], v[132:135], v[166:169], v[60:63]
	v_mfma_f32_16x16x32_bf16 v[56:59], v[140:143], v[166:169], v[56:59]
	v_mfma_f32_16x16x32_bf16 v[52:55], v[132:135], v[200:203], v[52:55]
	v_mfma_f32_16x16x32_bf16 v[48:51], v[140:143], v[200:203], v[48:51]
	v_mfma_f32_16x16x32_bf16 v[44:47], v[132:135], v[216:219], v[44:47]
	v_mfma_f32_16x16x32_bf16 v[40:43], v[140:143], v[216:219], v[40:43]
	v_mfma_f32_16x16x32_bf16 v[36:39], v[132:135], v[228:231], v[36:39]
	v_mfma_f32_16x16x32_bf16 v[32:35], v[140:143], v[228:231], v[32:35]
	s_barrier
	s_setprio 0
	s_add_u32 s50, s50, 0x40080
	s_addc_u32 s51, s51, 0
	s_add_i32 s27, s37, s76
	v_lshl_add_u64 v[128:129], s[50:51], 0, v[148:149]
	s_mov_b32 m0, s27
	s_nop 0
	global_load_lds_dwordx4 v[128:129], off
	v_lshl_add_u64 v[128:129], s[50:51], 0, v[152:153]
	s_add_i32 m0, s27, 0x2000
	s_nop 0
	global_load_lds_dwordx4 v[128:129], off
	s_waitcnt vmcnt(6)
	s_setprio 1
	s_barrier
	v_mfma_f32_16x16x32_bf16 v[28:31], v[232:235], v[162:165], v[28:31]
	v_mfma_f32_16x16x32_bf16 v[24:27], v[240:243], v[162:165], v[24:27]
	v_mfma_f32_16x16x32_bf16 v[20:23], v[232:235], v[196:199], v[20:23]
	v_mfma_f32_16x16x32_bf16 v[16:19], v[240:243], v[196:199], v[16:19]
	v_mfma_f32_16x16x32_bf16 v[12:15], v[232:235], v[204:207], v[12:15]
	v_mfma_f32_16x16x32_bf16 v[8:11], v[240:243], v[204:207], v[8:11]
	v_mfma_f32_16x16x32_bf16 v[4:7], v[232:235], v[220:223], v[4:7]
	v_mfma_f32_16x16x32_bf16 v[0:3], v[240:243], v[220:223], v[0:3]
	v_mfma_f32_16x16x32_bf16 v[28:31], v[236:239], v[166:169], v[28:31]
	v_mfma_f32_16x16x32_bf16 v[24:27], v[244:247], v[166:169], v[24:27]
	v_mfma_f32_16x16x32_bf16 v[20:23], v[236:239], v[200:203], v[20:23]
	v_mfma_f32_16x16x32_bf16 v[16:19], v[244:247], v[200:203], v[16:19]
	v_mfma_f32_16x16x32_bf16 v[12:15], v[236:239], v[216:219], v[12:15]
	v_mfma_f32_16x16x32_bf16 v[8:11], v[244:247], v[216:219], v[8:11]
	v_mfma_f32_16x16x32_bf16 v[4:7], v[236:239], v[228:231], v[4:7]
	v_mfma_f32_16x16x32_bf16 v[0:3], v[244:247], v[228:231], v[0:3]
	s_setprio 0
	s_add_i32 s36, s36, 2
	s_add_u32 s0, s0, 0x100
	s_addc_u32 s1, s1, 0
	s_add_u32 s34, s34, 0x100
	s_addc_u32 s35, s35, 0
	s_cmp_gt_u32 s36, 13
	s_barrier
	s_cbranch_scc0 .LBB0_351
	s_lshl_b32 s0, s11, 8
	s_or_b32 s50, s0, s79
	s_ashr_i32 s51, s50, 31
	v_lshl_add_u64 v[140:141], s[50:51], 3, v[154:155]
	global_load_dwordx4 v[128:131], v[140:141], off offset:48
	global_load_dwordx4 v[132:135], v[140:141], off offset:32
	global_load_dwordx4 v[136:139], v[140:141], off offset:16
	global_load_dwordx4 v[162:165], v[140:141], off
	s_mov_b32 s34, 0x35800000
	s_mov_b32 s0, 0x358637bd
	v_mov_b64_e32 v[168:169], s[0:1]
	s_mov_b32 s30, 0x45800000
	s_cmp_lt_u32 s10, 2
	s_waitcnt vmcnt(0)
	v_ffbh_u32_e32 v142, v165
	v_min_u32_e32 v161, 32, v142
	v_lshlrev_b64 v[142:143], v161, v[164:165]
	v_min_u32_e32 v142, 1, v142
	v_or_b32_e32 v142, v143, v142
	v_cvt_f32_u32_e32 v142, v142
	v_sub_u32_e32 v143, 32, v161
	v_ldexp_f32 v143, v142, v143
	v_ffbh_u32_e32 v142, v163
	v_min_u32_e32 v142, 32, v142
	v_lshlrev_b64 v[162:163], v142, v[162:163]
	v_min_u32_e32 v161, 1, v162
	v_or_b32_e32 v161, v163, v161
	v_cvt_f32_u32_e32 v161, v161
	v_sub_u32_e32 v142, 32, v142
	v_ldexp_f32 v142, v161, v142
	v_pk_mul_f32 v[142:143], v[142:143], s[34:35] op_sel_hi:[1,0]
	s_nop 0
	v_pk_fma_f32 v[142:143], v[142:143], s[2:3], v[168:169] op_sel_hi:[1,0,0]
	s_nop 0
	v_mul_f32_e32 v161, 0x4b800000, v142
	v_cmp_gt_f32_e64 s[0:1], s89, v142
	v_cmp_gt_f32_e32 vcc, s89, v143
	s_nop 0
	v_cndmask_b32_e64 v142, v142, v161, s[0:1]
	v_mul_f32_e32 v161, 0x4b800000, v143
	v_cndmask_b32_e32 v143, v143, v161, vcc
	v_rsq_f32_e32 v142, v142
	v_rsq_f32_e32 v143, v143
	s_nop 0
	v_pk_mul_f32 v[162:163], v[142:143], s[30:31] op_sel_hi:[1,0]
	s_nop 0
	v_cndmask_b32_e64 v166, v142, v162, s[0:1]
	v_ffbh_u32_e32 v142, v139
	v_min_u32_e32 v142, 32, v142
	v_lshlrev_b64 v[138:139], v142, v[138:139]
	v_min_u32_e32 v138, 1, v138
	v_or_b32_e32 v138, v139, v138
	v_cvt_f32_u32_e32 v138, v138
	v_sub_u32_e32 v139, 32, v142
	v_cndmask_b32_e32 v167, v143, v163, vcc
	v_pk_mul_f32 v[60:61], v[60:61], v[166:167]
	v_ldexp_f32 v139, v138, v139
	v_ffbh_u32_e32 v138, v137
	v_min_u32_e32 v138, 32, v138
	v_lshlrev_b64 v[136:137], v138, v[136:137]
	v_min_u32_e32 v136, 1, v136
	v_or_b32_e32 v136, v137, v136
	v_cvt_f32_u32_e32 v136, v136
	v_sub_u32_e32 v137, 32, v138
	v_pk_mul_f32 v[52:53], v[52:53], v[166:167]
	v_pk_mul_f32 v[44:45], v[44:45], v[166:167]
	v_ldexp_f32 v138, v136, v137
	v_pk_mul_f32 v[136:137], v[138:139], s[34:35] op_sel_hi:[1,0]
	v_pk_mul_f32 v[36:37], v[36:37], v[166:167]
	v_pk_fma_f32 v[136:137], v[136:137], s[2:3], v[168:169] op_sel_hi:[1,0,0]
	s_nop 0
	v_mul_f32_e32 v138, 0x4b800000, v136
	v_cmp_gt_f32_e64 s[0:1], s89, v136
	v_cmp_gt_f32_e32 vcc, s89, v137
	s_nop 0
	v_cndmask_b32_e64 v136, v136, v138, s[0:1]
	v_mul_f32_e32 v138, 0x4b800000, v137
	v_cndmask_b32_e32 v137, v137, v138, vcc
	v_rsq_f32_e32 v136, v136
	v_rsq_f32_e32 v137, v137
	s_nop 0
	v_pk_mul_f32 v[138:139], v[136:137], s[30:31] op_sel_hi:[1,0]
	s_nop 0
	v_cndmask_b32_e64 v162, v136, v138, s[0:1]
	v_ffbh_u32_e32 v136, v135
	v_min_u32_e32 v136, 32, v136
	v_lshlrev_b64 v[134:135], v136, v[134:135]
	v_min_u32_e32 v134, 1, v134
	v_or_b32_e32 v134, v135, v134
	v_cvt_f32_u32_e32 v134, v134
	v_sub_u32_e32 v135, 32, v136
	v_cndmask_b32_e32 v163, v137, v139, vcc
	v_ldexp_f32 v135, v134, v135
	v_ffbh_u32_e32 v134, v133
	v_min_u32_e32 v134, 32, v134
	v_lshlrev_b64 v[132:133], v134, v[132:133]
	v_min_u32_e32 v132, 1, v132
	v_or_b32_e32 v132, v133, v132
	v_cvt_f32_u32_e32 v132, v132
	v_sub_u32_e32 v133, 32, v134
	v_ldexp_f32 v134, v132, v133
	v_pk_mul_f32 v[132:133], v[134:135], s[34:35] op_sel_hi:[1,0]
	s_nop 0
	v_pk_fma_f32 v[132:133], v[132:133], s[2:3], v[168:169] op_sel_hi:[1,0,0]
	s_nop 0
	v_mul_f32_e32 v134, 0x4b800000, v132
	v_cmp_gt_f32_e64 s[0:1], s89, v132
	v_cmp_gt_f32_e32 vcc, s89, v133
	s_nop 0
	v_cndmask_b32_e64 v132, v132, v134, s[0:1]
	v_mul_f32_e32 v134, 0x4b800000, v133
	v_cndmask_b32_e32 v133, v133, v134, vcc
	v_rsq_f32_e32 v132, v132
	v_rsq_f32_e32 v133, v133
	s_nop 0
	v_pk_mul_f32 v[134:135], v[132:133], s[30:31] op_sel_hi:[1,0]
	s_nop 0
	v_cndmask_b32_e64 v188, v132, v134, s[0:1]
	v_ffbh_u32_e32 v132, v131
	v_min_u32_e32 v132, 32, v132
	v_lshlrev_b64 v[130:131], v132, v[130:131]
	v_min_u32_e32 v130, 1, v130
	v_or_b32_e32 v130, v131, v130
	v_cvt_f32_u32_e32 v130, v130
	v_sub_u32_e32 v131, 32, v132
	v_cndmask_b32_e32 v189, v133, v135, vcc
	v_pk_mul_f32 v[56:57], v[56:57], v[188:189]
	v_ldexp_f32 v131, v130, v131
	v_ffbh_u32_e32 v130, v129
	v_min_u32_e32 v130, 32, v130
	v_lshlrev_b64 v[128:129], v130, v[128:129]
	v_min_u32_e32 v128, 1, v128
	v_or_b32_e32 v128, v129, v128
	v_cvt_f32_u32_e32 v128, v128
	v_sub_u32_e32 v129, 32, v130
	v_pk_mul_f32 v[48:49], v[48:49], v[188:189]
	v_pk_mul_f32 v[40:41], v[40:41], v[188:189]
	v_ldexp_f32 v130, v128, v129
	v_pk_mul_f32 v[128:129], v[130:131], s[34:35] op_sel_hi:[1,0]
	v_pk_mul_f32 v[32:33], v[32:33], v[188:189]
	v_pk_fma_f32 v[128:129], v[128:129], s[2:3], v[168:169] op_sel_hi:[1,0,0]
	s_nop 0
	v_mul_f32_e32 v130, 0x4b800000, v128
	v_cmp_gt_f32_e64 s[0:1], s89, v128
	v_cmp_gt_f32_e32 vcc, s89, v129
	s_nop 0
	v_cndmask_b32_e64 v128, v128, v130, s[0:1]
	v_mul_f32_e32 v130, 0x4b800000, v129
	v_cndmask_b32_e32 v129, v129, v130, vcc
	v_rsq_f32_e32 v128, v128
	v_rsq_f32_e32 v129, v129
	s_nop 0
	v_pk_mul_f32 v[130:131], v[128:129], s[30:31] op_sel_hi:[1,0]
	s_nop 0
	v_cndmask_b32_e32 v165, v129, v131, vcc
	v_cndmask_b32_e64 v164, v128, v130, s[0:1]
	global_load_dwordx4 v[128:131], v[140:141], off offset:1072
	global_load_dwordx4 v[132:135], v[140:141], off offset:1056
	global_load_dwordx4 v[136:139], v[140:141], off offset:1040
	s_nop 0
	global_load_dwordx4 v[140:143], v[140:141], off offset:1024
	s_waitcnt vmcnt(0)
	v_ffbh_u32_e32 v161, v143
	v_min_u32_e32 v161, 32, v161
	v_lshlrev_b64 v[142:143], v161, v[142:143]
	v_min_u32_e32 v142, 1, v142
	v_or_b32_e32 v142, v143, v142
	v_cvt_f32_u32_e32 v142, v142
	v_sub_u32_e32 v143, 32, v161
	v_ldexp_f32 v143, v142, v143
	v_ffbh_u32_e32 v142, v141
	v_min_u32_e32 v142, 32, v142
	v_lshlrev_b64 v[140:141], v142, v[140:141]
	v_min_u32_e32 v140, 1, v140
	v_or_b32_e32 v140, v141, v140
	v_cvt_f32_u32_e32 v140, v140
	v_sub_u32_e32 v141, 32, v142
	v_ldexp_f32 v142, v140, v141
	v_pk_mul_f32 v[140:141], v[142:143], s[34:35] op_sel_hi:[1,0]
	s_nop 0
	v_pk_fma_f32 v[140:141], v[140:141], s[2:3], v[168:169] op_sel_hi:[1,0,0]
	s_nop 0
	v_mul_f32_e32 v142, 0x4b800000, v140
	v_cmp_gt_f32_e64 s[0:1], s89, v140
	v_cmp_gt_f32_e32 vcc, s89, v141
	s_nop 0
	v_cndmask_b32_e64 v140, v140, v142, s[0:1]
	v_mul_f32_e32 v142, 0x4b800000, v141
	v_cndmask_b32_e32 v141, v141, v142, vcc
	v_rsq_f32_e32 v140, v140
	v_rsq_f32_e32 v141, v141
	s_nop 0
	v_pk_mul_f32 v[142:143], v[140:141], s[30:31] op_sel_hi:[1,0]
	s_nop 0
	v_cndmask_b32_e64 v142, v140, v142, s[0:1]
	v_ffbh_u32_e32 v140, v139
	v_min_u32_e32 v140, 32, v140
	v_lshlrev_b64 v[138:139], v140, v[138:139]
	v_min_u32_e32 v138, 1, v138
	v_or_b32_e32 v138, v139, v138
	v_cvt_f32_u32_e32 v138, v138
	v_sub_u32_e32 v139, 32, v140
	v_cndmask_b32_e32 v143, v141, v143, vcc
	v_pk_mul_f32 v[140:141], v[124:125], v[166:167]
	v_ldexp_f32 v139, v138, v139
	v_ffbh_u32_e32 v138, v137
	v_min_u32_e32 v138, 32, v138
	v_lshlrev_b64 v[136:137], v138, v[136:137]
	v_min_u32_e32 v136, 1, v136
	v_or_b32_e32 v136, v137, v136
	v_cvt_f32_u32_e32 v136, v136
	v_sub_u32_e32 v137, 32, v138
	v_pk_mul_f32 v[28:29], v[28:29], v[142:143]
	v_pk_mul_f32 v[20:21], v[20:21], v[142:143]
	v_ldexp_f32 v138, v136, v137
	v_pk_mul_f32 v[136:137], v[138:139], s[34:35] op_sel_hi:[1,0]
	v_pk_mul_f32 v[12:13], v[12:13], v[142:143]
	v_pk_fma_f32 v[136:137], v[136:137], s[2:3], v[168:169] op_sel_hi:[1,0,0]
	v_pk_mul_f32 v[4:5], v[4:5], v[142:143]
	v_mul_f32_e32 v138, 0x4b800000, v136
	v_cmp_gt_f32_e64 s[0:1], s89, v136
	v_cmp_gt_f32_e32 vcc, s89, v137
	s_nop 0
	v_cndmask_b32_e64 v136, v136, v138, s[0:1]
	v_mul_f32_e32 v138, 0x4b800000, v137
	v_cndmask_b32_e32 v137, v137, v138, vcc
	v_rsq_f32_e32 v136, v136
	v_rsq_f32_e32 v137, v137
	s_nop 0
	v_pk_mul_f32 v[138:139], v[136:137], s[30:31] op_sel_hi:[1,0]
	s_nop 0
	v_cndmask_b32_e64 v136, v136, v138, s[0:1]
	v_ffbh_u32_e32 v138, v135
	v_min_u32_e32 v138, 32, v138
	v_lshlrev_b64 v[134:135], v138, v[134:135]
	v_min_u32_e32 v134, 1, v134
	v_or_b32_e32 v134, v135, v134
	v_cvt_f32_u32_e32 v134, v134
	v_sub_u32_e32 v135, 32, v138
	v_cndmask_b32_e32 v137, v137, v139, vcc
	v_pk_mul_f32 v[138:139], v[120:121], v[188:189]
	v_ldexp_f32 v135, v134, v135
	v_ffbh_u32_e32 v134, v133
	v_min_u32_e32 v134, 32, v134
	v_lshlrev_b64 v[132:133], v134, v[132:133]
	v_min_u32_e32 v132, 1, v132
	v_or_b32_e32 v132, v133, v132
	v_cvt_f32_u32_e32 v132, v132
	v_sub_u32_e32 v133, 32, v134
	v_pk_mul_f32 v[120:121], v[84:85], v[142:143]
	v_ldexp_f32 v134, v132, v133
	v_pk_mul_f32 v[132:133], v[134:135], s[34:35] op_sel_hi:[1,0]
	s_nop 0
	v_pk_fma_f32 v[132:133], v[132:133], s[2:3], v[168:169] op_sel_hi:[1,0,0]
	s_nop 0
	v_mul_f32_e32 v134, 0x4b800000, v132
	v_cmp_gt_f32_e64 s[0:1], s89, v132
	v_cmp_gt_f32_e32 vcc, s89, v133
	s_nop 0
	v_cndmask_b32_e64 v132, v132, v134, s[0:1]
	v_mul_f32_e32 v134, 0x4b800000, v133
	v_cndmask_b32_e32 v133, v133, v134, vcc
	v_rsq_f32_e32 v132, v132
	v_rsq_f32_e32 v133, v133
	s_nop 0
	v_pk_mul_f32 v[134:135], v[132:133], s[30:31] op_sel_hi:[1,0]
	s_nop 0
	v_cndmask_b32_e64 v176, v132, v134, s[0:1]
	v_ffbh_u32_e32 v132, v131
	v_min_u32_e32 v132, 32, v132
	v_lshlrev_b64 v[130:131], v132, v[130:131]
	v_min_u32_e32 v130, 1, v130
	v_or_b32_e32 v130, v131, v130
	v_cvt_f32_u32_e32 v130, v130
	v_sub_u32_e32 v131, 32, v132
	v_cndmask_b32_e32 v177, v133, v135, vcc
	v_pk_mul_f32 v[124:125], v[88:89], v[176:177]
	v_ldexp_f32 v131, v130, v131
	v_ffbh_u32_e32 v130, v129
	v_min_u32_e32 v130, 32, v130
	v_lshlrev_b64 v[128:129], v130, v[128:129]
	v_min_u32_e32 v128, 1, v128
	v_or_b32_e32 v128, v129, v128
	v_cvt_f32_u32_e32 v128, v128
	v_sub_u32_e32 v129, 32, v130
	v_pk_mul_f32 v[134:135], v[116:117], v[166:167]
	v_pk_mul_f32 v[132:133], v[112:113], v[188:189]
	v_ldexp_f32 v130, v128, v129
	v_pk_mul_f32 v[128:129], v[130:131], s[34:35] op_sel_hi:[1,0]
	v_pk_mul_f32 v[116:117], v[80:81], v[176:177]
	v_pk_fma_f32 v[128:129], v[128:129], s[2:3], v[168:169] op_sel_hi:[1,0,0]
	v_pk_mul_f32 v[88:89], v[104:105], v[188:189]
	v_mul_f32_e32 v130, 0x4b800000, v128
	v_cmp_gt_f32_e64 s[0:1], s89, v128
	v_cmp_gt_f32_e32 vcc, s89, v129
	v_pk_mul_f32 v[112:113], v[76:77], v[142:143]
	v_cndmask_b32_e64 v128, v128, v130, s[0:1]
	v_mul_f32_e32 v130, 0x4b800000, v129
	v_cndmask_b32_e32 v129, v129, v130, vcc
	v_rsq_f32_e32 v128, v128
	v_rsq_f32_e32 v129, v129
	v_pk_mul_f32 v[76:77], v[100:101], v[166:167]
	v_pk_mul_f32 v[104:105], v[68:69], v[142:143]
	v_pk_mul_f32 v[24:25], v[24:25], v[176:177]
	v_pk_mul_f32 v[130:131], v[128:129], s[30:31] op_sel_hi:[1,0]
	v_pk_mul_f32 v[16:17], v[16:17], v[176:177]
	v_cndmask_b32_e32 v129, v129, v131, vcc
	v_cndmask_b32_e64 v128, v128, v130, s[0:1]
	s_mov_b64 s[0:1], -1
	v_pk_mul_f32 v[130:131], v[92:93], v[142:143]
	v_pk_mul_f32 v[92:93], v[108:109], v[166:167]
	v_pk_mul_f32 v[108:109], v[72:73], v[176:177]
	v_pk_mul_f32 v[72:73], v[96:97], v[188:189]
	v_pk_mul_f32 v[96:97], v[64:65], v[176:177]
	v_pk_mul_f32 v[8:9], v[8:9], v[176:177]
	v_pk_mul_f32 v[0:1], v[0:1], v[176:177]
	s_cbranch_scc1 .LBB0_354
	v_lshl_add_u32 v68, s10, 8, v193
	v_ashrrev_i32_e32 v69, 31, v68
	v_pk_mul_f32 v[64:65], v[126:127], v[162:163]
	v_cvt_pk_bf16_f32 v80, v140, v141
	s_lshl_b64 s[0:1], s[50:51], 1
	v_cvt_pk_bf16_f32 v81, v64, v65
	v_lshlrev_b64 v[64:65], 13, v[68:69]
	v_lshl_add_u64 v[64:65], s[44:45], 0, v[64:65]
	v_lshl_add_u64 v[64:65], v[64:65], 0, s[0:1]
	v_lshl_add_u64 v[64:65], v[64:65], 0, v[144:145]
	v_mov_b32_e32 v161, v145
	v_lshl_add_u64 v[64:65], v[64:65], 0, v[160:161]
	global_store_dwordx2 v[64:65], v[80:81], off
	v_pk_mul_f32 v[80:81], v[122:123], v[164:165]
	v_cvt_pk_bf16_f32 v84, v138, v139
	s_nop 0
	v_cvt_pk_bf16_f32 v85, v80, v81
	v_pk_mul_f32 v[80:81], v[94:95], v[136:137]
	global_store_dwordx2 v[64:65], v[84:85], off offset:16
	v_cvt_pk_bf16_f32 v84, v130, v131
	v_cvt_pk_bf16_f32 v85, v80, v81
	v_pk_mul_f32 v[80:81], v[90:91], v[128:129]
	global_store_dwordx2 v[64:65], v[84:85], off offset:256
	v_cvt_pk_bf16_f32 v84, v124, v125
	v_cvt_pk_bf16_f32 v85, v80, v81
	v_or_b32_e32 v80, 16, v68
	v_ashrrev_i32_e32 v81, 31, v80
	v_lshlrev_b64 v[80:81], 13, v[80:81]
	v_lshl_add_u64 v[80:81], s[44:45], 0, v[80:81]
	v_lshl_add_u64 v[80:81], v[80:81], 0, s[0:1]
	v_lshl_add_u64 v[80:81], v[80:81], 0, v[144:145]
	global_store_dwordx2 v[64:65], v[84:85], off offset:272
	v_pk_mul_f32 v[84:85], v[118:119], v[162:163]
	v_cvt_pk_bf16_f32 v100, v134, v135
	v_lshl_add_u64 v[80:81], v[80:81], 0, v[160:161]
	v_cvt_pk_bf16_f32 v101, v84, v85
	global_store_dwordx2 v[80:81], v[100:101], off
	v_pk_mul_f32 v[84:85], v[114:115], v[164:165]
	v_cvt_pk_bf16_f32 v100, v132, v133
	s_nop 0
	v_cvt_pk_bf16_f32 v101, v84, v85
	global_store_dwordx2 v[80:81], v[100:101], off offset:16
	v_pk_mul_f32 v[84:85], v[86:87], v[136:137]
	v_cvt_pk_bf16_f32 v100, v120, v121
	s_nop 0
	v_cvt_pk_bf16_f32 v101, v84, v85
	global_store_dwordx2 v[80:81], v[100:101], off offset:256
	v_pk_mul_f32 v[84:85], v[82:83], v[128:129]
	v_cvt_pk_bf16_f32 v100, v116, v117
	s_nop 0
	v_cvt_pk_bf16_f32 v101, v84, v85
	global_store_dwordx2 v[80:81], v[100:101], off offset:272
	v_or_b32_e32 v80, 32, v68
	v_ashrrev_i32_e32 v81, 31, v80
	v_lshlrev_b64 v[80:81], 13, v[80:81]
	v_lshl_add_u64 v[80:81], s[44:45], 0, v[80:81]
	v_or_b32_e32 v68, 48, v68
	v_lshl_add_u64 v[80:81], v[80:81], 0, s[0:1]
	v_ashrrev_i32_e32 v69, 31, v68
	v_pk_mul_f32 v[84:85], v[110:111], v[162:163]
	v_lshl_add_u64 v[80:81], v[80:81], 0, v[144:145]
	v_lshlrev_b64 v[68:69], 13, v[68:69]
	v_cvt_pk_bf16_f32 v100, v92, v93
	v_cvt_pk_bf16_f32 v101, v84, v85
	v_lshl_add_u64 v[80:81], v[80:81], 0, v[160:161]
	v_pk_mul_f32 v[84:85], v[106:107], v[164:165]
	v_lshl_add_u64 v[68:69], s[44:45], 0, v[68:69]
	global_store_dwordx2 v[80:81], v[100:101], off
	v_cvt_pk_bf16_f32 v100, v88, v89
	v_cvt_pk_bf16_f32 v101, v84, v85
	v_pk_mul_f32 v[84:85], v[78:79], v[136:137]
	v_lshl_add_u64 v[68:69], v[68:69], 0, s[0:1]
	global_store_dwordx2 v[80:81], v[100:101], off offset:16
	v_cvt_pk_bf16_f32 v100, v112, v113
	v_cvt_pk_bf16_f32 v101, v84, v85
	v_pk_mul_f32 v[84:85], v[74:75], v[128:129]
	v_lshl_add_u64 v[68:69], v[68:69], 0, v[144:145]
	global_store_dwordx2 v[80:81], v[100:101], off offset:256
	v_cvt_pk_bf16_f32 v100, v108, v109
	v_cvt_pk_bf16_f32 v101, v84, v85
	global_store_dwordx2 v[80:81], v[100:101], off offset:272
	v_cvt_pk_bf16_f32 v84, v76, v77
	v_lshl_add_u64 v[68:69], v[68:69], 0, v[160:161]
	v_pk_mul_f32 v[80:81], v[102:103], v[162:163]
	s_mov_b64 s[0:1], 0x100000
	v_cvt_pk_bf16_f32 v85, v80, v81
	global_store_dwordx2 v[68:69], v[84:85], off
	v_cvt_pk_bf16_f32 v84, v72, v73
	v_pk_mul_f32 v[80:81], v[98:99], v[164:165]
	s_nop 0
	v_cvt_pk_bf16_f32 v85, v80, v81
	global_store_dwordx2 v[68:69], v[84:85], off offset:16
	v_cvt_pk_bf16_f32 v84, v104, v105
	v_pk_mul_f32 v[80:81], v[70:71], v[136:137]
	s_nop 0
	v_cvt_pk_bf16_f32 v85, v80, v81
	global_store_dwordx2 v[68:69], v[84:85], off offset:256
	v_cvt_pk_bf16_f32 v84, v96, v97
	v_pk_mul_f32 v[80:81], v[66:67], v[128:129]
	s_nop 0
	v_cvt_pk_bf16_f32 v85, v80, v81
	global_store_dwordx2 v[68:69], v[84:85], off offset:272
	v_add_co_u32_e32 v84, vcc, s29, v64
	v_pk_mul_f32 v[68:69], v[62:63], v[162:163]
	s_nop 0
	v_addc_co_u32_e32 v85, vcc, 0, v65, vcc
	v_cvt_pk_bf16_f32 v80, v60, v61
	v_cvt_pk_bf16_f32 v81, v68, v69
	v_lshl_add_u64 v[68:69], v[64:65], 0, s[0:1]
	global_store_dwordx2 v[84:85], v[80:81], off
	v_cvt_pk_bf16_f32 v84, v56, v57
	v_pk_mul_f32 v[80:81], v[58:59], v[164:165]
	s_mov_b64 s[0:1], 0x120000
	v_cvt_pk_bf16_f32 v85, v80, v81
	global_store_dwordx2 v[68:69], v[84:85], off offset:16
	v_cvt_pk_bf16_f32 v84, v28, v29
	v_pk_mul_f32 v[80:81], v[30:31], v[136:137]
	s_nop 0
	v_cvt_pk_bf16_f32 v85, v80, v81
	global_store_dwordx2 v[68:69], v[84:85], off offset:256
	v_cvt_pk_bf16_f32 v84, v24, v25
	v_pk_mul_f32 v[80:81], v[26:27], v[128:129]
	s_nop 0
	v_cvt_pk_bf16_f32 v85, v80, v81
	global_store_dwordx2 v[68:69], v[84:85], off offset:272
	v_add_co_u32_e32 v84, vcc, s49, v64
	v_pk_mul_f32 v[68:69], v[54:55], v[162:163]
	v_cvt_pk_bf16_f32 v80, v52, v53
	s_nop 0
	v_addc_co_u32_e32 v85, vcc, 0, v65, vcc
	v_cvt_pk_bf16_f32 v81, v68, v69
	v_lshl_add_u64 v[68:69], v[64:65], 0, s[0:1]
	global_store_dwordx2 v[84:85], v[80:81], off
	v_pk_mul_f32 v[80:81], v[50:51], v[164:165]
	v_cvt_pk_bf16_f32 v84, v48, v49
	s_mov_b64 s[0:1], 0x140000
	v_cvt_pk_bf16_f32 v85, v80, v81
	global_store_dwordx2 v[68:69], v[84:85], off offset:16
	v_pk_mul_f32 v[80:81], v[22:23], v[136:137]
	v_cvt_pk_bf16_f32 v84, v20, v21
	s_nop 0
	v_cvt_pk_bf16_f32 v85, v80, v81
	global_store_dwordx2 v[68:69], v[84:85], off offset:256
	v_pk_mul_f32 v[80:81], v[18:19], v[128:129]
	v_cvt_pk_bf16_f32 v84, v16, v17
	s_nop 0
	v_cvt_pk_bf16_f32 v85, v80, v81
	global_store_dwordx2 v[68:69], v[84:85], off offset:272
	v_pk_mul_f32 v[68:69], v[46:47], v[162:163]
	v_cvt_pk_bf16_f32 v80, v44, v45
	s_nop 0
	v_cvt_pk_bf16_f32 v81, v68, v69
	v_lshl_add_u64 v[68:69], v[64:65], 0, s[0:1]
	s_mov_b32 s0, 0x140000
	v_add_co_u32_e32 v84, vcc, s0, v64
	s_mov_b64 s[0:1], 0x160000
	s_nop 0
	v_addc_co_u32_e32 v85, vcc, 0, v65, vcc
	global_store_dwordx2 v[84:85], v[80:81], off
	v_pk_mul_f32 v[80:81], v[42:43], v[164:165]
	v_cvt_pk_bf16_f32 v84, v40, v41
	s_nop 0
	v_cvt_pk_bf16_f32 v85, v80, v81
	global_store_dwordx2 v[68:69], v[84:85], off offset:16
	v_pk_mul_f32 v[80:81], v[14:15], v[136:137]
	v_cvt_pk_bf16_f32 v84, v12, v13
	s_nop 0
	v_cvt_pk_bf16_f32 v85, v80, v81
	global_store_dwordx2 v[68:69], v[84:85], off offset:256
	v_pk_mul_f32 v[80:81], v[10:11], v[128:129]
	v_cvt_pk_bf16_f32 v84, v8, v9
	s_nop 0
	v_cvt_pk_bf16_f32 v85, v80, v81
	global_store_dwordx2 v[68:69], v[84:85], off offset:272
	v_pk_mul_f32 v[68:69], v[38:39], v[162:163]
	v_cvt_pk_bf16_f32 v80, v36, v37
	s_nop 0
	v_cvt_pk_bf16_f32 v81, v68, v69
	v_lshl_add_u64 v[68:69], v[64:65], 0, s[0:1]
	s_mov_b32 s0, 0x160000
	v_add_co_u32_e32 v64, vcc, s0, v64
	s_mov_b64 s[0:1], 0
	s_nop 0
	v_addc_co_u32_e32 v65, vcc, 0, v65, vcc
	global_store_dwordx2 v[64:65], v[80:81], off
	v_pk_mul_f32 v[64:65], v[34:35], v[164:165]
	v_cvt_pk_bf16_f32 v80, v32, v33
	s_nop 0
	v_cvt_pk_bf16_f32 v81, v64, v65
	global_store_dwordx2 v[68:69], v[80:81], off offset:16
	v_pk_mul_f32 v[64:65], v[6:7], v[136:137]
	v_cvt_pk_bf16_f32 v80, v4, v5
	s_nop 0
	v_cvt_pk_bf16_f32 v81, v64, v65
	global_store_dwordx2 v[68:69], v[80:81], off offset:256
	v_pk_mul_f32 v[64:65], v[2:3], v[128:129]
	v_cvt_pk_bf16_f32 v80, v0, v1
	s_nop 0
	v_cvt_pk_bf16_f32 v81, v64, v65
	s_nop 1
	global_store_dwordx2 v[68:69], v[80:81], off offset:272
